# speedup vs baseline: 1.0169x; 1.0070x over previous
; #define WAIT_V(n) asm volatile("s_waitcnt vmcnt(" #n ")" ::: "memory")
; #define BAR __builtin_amdgcn_s_barrier()
; template <bool HS>
; __device__ __forceinline__ void gemm_tile8(const u16* __restrict__ Ap, const u16* __restrict__ Bp, int K,
;                                            f32x4 (&acc)[2][2][4][2], char* shm, const int tid, const float* hsr = nullptr) {
;   const int wid = tid >> 6, lane = tid & 63, wr = wid >> 2, wc = wid & 3, fr = lane & 15, fq = lane >> 4;
;   int r0, c0, r1, c1;
;   stage_rc(tid * 16, r0, c0);
;   stage_rc(tid * 16 + 8192, r1, c1);
;   const unsigned off0 = (unsigned)(r0 * K + c0) * 2u, off1 = (unsigned)(r1 * K + c1) * 2u;
;   const int wvoff = __builtin_amdgcn_readfirstlane(tid >> 6) * 1024;
;   const u16* A1 = Ap + (size_t)128 * K;
;   const u16* B1p = Bp + (size_t)128 * K;
; #pragma unroll
;   for (int a = 0; a < 2; ++a)
; #pragma unroll
;     for (int b = 0; b < 2; ++b)
; #pragma unroll
;       for (int m = 0; m < 4; ++m)
; #pragma unroll
;         for (int n = 0; n < 2; ++n) acc[a][b][m][n] = f32x4{0.f, 0.f, 0.f, 0.f};
;   const int abase = lds_byte(wr * 64 + fr, fq * 8), bbase = lds_byte(wc * 32 + fr, fq * 8);
;   bf16x8 At[4][2], B0[2][2], B1[2][2];
;   const unsigned lds0 = (unsigned)(size_t)(__attribute__((address_space(3))) char*)shm + (unsigned)wvoff;
;     ...
;   const int nt = K / BK;
;   WAIT_V(0);
;   if (wr == 1) BAR;
;   BAR;
;   BAR;
.LBB0_98:
	s_or_b64 exec, exec, s[2:3]
	v_mov_b32_e32 v4, s14
	v_bfe_i32 v4, v4, 0, 8
	v_ashrrev_i32_e32 v5, 31, v4
	v_lshlrev_b64 v[4:5], 19, v[4:5]
	v_bfe_i32 v6, v0, 27, 1
	v_lshl_add_u64 v[130:131], s[0:1], 0, v[4:5]
	v_lshlrev_b32_e32 v4, 4, v0
	v_lshrrev_b32_e32 v6, 22, v6
	v_add_u32_e32 v6, v4, v6
	v_and_b32_e32 v6, 0xfffffc00, v6
	v_ashrrev_i32_e32 v5, 31, v0
	v_sub_u32_e32 v6, v4, v6
	v_lshrrev_b32_e32 v5, 26, v5
	v_lshrrev_b32_e32 v7, 4, v6
	v_add_u32_e32 v5, v0, v5
	v_bitop3_b32 v7, v7, v6, 32 bitop3:0x6c
	v_ashrrev_i32_e32 v6, 31, v6
	v_ashrrev_i32_e32 v5, 6, v5
	v_lshrrev_b32_e32 v6, 26, v6
	v_lshlrev_b32_e32 v8, 3, v5
	v_add_u32_e32 v6, v7, v6
	v_and_b32_e32 v8, 0x1ffff0, v8
	v_ashrrev_i32_e32 v6, 6, v6
	v_add_u32_e32 v8, v6, v8
	v_mul_i32_i24_e32 v6, 64, v6
	v_add_u32_e32 v4, 0x2000, v4
	v_sub_u32_e32 v6, v7, v6
	v_ashrrev_i32_e32 v7, 31, v4
	v_lshrrev_b32_e32 v7, 22, v7
	v_add_u32_e32 v7, v4, v7
	v_ashrrev_i32_e32 v7, 10, v7
	v_mul_i32_i24_e32 v9, 0x400, v7
	v_sub_u32_e32 v4, v4, v9
	v_lshrrev_b32_e32 v9, 4, v4
	v_bitop3_b32 v4, v9, v4, 32 bitop3:0x6c
	v_ashrrev_i32_e32 v10, 31, v4
	v_lshrrev_b32_e32 v10, 26, v10
	v_add_u32_e32 v10, v4, v10
	v_lshlrev_b32_e32 v9, 3, v7
	v_lshrrev_b32_e32 v11, 6, v10
	v_and_b32_e32 v10, 0xc0, v10
	s_ashr_i32 s5, s4, 31
	v_and_b32_e32 v9, 0x1ffff0, v9
	v_lshlrev_b32_e32 v7, 5, v7
	v_sub_u32_e32 v4, v4, v10
	s_lshl_b64 s[10:11], s[4:5], 11
	v_readlane_b32 s2, v253, 63
	v_lshlrev_b32_e32 v5, 5, v5
	v_add_u32_e32 v9, v11, v9
	v_and_b32_e32 v7, 32, v7
	v_ashrrev_i16_sdwa v4, v178, sext(v4) dst_sel:DWORD dst_unused:UNUSED_PAD src0_sel:DWORD src1_sel:BYTE_0
	v_readlane_b32 s3, v254, 0
	s_add_u32 s9, s2, s10
	v_and_b32_e32 v5, 32, v5
	v_ashrrev_i16_sdwa v6, v178, sext(v6) dst_sel:DWORD dst_unused:UNUSED_PAD src0_sel:DWORD src1_sel:BYTE_0
	v_bfe_i32 v4, v4, 0, 16
	v_lshl_or_b32 v7, v9, 10, v7
	s_addc_u32 s12, s3, s11
	v_bfe_i32 v6, v6, 0, 16
	v_lshl_or_b32 v5, v8, 10, v5
	v_and_b32_e32 v8, 15, v0
	v_add_lshl_u32 v135, v7, v4, 1
	s_lshl_b32 s13, s13, 10
	v_lshlrev_b32_e32 v7, 2, v0
	v_add_lshl_u32 v136, v5, v6, 1
	s_mov_b64 s[2:3], 0x40000
	v_and_b32_e32 v4, 48, v0
	v_lshlrev_b32_e32 v5, 6, v8
	v_and_b32_e32 v7, 32, v7
	s_add_i32 s14, s13, 0
	v_lshl_add_u64 v[132:133], v[130:131], 0, s[2:3]
	v_or_b32_e32 v6, v5, v4
	v_bitop3_b32 v4, v5, v7, v4 bitop3:0x36
	v_lshlrev_b32_e32 v2, 12, v2
	s_movk_i32 s2, 0x3000
	s_add_u32 s15, s9, 0x40100
	v_lshlrev_b32_e32 v3, 13, v3
	v_and_or_b32 v137, v2, s2, v4
	s_addc_u32 s16, s12, 0
	v_readlane_b32 s2, v254, 32
	v_bitop3_b32 v3, v6, v3, v7 bitop3:0xde
	s_add_u32 s17, s2, s10
	v_readlane_b32 s2, v254, 33
	v_mov_b32_e32 v2, 0
	s_addc_u32 s18, s2, s11
	s_mov_b32 s19, -2
	s_mov_b64 s[2:3], 0
	v_add_u32_e32 v134, 0, v3
	v_mov_b32_e32 v3, v2
	v_mov_b32_e32 v4, v2
	v_mov_b32_e32 v5, v2
	v_mov_b32_e32 v6, v2
	v_mov_b32_e32 v7, v2
	v_mov_b32_e32 v8, v2
	v_mov_b32_e32 v9, v2
	v_mov_b32_e32 v10, v2
	v_mov_b32_e32 v11, v2
	v_mov_b32_e32 v12, v2
	v_mov_b32_e32 v13, v2
	v_mov_b32_e32 v14, v2
	v_mov_b32_e32 v15, v2
	v_mov_b32_e32 v16, v2
	v_mov_b32_e32 v17, v2
	v_mov_b32_e32 v18, v2
	v_mov_b32_e32 v19, v2
	v_mov_b32_e32 v20, v2
	v_mov_b32_e32 v21, v2
	v_mov_b32_e32 v22, v2
	v_mov_b32_e32 v23, v2
	v_mov_b32_e32 v24, v2
	v_mov_b32_e32 v25, v2
	v_mov_b32_e32 v26, v2
	v_mov_b32_e32 v27, v2
	v_mov_b32_e32 v28, v2
	s_waitcnt lgkmcnt(0)
	v_mov_b32_e32 v29, v2
	v_mov_b32_e32 v30, v2
	v_mov_b32_e32 v31, v2
	v_mov_b32_e32 v32, v2
	v_mov_b32_e32 v33, v2
	v_mov_b32_e32 v34, v2
	v_mov_b32_e32 v35, v2
	v_mov_b32_e32 v36, v2
	v_mov_b32_e32 v37, v2
	v_mov_b32_e32 v38, v2
	v_mov_b32_e32 v39, v2
	v_mov_b32_e32 v40, v2
	v_mov_b32_e32 v41, v2
	v_mov_b32_e32 v42, v2
	v_mov_b32_e32 v43, v2
	v_mov_b32_e32 v44, v2
	v_mov_b32_e32 v45, v2
	v_mov_b32_e32 v46, v2
	v_mov_b32_e32 v47, v2
	v_mov_b32_e32 v48, v2
	v_mov_b32_e32 v49, v2
	v_mov_b32_e32 v50, v2
	v_mov_b32_e32 v51, v2
	v_mov_b32_e32 v52, v2
	v_mov_b32_e32 v53, v2
	v_mov_b32_e32 v54, v2
	v_mov_b32_e32 v55, v2
	v_mov_b32_e32 v56, v2
	v_mov_b32_e32 v57, v2
	v_mov_b32_e32 v58, v2
	v_mov_b32_e32 v59, v2
	v_mov_b32_e32 v60, v2
	v_mov_b32_e32 v61, v2
	v_mov_b32_e32 v62, v2
	v_mov_b32_e32 v63, v2
	v_mov_b32_e32 v64, v2
	v_mov_b32_e32 v65, v2
	v_mov_b32_e32 v66, v2
	v_mov_b32_e32 v67, v2
	v_mov_b32_e32 v68, v2
	v_mov_b32_e32 v69, v2
	v_mov_b32_e32 v70, v2
	v_mov_b32_e32 v71, v2
	v_mov_b32_e32 v72, v2
	v_mov_b32_e32 v73, v2
	v_mov_b32_e32 v74, v2
	v_mov_b32_e32 v75, v2
	v_mov_b32_e32 v76, v2
	v_mov_b32_e32 v77, v2
	v_mov_b32_e32 v78, v2
	v_mov_b32_e32 v79, v2
	v_mov_b32_e32 v80, v2
	v_mov_b32_e32 v81, v2
	v_mov_b32_e32 v82, v2
	v_mov_b32_e32 v83, v2
	v_mov_b32_e32 v84, v2
	v_mov_b32_e32 v85, v2
	v_mov_b32_e32 v86, v2
	v_mov_b32_e32 v87, v2
	v_mov_b32_e32 v88, v2
	v_mov_b32_e32 v89, v2
	v_mov_b32_e32 v90, v2
	v_mov_b32_e32 v91, v2
	v_mov_b32_e32 v92, v2
	v_mov_b32_e32 v93, v2
	v_mov_b32_e32 v94, v2
	v_mov_b32_e32 v95, v2
	v_mov_b32_e32 v96, v2
	v_mov_b32_e32 v97, v2
	v_mov_b32_e32 v98, v2
	v_mov_b32_e32 v99, v2
	v_mov_b32_e32 v100, v2
	v_mov_b32_e32 v101, v2
	v_mov_b32_e32 v102, v2
	v_mov_b32_e32 v103, v2
	v_mov_b32_e32 v104, v2
	v_mov_b32_e32 v105, v2
	v_mov_b32_e32 v106, v2
	v_mov_b32_e32 v107, v2
	v_mov_b32_e32 v108, v2
	v_mov_b32_e32 v109, v2
	v_mov_b32_e32 v110, v2
	v_mov_b32_e32 v111, v2
	v_mov_b32_e32 v112, v2
	v_mov_b32_e32 v113, v2
	v_mov_b32_e32 v114, v2
	v_mov_b32_e32 v115, v2
	v_mov_b32_e32 v116, v2
	v_mov_b32_e32 v117, v2
	v_mov_b32_e32 v118, v2
	v_mov_b32_e32 v119, v2
	v_mov_b32_e32 v120, v2
	v_mov_b32_e32 v121, v2
	v_mov_b32_e32 v122, v2
	v_mov_b32_e32 v123, v2
	v_mov_b32_e32 v124, v2
	v_mov_b32_e32 v125, v2
	v_mov_b32_e32 v126, v2
	v_mov_b32_e32 v127, v2
	v_mov_b32_e32 v128, v2
	v_mov_b32_e32 v129, v2
	v_readfirstlane_b32 s24, v130
	v_readfirstlane_b32 s25, v131
	v_readfirstlane_b32 s26, v132
	v_readfirstlane_b32 s27, v133
	s_barrier
	s_barrier
; #define WAIT_L(n) asm volatile("s_waitcnt lgkmcnt(" #n ")" ::: "memory")
; #define BAR __builtin_amdgcn_s_barrier()
; #define SCHED __builtin_amdgcn_sched_barrier(0)
; #define STG_A(b, h, kt) stage_half_s(lds0 + ((b) * 2 + (h)) * HT_B, ((h) ? A1 : Ap) + (kt) * BK, off0, off1)
; #define STG_B(b, h, kt) stage_half_s(lds0 + (4 + (b) * 2 + (h)) * HT_B, ((h) ? B1p : Bp) + (kt) * BK, off0, off1)
; #define STG_A(b, h, kt) stage_half_s(lds0 + ((b) * 2 + (h)) * HT_B, ((h) ? A1 : Ap) + (kt) * BK, off0, off1)
; #define STG_B(b, h, kt) stage_half_s(lds0 + (4 + (b) * 2 + (h)) * HT_B, ((h) ? B1p : Bp) + (kt) * BK, off0, off1)
; #define LDA8(b, h) _Pragma("unroll") for (int m = 0; m < 4; ++m) _Pragma("unroll") for (int k = 0; k < 2; ++k) \
;     At[m][k] = *(const bf16x8*)(SA_(shm, b, h) + abase + (m * 2 + k) * 1024)
; #define LDB8(dst, b, h) _Pragma("unroll") for (int n = 0; n < 2; ++n) _Pragma("unroll") for (int k = 0; k < 2; ++k) \
;     dst[n][k] = *(const bf16x8*)(SB_(shm, b, h) + bbase + (n * 2 + k) * 1024)
; #define MMA8(ai, bj, Bx) do { __builtin_amdgcn_s_setprio(1); \
;     _Pragma("unroll") for (int m = 0; m < 4; ++m) _Pragma("unroll") for (int n = 0; n < 2; ++n) _Pragma("unroll") for (int k = 0; k < 2; ++k) \
;       acc[ai][bj][m][n] = __builtin_amdgcn_mfma_f32_16x16x32_bf16(At[m][k], Bx[n][k], acc[ai][bj][m][n], 0, 0, 0); \
;     __builtin_amdgcn_s_setprio(0); } while (0)
; template <bool HS>
; __device__ __forceinline__ void gemm_tile8(const u16* __restrict__ Ap, const u16* __restrict__ Bp, int K,
;                                            f32x4 (&acc)[2][2][4][2], char* shm, const int tid, const float* hsr = nullptr) {
;     ...
;     LDB8(B0, 0, 0); SCHED; LDA8(0, 0); STG_A(1, 1, t + 1);
;     WAIT_L(8); BAR; WAIT_L(0); MMA8(0, 0, B0); BAR; SCHED;
;     LDB8(B1, 0, 1); STG_B(0, 0, t + 2);
;     BAR; WAIT_L(0); MMA8(0, 1, B1); BAR;
;     LDA8(0, 1); STG_A(0, 0, t + 2);
;     BAR; WAIT_L(0); MMA8(1, 0, B0); BAR; SCHED;
;     STG_B(0, 1, t + 2);
.Lk_conv_out:
	v_add_u32_e32 v158, 0x10000, v137
	ds_read_b128 v[138:141], v158
	ds_read_b128 v[142:145], v158 offset:1024
	ds_read_b128 v[154:157], v158 offset:2048
	ds_read_b128 v[158:161], v158 offset:3072
	ds_read_b128 v[162:165], v134
	ds_read_b128 v[166:169], v134 offset:1024
	ds_read_b128 v[170:173], v134 offset:2048
	ds_read_b128 v[174:177], v134 offset:3072
	ds_read_b128 v[180:183], v134 offset:4096
	ds_read_b128 v[184:187], v134 offset:5120
	ds_read_b128 v[188:191], v134 offset:6144
	ds_read_b128 v[192:195], v134 offset:7168
	v_add_u32_e32 v208, 0x14000, v137
	ds_read_b128 v[196:199], v208
	ds_read_b128 v[200:203], v208 offset:1024
	ds_read_b128 v[204:207], v208 offset:2048
	ds_read_b128 v[208:211], v208 offset:3072
	s_add_u32 s22, s17, s2
	s_addc_u32 s23, s18, s3
	s_add_u32 s22, s22, 0x80
	s_addc_u32 s23, s23, 0
	s_add_i32 s36, s14, 0xc000
	s_mov_b32 m0, s36
	s_nop 0
	global_load_lds_dwordx4 v136, s[22:23]
	s_add_i32 s36, s14, 0xe000
	s_mov_b32 m0, s36
	s_nop 0
	global_load_lds_dwordx4 v135, s[22:23]
	s_waitcnt vmcnt(8) lgkmcnt(0)
	s_barrier
	s_setprio 1
	v_mfma_f32_16x16x32_bf16 v[126:129], v[162:165], v[138:141], v[126:129]
	v_mfma_f32_16x16x32_bf16 v[122:125], v[162:165], v[154:157], v[122:125]
	v_mfma_f32_16x16x32_bf16 v[118:121], v[170:173], v[138:141], v[118:121]
	v_mfma_f32_16x16x32_bf16 v[114:117], v[170:173], v[154:157], v[114:117]
	v_mfma_f32_16x16x32_bf16 v[110:113], v[180:183], v[138:141], v[110:113]
	v_mfma_f32_16x16x32_bf16 v[106:109], v[180:183], v[154:157], v[106:109]
	v_mfma_f32_16x16x32_bf16 v[102:105], v[188:191], v[138:141], v[102:105]
	v_mfma_f32_16x16x32_bf16 v[98:101], v[188:191], v[154:157], v[98:101]
	v_mfma_f32_16x16x32_bf16 v[126:129], v[166:169], v[142:145], v[126:129]
	v_mfma_f32_16x16x32_bf16 v[122:125], v[166:169], v[158:161], v[122:125]
	v_mfma_f32_16x16x32_bf16 v[118:121], v[174:177], v[142:145], v[118:121]
	v_mfma_f32_16x16x32_bf16 v[114:117], v[174:177], v[158:161], v[114:117]
	v_mfma_f32_16x16x32_bf16 v[110:113], v[184:187], v[142:145], v[110:113]
	v_mfma_f32_16x16x32_bf16 v[106:109], v[184:187], v[158:161], v[106:109]
	v_mfma_f32_16x16x32_bf16 v[102:105], v[192:195], v[142:145], v[102:105]
	v_mfma_f32_16x16x32_bf16 v[98:101], v[192:195], v[158:161], v[98:101]
	v_mfma_f32_16x16x32_bf16 v[94:97], v[162:165], v[196:199], v[94:97]
	v_mfma_f32_16x16x32_bf16 v[90:93], v[162:165], v[204:207], v[90:93]
	v_mfma_f32_16x16x32_bf16 v[86:89], v[170:173], v[196:199], v[86:89]
	v_mfma_f32_16x16x32_bf16 v[82:85], v[170:173], v[204:207], v[82:85]
	v_mfma_f32_16x16x32_bf16 v[78:81], v[180:183], v[196:199], v[78:81]
	v_mfma_f32_16x16x32_bf16 v[74:77], v[180:183], v[204:207], v[74:77]
	v_mfma_f32_16x16x32_bf16 v[70:73], v[188:191], v[196:199], v[70:73]
	v_mfma_f32_16x16x32_bf16 v[66:69], v[188:191], v[204:207], v[66:69]
	v_mfma_f32_16x16x32_bf16 v[94:97], v[166:169], v[200:203], v[94:97]
	v_mfma_f32_16x16x32_bf16 v[90:93], v[166:169], v[208:211], v[90:93]
	v_mfma_f32_16x16x32_bf16 v[86:89], v[174:177], v[200:203], v[86:89]
	v_mfma_f32_16x16x32_bf16 v[82:85], v[174:177], v[208:211], v[82:85]
	v_mfma_f32_16x16x32_bf16 v[78:81], v[184:187], v[200:203], v[78:81]
	v_mfma_f32_16x16x32_bf16 v[74:77], v[184:187], v[208:211], v[74:77]
	v_mfma_f32_16x16x32_bf16 v[70:73], v[192:195], v[200:203], v[70:73]
	v_mfma_f32_16x16x32_bf16 v[66:69], v[192:195], v[208:211], v[66:69]
	s_setprio 0
	s_barrier
	ds_read_b128 v[162:165], v134 offset:16384
	ds_read_b128 v[166:169], v134 offset:17408
	ds_read_b128 v[170:173], v134 offset:18432
	ds_read_b128 v[174:177], v134 offset:19456
	ds_read_b128 v[180:183], v134 offset:20480
	ds_read_b128 v[184:187], v134 offset:21504
	ds_read_b128 v[188:191], v134 offset:22528
	ds_read_b128 v[192:195], v134 offset:23552
	s_add_u32 s22, s24, s2
	s_addc_u32 s23, s25, s3
	s_add_u32 s22, s22, 0x100
	s_addc_u32 s23, s23, 0
	s_add_i32 s36, s14, 0x10000
	s_mov_b32 m0, s36
	s_nop 0
	global_load_lds_dwordx4 v136, s[22:23]
	s_add_i32 s36, s14, 0x12000
	s_mov_b32 m0, s36
	s_nop 0
	global_load_lds_dwordx4 v135, s[22:23]
	s_add_u32 s22, s9, s2
	s_addc_u32 s23, s12, s3
	s_add_u32 s22, s22, 0x100
	s_addc_u32 s23, s23, 0
	s_mov_b32 m0, s14
	s_nop 0
	global_load_lds_dwordx4 v136, s[22:23]
	s_add_i32 s36, s14, 0x2000
	s_mov_b32 m0, s36
	s_nop 0
	global_load_lds_dwordx4 v135, s[22:23]
	s_add_u32 s22, s26, s2
	s_addc_u32 s23, s27, s3
	s_add_u32 s22, s22, 0x100
	s_addc_u32 s23, s23, 0
	s_add_i32 s36, s14, 0x14000
	s_mov_b32 m0, s36
	s_nop 0
	global_load_lds_dwordx4 v136, s[22:23]
	s_add_i32 s36, s14, 0x16000
	s_mov_b32 m0, s36
	s_nop 0
	global_load_lds_dwordx4 v135, s[22:23]
	s_waitcnt vmcnt(8) lgkmcnt(0)
	s_barrier
; #define WAIT_V(n) asm volatile("s_waitcnt vmcnt(" #n ")" ::: "memory")
; #define WAIT_L(n) asm volatile("s_waitcnt lgkmcnt(" #n ")" ::: "memory")
; #define BAR __builtin_amdgcn_s_barrier()
; #define SCHED __builtin_amdgcn_sched_barrier(0)
; #define STG_A(b, h, kt) stage_half_s(lds0 + ((b) * 2 + (h)) * HT_B, ((h) ? A1 : Ap) + (kt) * BK, off0, off1)
; #define STG_B(b, h, kt) stage_half_s(lds0 + (4 + (b) * 2 + (h)) * HT_B, ((h) ? B1p : Bp) + (kt) * BK, off0, off1)
; #define STG_A(b, h, kt) stage_half_s(lds0 + ((b) * 2 + (h)) * HT_B, ((h) ? A1 : Ap) + (kt) * BK, off0, off1)
; #define STG_B(b, h, kt) stage_half_s(lds0 + (4 + (b) * 2 + (h)) * HT_B, ((h) ? B1p : Bp) + (kt) * BK, off0, off1)
; #define LDA8(b, h) _Pragma("unroll") for (int m = 0; m < 4; ++m) _Pragma("unroll") for (int k = 0; k < 2; ++k) \
;     At[m][k] = *(const bf16x8*)(SA_(shm, b, h) + abase + (m * 2 + k) * 1024)
; #define LDB8(dst, b, h) _Pragma("unroll") for (int n = 0; n < 2; ++n) _Pragma("unroll") for (int k = 0; k < 2; ++k) \
;     dst[n][k] = *(const bf16x8*)(SB_(shm, b, h) + bbase + (n * 2 + k) * 1024)
; #define MMA8(ai, bj, Bx) do { __builtin_amdgcn_s_setprio(1); \
;     _Pragma("unroll") for (int m = 0; m < 4; ++m) _Pragma("unroll") for (int n = 0; n < 2; ++n) _Pragma("unroll") for (int k = 0; k < 2; ++k) \
;       acc[ai][bj][m][n] = __builtin_amdgcn_mfma_f32_16x16x32_bf16(At[m][k], Bx[n][k], acc[ai][bj][m][n], 0, 0, 0); \
;     __builtin_amdgcn_s_setprio(0); } while (0)
; template <bool HS>
; __device__ __forceinline__ void gemm_tile8(const u16* __restrict__ Ap, const u16* __restrict__ Bp, int K,
;                                            f32x4 (&acc)[2][2][4][2], char* shm, const int tid, const float* hsr = nullptr) {
;     ...
;     BAR; WAIT_L(0); MMA8(1, 0, B0); BAR; SCHED;
;     STG_B(0, 1, t + 2);
;     WAIT_V(6); BAR; MMA8(1, 1, B1); BAR;
;     LDB8(B0, 1, 0); SCHED; LDA8(1, 0); STG_A(0, 1, t + 2);
;     WAIT_L(8); BAR; WAIT_L(0); MMA8(0, 0, B0); BAR; SCHED;
;     LDB8(B1, 1, 1); STG_B(1, 0, t + 3);
;     BAR; WAIT_L(0); MMA8(0, 1, B1); BAR;
	s_setprio 1
	v_mfma_f32_16x16x32_bf16 v[62:65], v[162:165], v[138:141], v[62:65]
	v_mfma_f32_16x16x32_bf16 v[58:61], v[162:165], v[154:157], v[58:61]
	v_mfma_f32_16x16x32_bf16 v[54:57], v[170:173], v[138:141], v[54:57]
	v_mfma_f32_16x16x32_bf16 v[50:53], v[170:173], v[154:157], v[50:53]
	v_mfma_f32_16x16x32_bf16 v[46:49], v[180:183], v[138:141], v[46:49]
	v_mfma_f32_16x16x32_bf16 v[42:45], v[180:183], v[154:157], v[42:45]
	v_mfma_f32_16x16x32_bf16 v[38:41], v[188:191], v[138:141], v[38:41]
	v_mfma_f32_16x16x32_bf16 v[34:37], v[188:191], v[154:157], v[34:37]
	v_mfma_f32_16x16x32_bf16 v[62:65], v[166:169], v[142:145], v[62:65]
	v_mfma_f32_16x16x32_bf16 v[58:61], v[166:169], v[158:161], v[58:61]
	v_mfma_f32_16x16x32_bf16 v[54:57], v[174:177], v[142:145], v[54:57]
	v_mfma_f32_16x16x32_bf16 v[50:53], v[174:177], v[158:161], v[50:53]
	v_mfma_f32_16x16x32_bf16 v[46:49], v[184:187], v[142:145], v[46:49]
	v_mfma_f32_16x16x32_bf16 v[42:45], v[184:187], v[158:161], v[42:45]
	v_mfma_f32_16x16x32_bf16 v[38:41], v[192:195], v[142:145], v[38:41]
	v_mfma_f32_16x16x32_bf16 v[34:37], v[192:195], v[158:161], v[34:37]
	v_mfma_f32_16x16x32_bf16 v[30:33], v[162:165], v[196:199], v[30:33]
	v_mfma_f32_16x16x32_bf16 v[26:29], v[162:165], v[204:207], v[26:29]
	v_mfma_f32_16x16x32_bf16 v[22:25], v[170:173], v[196:199], v[22:25]
	v_mfma_f32_16x16x32_bf16 v[18:21], v[170:173], v[204:207], v[18:21]
	v_mfma_f32_16x16x32_bf16 v[14:17], v[180:183], v[196:199], v[14:17]
	v_mfma_f32_16x16x32_bf16 v[10:13], v[180:183], v[204:207], v[10:13]
	v_mfma_f32_16x16x32_bf16 v[6:9], v[188:191], v[196:199], v[6:9]
	v_mfma_f32_16x16x32_bf16 v[2:5], v[188:191], v[204:207], v[2:5]
	v_mfma_f32_16x16x32_bf16 v[30:33], v[166:169], v[200:203], v[30:33]
	v_mfma_f32_16x16x32_bf16 v[26:29], v[166:169], v[208:211], v[26:29]
	v_mfma_f32_16x16x32_bf16 v[22:25], v[174:177], v[200:203], v[22:25]
	v_mfma_f32_16x16x32_bf16 v[18:21], v[174:177], v[208:211], v[18:21]
	v_mfma_f32_16x16x32_bf16 v[14:17], v[184:187], v[200:203], v[14:17]
	v_mfma_f32_16x16x32_bf16 v[10:13], v[184:187], v[208:211], v[10:13]
	v_mfma_f32_16x16x32_bf16 v[6:9], v[192:195], v[200:203], v[6:9]
	v_mfma_f32_16x16x32_bf16 v[2:5], v[192:195], v[208:211], v[2:5]
	s_setprio 0
	s_barrier
	v_add_u32_e32 v158, 0x18000, v137
	ds_read_b128 v[138:141], v158
	ds_read_b128 v[142:145], v158 offset:1024
	ds_read_b128 v[154:157], v158 offset:2048
	ds_read_b128 v[158:161], v158 offset:3072
	ds_read_b128 v[162:165], v134 offset:32768
	ds_read_b128 v[166:169], v134 offset:33792
	ds_read_b128 v[170:173], v134 offset:34816
	ds_read_b128 v[174:177], v134 offset:35840
	ds_read_b128 v[180:183], v134 offset:36864
	ds_read_b128 v[184:187], v134 offset:37888
	ds_read_b128 v[188:191], v134 offset:38912
	ds_read_b128 v[192:195], v134 offset:39936
	v_add_u32_e32 v208, 0x1c000, v137
	ds_read_b128 v[196:199], v208
	ds_read_b128 v[200:203], v208 offset:1024
	ds_read_b128 v[204:207], v208 offset:2048
	ds_read_b128 v[208:211], v208 offset:3072
	s_add_u32 s22, s17, s2
	s_addc_u32 s23, s18, s3
	s_add_u32 s22, s22, 0x100
	s_addc_u32 s23, s23, 0
	s_add_i32 s36, s14, 0x4000
	s_mov_b32 m0, s36
	s_nop 0
	global_load_lds_dwordx4 v136, s[22:23]
	s_add_i32 s36, s14, 0x6000
	s_mov_b32 m0, s36
	s_nop 0
	global_load_lds_dwordx4 v135, s[22:23]
	s_waitcnt vmcnt(8) lgkmcnt(0)
	s_barrier
	s_setprio 1
	v_mfma_f32_16x16x32_bf16 v[126:129], v[162:165], v[138:141], v[126:129]
	v_mfma_f32_16x16x32_bf16 v[122:125], v[162:165], v[154:157], v[122:125]
	v_mfma_f32_16x16x32_bf16 v[118:121], v[170:173], v[138:141], v[118:121]
	v_mfma_f32_16x16x32_bf16 v[114:117], v[170:173], v[154:157], v[114:117]
	v_mfma_f32_16x16x32_bf16 v[110:113], v[180:183], v[138:141], v[110:113]
	v_mfma_f32_16x16x32_bf16 v[106:109], v[180:183], v[154:157], v[106:109]
	v_mfma_f32_16x16x32_bf16 v[102:105], v[188:191], v[138:141], v[102:105]
	v_mfma_f32_16x16x32_bf16 v[98:101], v[188:191], v[154:157], v[98:101]
	v_mfma_f32_16x16x32_bf16 v[126:129], v[166:169], v[142:145], v[126:129]
	v_mfma_f32_16x16x32_bf16 v[122:125], v[166:169], v[158:161], v[122:125]
	v_mfma_f32_16x16x32_bf16 v[118:121], v[174:177], v[142:145], v[118:121]
	v_mfma_f32_16x16x32_bf16 v[114:117], v[174:177], v[158:161], v[114:117]
	v_mfma_f32_16x16x32_bf16 v[110:113], v[184:187], v[142:145], v[110:113]
	v_mfma_f32_16x16x32_bf16 v[106:109], v[184:187], v[158:161], v[106:109]
	v_mfma_f32_16x16x32_bf16 v[102:105], v[192:195], v[142:145], v[102:105]
	v_mfma_f32_16x16x32_bf16 v[98:101], v[192:195], v[158:161], v[98:101]
	v_mfma_f32_16x16x32_bf16 v[94:97], v[162:165], v[196:199], v[94:97]
	v_mfma_f32_16x16x32_bf16 v[90:93], v[162:165], v[204:207], v[90:93]
	v_mfma_f32_16x16x32_bf16 v[86:89], v[170:173], v[196:199], v[86:89]
	v_mfma_f32_16x16x32_bf16 v[82:85], v[170:173], v[204:207], v[82:85]
	v_mfma_f32_16x16x32_bf16 v[78:81], v[180:183], v[196:199], v[78:81]
	v_mfma_f32_16x16x32_bf16 v[74:77], v[180:183], v[204:207], v[74:77]
	v_mfma_f32_16x16x32_bf16 v[70:73], v[188:191], v[196:199], v[70:73]
	v_mfma_f32_16x16x32_bf16 v[66:69], v[188:191], v[204:207], v[66:69]
	v_mfma_f32_16x16x32_bf16 v[94:97], v[166:169], v[200:203], v[94:97]
	v_mfma_f32_16x16x32_bf16 v[90:93], v[166:169], v[208:211], v[90:93]
	v_mfma_f32_16x16x32_bf16 v[86:89], v[174:177], v[200:203], v[86:89]
	v_mfma_f32_16x16x32_bf16 v[82:85], v[174:177], v[208:211], v[82:85]
	v_mfma_f32_16x16x32_bf16 v[78:81], v[184:187], v[200:203], v[78:81]
	v_mfma_f32_16x16x32_bf16 v[74:77], v[184:187], v[208:211], v[74:77]
	v_mfma_f32_16x16x32_bf16 v[70:73], v[192:195], v[200:203], v[70:73]
	v_mfma_f32_16x16x32_bf16 v[66:69], v[192:195], v[208:211], v[66:69]
	s_setprio 0
	s_barrier
; #define WAIT_V(n) asm volatile("s_waitcnt vmcnt(" #n ")" ::: "memory")
; #define WAIT_L(n) asm volatile("s_waitcnt lgkmcnt(" #n ")" ::: "memory")
; #define BAR __builtin_amdgcn_s_barrier()
; #define SCHED __builtin_amdgcn_sched_barrier(0)
; #define STG_A(b, h, kt) stage_half_s(lds0 + ((b) * 2 + (h)) * HT_B, ((h) ? A1 : Ap) + (kt) * BK, off0, off1)
; #define STG_B(b, h, kt) stage_half_s(lds0 + (4 + (b) * 2 + (h)) * HT_B, ((h) ? B1p : Bp) + (kt) * BK, off0, off1)
; #define STG_A(b, h, kt) stage_half_s(lds0 + ((b) * 2 + (h)) * HT_B, ((h) ? A1 : Ap) + (kt) * BK, off0, off1)
; #define STG_B(b, h, kt) stage_half_s(lds0 + (4 + (b) * 2 + (h)) * HT_B, ((h) ? B1p : Bp) + (kt) * BK, off0, off1)
; #define LDA8(b, h) _Pragma("unroll") for (int m = 0; m < 4; ++m) _Pragma("unroll") for (int k = 0; k < 2; ++k) \
;     At[m][k] = *(const bf16x8*)(SA_(shm, b, h) + abase + (m * 2 + k) * 1024)
; #define LDB8(dst, b, h) _Pragma("unroll") for (int n = 0; n < 2; ++n) _Pragma("unroll") for (int k = 0; k < 2; ++k) \
;     dst[n][k] = *(const bf16x8*)(SB_(shm, b, h) + bbase + (n * 2 + k) * 1024)
; #define MMA8(ai, bj, Bx) do { __builtin_amdgcn_s_setprio(1); \
;     _Pragma("unroll") for (int m = 0; m < 4; ++m) _Pragma("unroll") for (int n = 0; n < 2; ++n) _Pragma("unroll") for (int k = 0; k < 2; ++k) \
;       acc[ai][bj][m][n] = __builtin_amdgcn_mfma_f32_16x16x32_bf16(At[m][k], Bx[n][k], acc[ai][bj][m][n], 0, 0, 0); \
;     __builtin_amdgcn_s_setprio(0); } while (0)
; template <bool HS>
; __device__ __forceinline__ void gemm_tile8(const u16* __restrict__ Ap, const u16* __restrict__ Bp, int K,
;                                            f32x4 (&acc)[2][2][4][2], char* shm, const int tid, const float* hsr = nullptr) {
;     ...
;     LDA8(1, 1); STG_A(1, 0, t + 3);
;     BAR; WAIT_L(0); MMA8(1, 0, B0); BAR; SCHED;
;     STG_B(1, 1, t + 3);
;     WAIT_V(6); BAR; MMA8(1, 1, B1); BAR;
;   }
;   { LDB8(B0, 0, 0); LDA8(0, 0); STG_A(1, 1, nt - 1);
;     BAR; WAIT_L(0); MMA8(0, 0, B0); BAR;
	ds_read_b128 v[162:165], v134 offset:49152
	ds_read_b128 v[166:169], v134 offset:50176
	ds_read_b128 v[170:173], v134 offset:51200
	ds_read_b128 v[174:177], v134 offset:52224
	ds_read_b128 v[180:183], v134 offset:53248
	ds_read_b128 v[184:187], v134 offset:54272
	ds_read_b128 v[188:191], v134 offset:55296
	ds_read_b128 v[192:195], v134 offset:56320
	s_add_u32 s22, s24, s2
	s_addc_u32 s23, s25, s3
	s_add_u32 s22, s22, 0x180
	s_addc_u32 s23, s23, 0
	s_add_i32 s36, s14, 0x18000
	s_mov_b32 m0, s36
	s_nop 0
	global_load_lds_dwordx4 v136, s[22:23]
	s_add_i32 s36, s14, 0x1a000
	s_mov_b32 m0, s36
	s_nop 0
	global_load_lds_dwordx4 v135, s[22:23]
	s_add_u32 s22, s9, s2
	s_addc_u32 s23, s12, s3
	s_add_u32 s22, s22, 0x180
	s_addc_u32 s23, s23, 0
	s_add_i32 s36, s14, 0x8000
	s_mov_b32 m0, s36
	s_nop 0
	global_load_lds_dwordx4 v136, s[22:23]
	s_add_i32 s36, s14, 0xa000
	s_mov_b32 m0, s36
	s_nop 0
	global_load_lds_dwordx4 v135, s[22:23]
	s_add_u32 s22, s26, s2
	s_addc_u32 s23, s27, s3
	s_add_u32 s22, s22, 0x180
	s_addc_u32 s23, s23, 0
	s_add_i32 s36, s14, 0x1c000
	s_mov_b32 m0, s36
	s_nop 0
	global_load_lds_dwordx4 v136, s[22:23]
	s_add_i32 s36, s14, 0x1e000
	s_mov_b32 m0, s36
	s_nop 0
	global_load_lds_dwordx4 v135, s[22:23]
	s_waitcnt vmcnt(8) lgkmcnt(0)
	s_barrier
	s_setprio 1
	v_mfma_f32_16x16x32_bf16 v[62:65], v[162:165], v[138:141], v[62:65]
	v_mfma_f32_16x16x32_bf16 v[58:61], v[162:165], v[154:157], v[58:61]
	v_mfma_f32_16x16x32_bf16 v[54:57], v[170:173], v[138:141], v[54:57]
	v_mfma_f32_16x16x32_bf16 v[50:53], v[170:173], v[154:157], v[50:53]
	v_mfma_f32_16x16x32_bf16 v[46:49], v[180:183], v[138:141], v[46:49]
	v_mfma_f32_16x16x32_bf16 v[42:45], v[180:183], v[154:157], v[42:45]
	v_mfma_f32_16x16x32_bf16 v[38:41], v[188:191], v[138:141], v[38:41]
	v_mfma_f32_16x16x32_bf16 v[34:37], v[188:191], v[154:157], v[34:37]
	v_mfma_f32_16x16x32_bf16 v[62:65], v[166:169], v[142:145], v[62:65]
	v_mfma_f32_16x16x32_bf16 v[58:61], v[166:169], v[158:161], v[58:61]
	v_mfma_f32_16x16x32_bf16 v[54:57], v[174:177], v[142:145], v[54:57]
	v_mfma_f32_16x16x32_bf16 v[50:53], v[174:177], v[158:161], v[50:53]
	v_mfma_f32_16x16x32_bf16 v[46:49], v[184:187], v[142:145], v[46:49]
	v_mfma_f32_16x16x32_bf16 v[42:45], v[184:187], v[158:161], v[42:45]
	v_mfma_f32_16x16x32_bf16 v[38:41], v[192:195], v[142:145], v[38:41]
	v_mfma_f32_16x16x32_bf16 v[34:37], v[192:195], v[158:161], v[34:37]
	v_mfma_f32_16x16x32_bf16 v[30:33], v[162:165], v[196:199], v[30:33]
	v_mfma_f32_16x16x32_bf16 v[26:29], v[162:165], v[204:207], v[26:29]
	v_mfma_f32_16x16x32_bf16 v[22:25], v[170:173], v[196:199], v[22:25]
	v_mfma_f32_16x16x32_bf16 v[18:21], v[170:173], v[204:207], v[18:21]
	v_mfma_f32_16x16x32_bf16 v[14:17], v[180:183], v[196:199], v[14:17]
	v_mfma_f32_16x16x32_bf16 v[10:13], v[180:183], v[204:207], v[10:13]
	v_mfma_f32_16x16x32_bf16 v[6:9], v[188:191], v[196:199], v[6:9]
	v_mfma_f32_16x16x32_bf16 v[2:5], v[188:191], v[204:207], v[2:5]
	v_mfma_f32_16x16x32_bf16 v[30:33], v[166:169], v[200:203], v[30:33]
	v_mfma_f32_16x16x32_bf16 v[26:29], v[166:169], v[208:211], v[26:29]
	v_mfma_f32_16x16x32_bf16 v[22:25], v[174:177], v[200:203], v[22:25]
	v_mfma_f32_16x16x32_bf16 v[18:21], v[174:177], v[208:211], v[18:21]
	v_mfma_f32_16x16x32_bf16 v[14:17], v[184:187], v[200:203], v[14:17]
	v_mfma_f32_16x16x32_bf16 v[10:13], v[184:187], v[208:211], v[10:13]
	v_mfma_f32_16x16x32_bf16 v[6:9], v[192:195], v[200:203], v[6:9]
	v_mfma_f32_16x16x32_bf16 v[2:5], v[192:195], v[208:211], v[2:5]
	s_setprio 0
	s_add_i32 s19, s19, 2
	s_add_u32 s2, s2, 0x100
	s_addc_u32 s3, s3, 0
	s_cmp_lt_u32 s19, 12
	s_barrier
	s_cbranch_scc1 .Lk_conv_out
	s_waitcnt vmcnt(6)
	s_add_i32 s20, s14, 0xc000
	s_add_i32 s21, s14, 0xe000
	v_add_u32_e32 v220, 0, v137
	v_add_u32_e32 v137, 0x10000, v220
	ds_read_b128 v[130:133], v137
	ds_read_b128 v[138:141], v137 offset:1024
	ds_read_b128 v[142:145], v137 offset:2048
	ds_read_b128 v[154:157], v137 offset:3072
	ds_read_b128 v[158:161], v134
	ds_read_b128 v[162:165], v134 offset:1024
	ds_read_b128 v[166:169], v134 offset:2048
	ds_read_b128 v[170:173], v134 offset:3072
	ds_read_b128 v[174:177], v134 offset:4096
	ds_read_b128 v[180:183], v134 offset:5120
	ds_read_b128 v[184:187], v134 offset:6144
	ds_read_b128 v[188:191], v134 offset:7168
	s_add_u32 s2, s9, 0x40780
	s_addc_u32 s3, s12, 0
	s_mov_b32 m0, s20
	s_nop 0
	global_load_lds_dwordx4 v136, s[2:3]
	s_nop 0
	s_mov_b32 m0, s21
	s_nop 0
	global_load_lds_dwordx4 v135, s[2:3]
	s_barrier
	s_waitcnt lgkmcnt(0)
	s_setprio 1
	s_waitcnt lgkmcnt(7)
	v_mfma_f32_16x16x32_bf16 v[126:129], v[158:161], v[130:133], v[126:129]
	s_waitcnt lgkmcnt(5)
	v_mfma_f32_16x16x32_bf16 v[118:121], v[166:169], v[130:133], v[118:121]
	v_mfma_f32_16x16x32_bf16 v[114:117], v[166:169], v[142:145], v[114:117]
	s_waitcnt lgkmcnt(1)
	v_mfma_f32_16x16x32_bf16 v[102:105], v[184:187], v[130:133], v[102:105]
	v_mfma_f32_16x16x32_bf16 v[98:101], v[184:187], v[142:145], v[98:101]
	v_mfma_f32_16x16x32_bf16 v[126:129], v[162:165], v[138:141], v[126:129]
	v_mfma_f32_16x16x32_bf16 v[122:125], v[158:161], v[142:145], v[122:125]
	v_mfma_f32_16x16x32_bf16 v[118:121], v[170:173], v[138:141], v[118:121]
	v_mfma_f32_16x16x32_bf16 v[114:117], v[170:173], v[154:157], v[114:117]
	v_mfma_f32_16x16x32_bf16 v[110:113], v[174:177], v[130:133], v[110:113]
	v_mfma_f32_16x16x32_bf16 v[106:109], v[174:177], v[142:145], v[106:109]
	s_waitcnt lgkmcnt(0)
	v_mfma_f32_16x16x32_bf16 v[102:105], v[188:191], v[138:141], v[102:105]
	v_mfma_f32_16x16x32_bf16 v[98:101], v[188:191], v[154:157], v[98:101]
	v_mfma_f32_16x16x32_bf16 v[192:195], v[162:165], v[154:157], v[122:125]
	v_mfma_f32_16x16x32_bf16 v[196:199], v[180:183], v[138:141], v[110:113]
	v_mfma_f32_16x16x32_bf16 v[200:203], v[180:183], v[154:157], v[106:109]
	s_setprio 0
	v_add_u32_e32 v135, 0x14000, v220
	s_barrier
; #define WAIT_V(n) asm volatile("s_waitcnt vmcnt(" #n ")" ::: "memory")
; #define WAIT_L(n) asm volatile("s_waitcnt lgkmcnt(" #n ")" ::: "memory")
; #define BAR __builtin_amdgcn_s_barrier()
; #define LDA8(b, h) _Pragma("unroll") for (int m = 0; m < 4; ++m) _Pragma("unroll") for (int k = 0; k < 2; ++k) \
;     At[m][k] = *(const bf16x8*)(SA_(shm, b, h) + abase + (m * 2 + k) * 1024)
; #define LDB8(dst, b, h) _Pragma("unroll") for (int n = 0; n < 2; ++n) _Pragma("unroll") for (int k = 0; k < 2; ++k) \
;     dst[n][k] = *(const bf16x8*)(SB_(shm, b, h) + bbase + (n * 2 + k) * 1024)
; #define MMA8(ai, bj, Bx) do { __builtin_amdgcn_s_setprio(1); \
;     _Pragma("unroll") for (int m = 0; m < 4; ++m) _Pragma("unroll") for (int n = 0; n < 2; ++n) _Pragma("unroll") for (int k = 0; k < 2; ++k) \
;       acc[ai][bj][m][n] = __builtin_amdgcn_mfma_f32_16x16x32_bf16(At[m][k], Bx[n][k], acc[ai][bj][m][n], 0, 0, 0); \
;     __builtin_amdgcn_s_setprio(0); } while (0)
; template <bool HS>
; __device__ __forceinline__ void gemm_tile8(const u16* __restrict__ Ap, const u16* __restrict__ Bp, int K,
;                                            f32x4 (&acc)[2][2][4][2], char* shm, const int tid, const float* hsr = nullptr) {
;     ...
;     BAR; WAIT_L(0); MMA8(0, 0, B0); BAR;
;     LDB8(B1, 0, 1); BAR; WAIT_L(0); MMA8(0, 1, B1); BAR;
;     LDA8(0, 1); WAIT_V(4); BAR; WAIT_L(0); MMA8(1, 0, B0); MMA8(1, 1, B1); BAR; }
;   { LDB8(B0, 1, 0); LDA8(1, 0); WAIT_V(2); BAR; WAIT_L(0); MMA8(0, 0, B0); BAR;
	ds_read_b128 v[106:109], v135
	ds_read_b128 v[110:113], v135 offset:1024
	ds_read_b128 v[122:125], v135 offset:2048
	ds_read_b128 v[204:207], v135 offset:3072
	s_barrier
	s_waitcnt lgkmcnt(0)
	s_setprio 1
	s_waitcnt lgkmcnt(3)
	v_mfma_f32_16x16x32_bf16 v[86:89], v[166:169], v[106:109], v[86:89]
	s_waitcnt lgkmcnt(1)
	v_mfma_f32_16x16x32_bf16 v[82:85], v[166:169], v[122:125], v[82:85]
	v_mfma_f32_16x16x32_bf16 v[70:73], v[184:187], v[106:109], v[70:73]
	v_mfma_f32_16x16x32_bf16 v[94:97], v[158:161], v[106:109], v[94:97]
	v_mfma_f32_16x16x32_bf16 v[90:93], v[158:161], v[122:125], v[90:93]
	v_mfma_f32_16x16x32_bf16 v[86:89], v[170:173], v[110:113], v[86:89]
	s_waitcnt lgkmcnt(0)
	v_mfma_f32_16x16x32_bf16 v[82:85], v[170:173], v[204:207], v[82:85]
	v_mfma_f32_16x16x32_bf16 v[78:81], v[174:177], v[106:109], v[78:81]
	v_mfma_f32_16x16x32_bf16 v[74:77], v[174:177], v[122:125], v[74:77]
	v_mfma_f32_16x16x32_bf16 v[70:73], v[188:191], v[110:113], v[70:73]
	v_mfma_f32_16x16x32_bf16 v[66:69], v[184:187], v[122:125], v[66:69]
	v_mfma_f32_16x16x32_bf16 v[208:211], v[162:165], v[110:113], v[94:97]
	v_mfma_f32_16x16x32_bf16 v[158:161], v[162:165], v[204:207], v[90:93]
	v_mfma_f32_16x16x32_bf16 v[162:165], v[180:183], v[110:113], v[78:81]
	v_mfma_f32_16x16x32_bf16 v[166:169], v[180:183], v[204:207], v[74:77]
	v_mfma_f32_16x16x32_bf16 v[170:173], v[188:191], v[204:207], v[66:69]
	s_setprio 0
	s_barrier
	s_nop 0
	ds_read_b128 v[66:69], v134 offset:16384
	ds_read_b128 v[74:77], v134 offset:17408
	ds_read_b128 v[78:81], v134 offset:18432
	ds_read_b128 v[90:93], v134 offset:19456
	ds_read_b128 v[94:97], v134 offset:20480
	ds_read_b128 v[174:177], v134 offset:21504
	ds_read_b128 v[180:183], v134 offset:22528
	ds_read_b128 v[184:187], v134 offset:23552
	s_waitcnt vmcnt(4)
	s_barrier
	s_waitcnt lgkmcnt(0)
	s_setprio 1
	s_waitcnt lgkmcnt(7)
	v_mfma_f32_16x16x32_bf16 v[62:65], v[66:69], v[130:133], v[62:65]
	s_waitcnt lgkmcnt(5)
	v_mfma_f32_16x16x32_bf16 v[54:57], v[78:81], v[130:133], v[54:57]
	v_mfma_f32_16x16x32_bf16 v[50:53], v[78:81], v[142:145], v[50:53]
	s_waitcnt lgkmcnt(1)
	v_mfma_f32_16x16x32_bf16 v[38:41], v[180:183], v[130:133], v[38:41]
	v_mfma_f32_16x16x32_bf16 v[34:37], v[180:183], v[142:145], v[34:37]
	v_mfma_f32_16x16x32_bf16 v[62:65], v[74:77], v[138:141], v[62:65]
	v_mfma_f32_16x16x32_bf16 v[58:61], v[66:69], v[142:145], v[58:61]
	v_mfma_f32_16x16x32_bf16 v[54:57], v[90:93], v[138:141], v[54:57]
	v_mfma_f32_16x16x32_bf16 v[50:53], v[90:93], v[154:157], v[50:53]
	v_mfma_f32_16x16x32_bf16 v[46:49], v[94:97], v[130:133], v[46:49]
	v_mfma_f32_16x16x32_bf16 v[42:45], v[94:97], v[142:145], v[42:45]
	s_waitcnt lgkmcnt(0)
	v_mfma_f32_16x16x32_bf16 v[38:41], v[184:187], v[138:141], v[38:41]
	v_mfma_f32_16x16x32_bf16 v[34:37], v[184:187], v[154:157], v[34:37]
	v_mfma_f32_16x16x32_bf16 v[188:191], v[74:77], v[154:157], v[58:61]
	v_mfma_f32_16x16x32_bf16 v[212:215], v[174:177], v[138:141], v[46:49]
	v_mfma_f32_16x16x32_bf16 v[216:219], v[174:177], v[154:157], v[42:45]
	s_setprio 0
	s_setprio 1
	v_mfma_f32_16x16x32_bf16 v[22:25], v[78:81], v[106:109], v[22:25]
	v_mfma_f32_16x16x32_bf16 v[18:21], v[78:81], v[122:125], v[18:21]
	v_mfma_f32_16x16x32_bf16 v[6:9], v[180:183], v[106:109], v[6:9]
	v_mfma_f32_16x16x32_bf16 v[30:33], v[66:69], v[106:109], v[30:33]
	v_mfma_f32_16x16x32_bf16 v[26:29], v[66:69], v[122:125], v[26:29]
	v_mfma_f32_16x16x32_bf16 v[22:25], v[90:93], v[110:113], v[22:25]
	v_mfma_f32_16x16x32_bf16 v[18:21], v[90:93], v[204:207], v[18:21]
	v_mfma_f32_16x16x32_bf16 v[14:17], v[94:97], v[106:109], v[14:17]
	v_mfma_f32_16x16x32_bf16 v[10:13], v[94:97], v[122:125], v[10:13]
	v_mfma_f32_16x16x32_bf16 v[6:9], v[184:187], v[110:113], v[6:9]
	v_mfma_f32_16x16x32_bf16 v[2:5], v[180:183], v[122:125], v[2:5]
	v_mfma_f32_16x16x32_bf16 v[130:133], v[74:77], v[110:113], v[30:33]
	v_mfma_f32_16x16x32_bf16 v[136:139], v[74:77], v[204:207], v[26:29]
	v_mfma_f32_16x16x32_bf16 v[140:143], v[174:177], v[110:113], v[14:17]
	v_mfma_f32_16x16x32_bf16 v[154:157], v[174:177], v[204:207], v[10:13]
	v_mfma_f32_16x16x32_bf16 v[174:177], v[184:187], v[204:207], v[2:5]
	s_setprio 0
	v_add_u32_e32 v26, 0x18000, v220
	s_barrier
	ds_read_b128 v[2:5], v26
	ds_read_b128 v[10:13], v26 offset:1024
	ds_read_b128 v[14:17], v26 offset:2048
	ds_read_b128 v[180:183], v26 offset:3072
	ds_read_b128 v[26:29], v134 offset:32768
	ds_read_b128 v[30:33], v134 offset:33792
	ds_read_b128 v[42:45], v134 offset:34816
	ds_read_b128 v[46:49], v134 offset:35840
	ds_read_b128 v[58:61], v134 offset:36864
	ds_read_b128 v[66:69], v134 offset:37888
	ds_read_b128 v[184:187], v134 offset:38912
	ds_read_b128 v[204:207], v134 offset:39936
	s_waitcnt vmcnt(2)
	s_barrier
; #define WAIT_V(n) asm volatile("s_waitcnt vmcnt(" #n ")" ::: "memory")
; #define WAIT_L(n) asm volatile("s_waitcnt lgkmcnt(" #n ")" ::: "memory")
; #define BAR __builtin_amdgcn_s_barrier()
; #define LDA8(b, h) _Pragma("unroll") for (int m = 0; m < 4; ++m) _Pragma("unroll") for (int k = 0; k < 2; ++k) \
;     At[m][k] = *(const bf16x8*)(SA_(shm, b, h) + abase + (m * 2 + k) * 1024)
; #define LDB8(dst, b, h) _Pragma("unroll") for (int n = 0; n < 2; ++n) _Pragma("unroll") for (int k = 0; k < 2; ++k) \
;     dst[n][k] = *(const bf16x8*)(SB_(shm, b, h) + bbase + (n * 2 + k) * 1024)
; #define MMA8(ai, bj, Bx) do { __builtin_amdgcn_s_setprio(1); \
;     _Pragma("unroll") for (int m = 0; m < 4; ++m) _Pragma("unroll") for (int n = 0; n < 2; ++n) _Pragma("unroll") for (int k = 0; k < 2; ++k) \
;       acc[ai][bj][m][n] = __builtin_amdgcn_mfma_f32_16x16x32_bf16(At[m][k], Bx[n][k], acc[ai][bj][m][n], 0, 0, 0); \
;     __builtin_amdgcn_s_setprio(0); } while (0)
; template <bool HS>
; __device__ __forceinline__ void gemm_tile8(const u16* __restrict__ Ap, const u16* __restrict__ Bp, int K,
;                                            f32x4 (&acc)[2][2][4][2], char* shm, const int tid, const float* hsr = nullptr) {
;     ...
;   { LDB8(B0, 1, 0); LDA8(1, 0); WAIT_V(2); BAR; WAIT_L(0); MMA8(0, 0, B0); BAR;
;     LDB8(B1, 1, 1); WAIT_V(0); BAR; WAIT_L(0); MMA8(0, 1, B1); BAR;
;     LDA8(1, 1); BAR; WAIT_L(0); MMA8(1, 0, B0); MMA8(1, 1, B1); BAR; }
;   if (wr == 0) BAR;
	s_waitcnt lgkmcnt(0)
	s_setprio 1
	s_waitcnt lgkmcnt(7)
	v_mfma_f32_16x16x32_bf16 v[74:77], v[26:29], v[2:5], v[126:129]
	s_waitcnt lgkmcnt(6)
	v_mfma_f32_16x16x32_bf16 v[122:125], v[30:33], v[10:13], v[74:77]
	v_mfma_f32_16x16x32_bf16 v[74:77], v[26:29], v[14:17], v[192:195]
	v_mfma_f32_16x16x32_bf16 v[126:129], v[30:33], v[180:183], v[74:77]
	s_waitcnt lgkmcnt(5)
	v_mfma_f32_16x16x32_bf16 v[74:77], v[42:45], v[2:5], v[118:121]
	s_waitcnt lgkmcnt(4)
	v_mfma_f32_16x16x32_bf16 v[106:109], v[46:49], v[10:13], v[74:77]
	v_mfma_f32_16x16x32_bf16 v[74:77], v[42:45], v[14:17], v[114:117]
	v_mfma_f32_16x16x32_bf16 v[110:113], v[46:49], v[180:183], v[74:77]
	s_waitcnt lgkmcnt(3)
	v_mfma_f32_16x16x32_bf16 v[74:77], v[58:61], v[2:5], v[196:199]
	s_waitcnt lgkmcnt(2)
	v_mfma_f32_16x16x32_bf16 v[90:93], v[66:69], v[10:13], v[74:77]
	v_mfma_f32_16x16x32_bf16 v[74:77], v[58:61], v[14:17], v[200:203]
	v_mfma_f32_16x16x32_bf16 v[94:97], v[66:69], v[180:183], v[74:77]
	s_waitcnt lgkmcnt(1)
	v_mfma_f32_16x16x32_bf16 v[74:77], v[184:187], v[2:5], v[102:105]
	v_mfma_f32_16x16x32_bf16 v[78:81], v[184:187], v[14:17], v[98:101]
	s_waitcnt lgkmcnt(0)
	v_mfma_f32_16x16x32_bf16 v[74:77], v[204:207], v[10:13], v[74:77]
	v_mfma_f32_16x16x32_bf16 v[78:81], v[204:207], v[180:183], v[78:81]
	s_setprio 0
	v_add_u32_e32 v98, 0x1c000, v220
	s_barrier
	ds_read_b128 v[192:195], v98
	ds_read_b128 v[196:199], v98 offset:1024
	ds_read_b128 v[200:203], v98 offset:2048
	ds_read_b128 v[220:223], v98 offset:3072
	s_waitcnt vmcnt(0)
	s_barrier
	s_waitcnt lgkmcnt(0)
	s_setprio 1
	s_waitcnt lgkmcnt(3)
	v_mfma_f32_16x16x32_bf16 v[98:101], v[26:29], v[192:195], v[208:211]
	s_waitcnt lgkmcnt(1)
	v_mfma_f32_16x16x32_bf16 v[26:29], v[26:29], v[200:203], v[158:161]
	s_waitcnt lgkmcnt(0)
	v_mfma_f32_16x16x32_bf16 v[118:121], v[30:33], v[220:223], v[26:29]
	v_mfma_f32_16x16x32_bf16 v[26:29], v[42:45], v[192:195], v[86:89]
	v_mfma_f32_16x16x32_bf16 v[114:117], v[30:33], v[196:199], v[98:101]
	v_mfma_f32_16x16x32_bf16 v[98:101], v[46:49], v[196:199], v[26:29]
	v_mfma_f32_16x16x32_bf16 v[26:29], v[42:45], v[200:203], v[82:85]
	v_mfma_f32_16x16x32_bf16 v[102:105], v[46:49], v[220:223], v[26:29]
	v_mfma_f32_16x16x32_bf16 v[26:29], v[58:61], v[192:195], v[162:165]
	v_mfma_f32_16x16x32_bf16 v[82:85], v[66:69], v[196:199], v[26:29]
	v_mfma_f32_16x16x32_bf16 v[26:29], v[58:61], v[200:203], v[166:169]
	v_mfma_f32_16x16x32_bf16 v[86:89], v[66:69], v[220:223], v[26:29]
	v_mfma_f32_16x16x32_bf16 v[26:29], v[184:187], v[192:195], v[70:73]
	v_mfma_f32_16x16x32_bf16 v[66:69], v[204:207], v[196:199], v[26:29]
	v_mfma_f32_16x16x32_bf16 v[26:29], v[184:187], v[200:203], v[170:173]
	v_mfma_f32_16x16x32_bf16 v[70:73], v[204:207], v[220:223], v[26:29]
	s_setprio 0
	s_barrier
	ds_read_b128 v[158:161], v134 offset:49152
	ds_read_b128 v[162:165], v134 offset:50176
	ds_read_b128 v[166:169], v134 offset:51200
	ds_read_b128 v[170:173], v134 offset:52224
	ds_read_b128 v[184:187], v134 offset:53248
	ds_read_b128 v[204:207], v134 offset:54272
	ds_read_b128 v[208:211], v134 offset:55296
	ds_read_b128 v[224:227], v134 offset:56320
	s_barrier
	s_waitcnt lgkmcnt(0)
	s_setprio 1
	s_waitcnt lgkmcnt(7)
	v_mfma_f32_16x16x32_bf16 v[26:29], v[158:161], v[2:5], v[62:65]
	s_waitcnt lgkmcnt(6)
	v_mfma_f32_16x16x32_bf16 v[58:61], v[162:165], v[10:13], v[26:29]
	v_mfma_f32_16x16x32_bf16 v[26:29], v[158:161], v[14:17], v[188:191]
	v_mfma_f32_16x16x32_bf16 v[62:65], v[162:165], v[180:183], v[26:29]
	s_waitcnt lgkmcnt(5)
	v_mfma_f32_16x16x32_bf16 v[26:29], v[166:169], v[2:5], v[54:57]
	s_waitcnt lgkmcnt(4)
	v_mfma_f32_16x16x32_bf16 v[42:45], v[170:173], v[10:13], v[26:29]
	v_mfma_f32_16x16x32_bf16 v[26:29], v[166:169], v[14:17], v[50:53]
	v_mfma_f32_16x16x32_bf16 v[46:49], v[170:173], v[180:183], v[26:29]
	s_waitcnt lgkmcnt(3)
	v_mfma_f32_16x16x32_bf16 v[26:29], v[184:187], v[2:5], v[212:215]
	s_waitcnt lgkmcnt(1)
	v_mfma_f32_16x16x32_bf16 v[2:5], v[208:211], v[2:5], v[38:41]
	v_mfma_f32_16x16x32_bf16 v[26:29], v[204:207], v[10:13], v[26:29]
	v_mfma_f32_16x16x32_bf16 v[30:33], v[184:187], v[14:17], v[216:219]
	s_waitcnt lgkmcnt(0)
	v_mfma_f32_16x16x32_bf16 v[10:13], v[224:227], v[10:13], v[2:5]
	v_mfma_f32_16x16x32_bf16 v[2:5], v[208:211], v[14:17], v[34:37]
	v_mfma_f32_16x16x32_bf16 v[30:33], v[204:207], v[180:183], v[30:33]
	v_mfma_f32_16x16x32_bf16 v[14:17], v[224:227], v[180:183], v[2:5]
	s_setprio 0
	s_setprio 1
	v_mfma_f32_16x16x32_bf16 v[2:5], v[158:161], v[192:195], v[130:133]
	v_mfma_f32_16x16x32_bf16 v[50:53], v[162:165], v[196:199], v[2:5]
	v_mfma_f32_16x16x32_bf16 v[2:5], v[158:161], v[200:203], v[136:139]
	v_mfma_f32_16x16x32_bf16 v[54:57], v[162:165], v[220:223], v[2:5]
	v_mfma_f32_16x16x32_bf16 v[2:5], v[166:169], v[192:195], v[22:25]
	v_mfma_f32_16x16x32_bf16 v[34:37], v[170:173], v[196:199], v[2:5]
	v_mfma_f32_16x16x32_bf16 v[2:5], v[166:169], v[200:203], v[18:21]
	v_mfma_f32_16x16x32_bf16 v[38:41], v[170:173], v[220:223], v[2:5]
	v_mfma_f32_16x16x32_bf16 v[2:5], v[184:187], v[192:195], v[140:143]
	v_mfma_f32_16x16x32_bf16 v[18:21], v[204:207], v[196:199], v[2:5]
	v_mfma_f32_16x16x32_bf16 v[2:5], v[184:187], v[200:203], v[154:157]
	v_mfma_f32_16x16x32_bf16 v[22:25], v[204:207], v[220:223], v[2:5]
	v_mfma_f32_16x16x32_bf16 v[2:5], v[208:211], v[192:195], v[6:9]
	v_mfma_f32_16x16x32_bf16 v[6:9], v[208:211], v[200:203], v[174:177]
	v_mfma_f32_16x16x32_bf16 v[2:5], v[224:227], v[196:199], v[2:5]
	v_mfma_f32_16x16x32_bf16 v[6:9], v[224:227], v[220:223], v[6:9]
	s_setprio 0
	s_movk_i32 s2, 0x100
	v_cmp_gt_u32_e32 vcc, s2, v0
	s_barrier
	s_and_saveexec_b64 s[2:3], vcc
	s_cbranch_execz .LBB0_102
	s_barrier

; #define WAIT_V(n) asm volatile("s_waitcnt vmcnt(" #n ")" ::: "memory")
; #define BAR __builtin_amdgcn_s_barrier()
; template <bool HS>
; __device__ __forceinline__ void gemm_tile8(const u16* __restrict__ Ap, const u16* __restrict__ Bp, int K,
;                                            f32x4 (&acc)[2][2][4][2], char* shm, const int tid, const float* hsr = nullptr) {
;   const int wid = tid >> 6, lane = tid & 63, wr = wid >> 2, wc = wid & 3, fr = lane & 15, fq = lane >> 4;
;   int r0, c0, r1, c1;
;   stage_rc(tid * 16, r0, c0);
;   stage_rc(tid * 16 + 8192, r1, c1);
;   const unsigned off0 = (unsigned)(r0 * K + c0) * 2u, off1 = (unsigned)(r1 * K + c1) * 2u;
;   const int wvoff = __builtin_amdgcn_readfirstlane(tid >> 6) * 1024;
;   const u16* A1 = Ap + (size_t)128 * K;
;   const u16* B1p = Bp + (size_t)128 * K;
; #pragma unroll
;   for (int a = 0; a < 2; ++a)
; #pragma unroll
;     for (int b = 0; b < 2; ++b)
; #pragma unroll
;       for (int m = 0; m < 4; ++m)
; #pragma unroll
;         for (int n = 0; n < 2; ++n) acc[a][b][m][n] = f32x4{0.f, 0.f, 0.f, 0.f};
;   const int abase = lds_byte(wr * 64 + fr, fq * 8), bbase = lds_byte(wc * 32 + fr, fq * 8);
;   bf16x8 At[4][2], B0[2][2], B1[2][2];
;   const unsigned lds0 = (unsigned)(size_t)(__attribute__((address_space(3))) char*)shm + (unsigned)wvoff;
;     ...
;   const int nt = K / BK;
;   WAIT_V(0);
;   if (wr == 1) BAR;
;   BAR;
;   BAR;
.LBB0_317:
	s_or_b64 exec, exec, s[6:7]
	v_mov_b32_e32 v4, s11
	v_bfe_i32 v4, v4, 0, 8
	v_ashrrev_i32_e32 v5, 31, v4
	v_lshlrev_b64 v[4:5], 19, v[4:5]
	v_bfe_i32 v6, v0, 27, 1
	v_lshl_add_u64 v[130:131], s[0:1], 0, v[4:5]
	v_lshlrev_b32_e32 v4, 4, v0
	v_lshrrev_b32_e32 v6, 22, v6
	v_add_u32_e32 v6, v4, v6
	v_and_b32_e32 v6, 0xfffffc00, v6
	v_ashrrev_i32_e32 v5, 31, v0
	v_sub_u32_e32 v6, v4, v6
	v_lshrrev_b32_e32 v5, 26, v5
	v_lshrrev_b32_e32 v7, 4, v6
	v_add_u32_e32 v5, v0, v5
	v_bitop3_b32 v7, v7, v6, 32 bitop3:0x6c
	v_ashrrev_i32_e32 v6, 31, v6
	v_ashrrev_i32_e32 v5, 6, v5
	v_lshrrev_b32_e32 v6, 26, v6
	v_lshlrev_b32_e32 v8, 3, v5
	v_add_u32_e32 v6, v7, v6
	v_and_b32_e32 v8, 0x1ffff0, v8
	v_ashrrev_i32_e32 v6, 6, v6
	v_add_u32_e32 v8, v6, v8
	v_mul_i32_i24_e32 v6, 64, v6
	v_add_u32_e32 v4, 0x2000, v4
	v_sub_u32_e32 v6, v7, v6
	v_ashrrev_i32_e32 v7, 31, v4
	v_lshrrev_b32_e32 v7, 22, v7
	v_add_u32_e32 v7, v4, v7
	v_ashrrev_i32_e32 v7, 10, v7
	v_mul_i32_i24_e32 v9, 0x400, v7
	v_sub_u32_e32 v4, v4, v9
	v_lshrrev_b32_e32 v9, 4, v4
	v_bitop3_b32 v4, v9, v4, 32 bitop3:0x6c
	v_ashrrev_i32_e32 v10, 31, v4
	v_lshrrev_b32_e32 v10, 26, v10
	v_add_u32_e32 v10, v4, v10
	v_lshlrev_b32_e32 v9, 3, v7
	v_lshrrev_b32_e32 v11, 6, v10
	v_and_b32_e32 v10, 0xc0, v10
	s_ashr_i32 s5, s4, 31
	v_and_b32_e32 v9, 0x1ffff0, v9
	v_lshlrev_b32_e32 v7, 5, v7
	v_sub_u32_e32 v4, v4, v10
	s_lshl_b64 s[6:7], s[4:5], 11
	v_lshlrev_b32_e32 v5, 5, v5
	v_add_u32_e32 v9, v11, v9
	v_and_b32_e32 v7, 32, v7
	v_ashrrev_i16_sdwa v4, v178, sext(v4) dst_sel:DWORD dst_unused:UNUSED_PAD src0_sel:DWORD src1_sel:BYTE_0
	s_add_u32 s8, s88, s6
	v_and_b32_e32 v5, 32, v5
	v_ashrrev_i16_sdwa v6, v178, sext(v6) dst_sel:DWORD dst_unused:UNUSED_PAD src0_sel:DWORD src1_sel:BYTE_0
	v_bfe_i32 v4, v4, 0, 16
	v_lshl_or_b32 v7, v9, 10, v7
	s_addc_u32 s9, s89, s7
	v_bfe_i32 v6, v6, 0, 16
	v_lshl_or_b32 v5, v8, 10, v5
	v_and_b32_e32 v8, 15, v0
	v_add_lshl_u32 v139, v7, v4, 1
	s_lshl_b32 s10, s10, 10
	v_lshlrev_b32_e32 v7, 2, v0
	v_add_lshl_u32 v140, v5, v6, 1
	s_mov_b64 s[4:5], 0x40000
	v_and_b32_e32 v4, 48, v0
	v_lshlrev_b32_e32 v5, 6, v8
	v_and_b32_e32 v7, 32, v7
	s_add_i32 s11, s10, 0
	v_lshl_add_u64 v[132:133], v[130:131], 0, s[4:5]
	v_or_b32_e32 v6, v5, v4
	v_bitop3_b32 v4, v5, v7, v4 bitop3:0x36
	v_lshlrev_b32_e32 v2, 12, v2
	s_movk_i32 s4, 0x3000
	s_add_u32 s13, s8, 0x40100
	v_lshlrev_b32_e32 v3, 13, v3
	v_and_or_b32 v141, v2, s4, v4
	s_addc_u32 s14, s9, 0
	v_readlane_b32 s4, v254, 34
	v_bitop3_b32 v3, v6, v3, v7 bitop3:0xde
	s_add_u32 s15, s4, s6
	v_readlane_b32 s4, v254, 35
	v_mov_b32_e32 v2, 0
	s_addc_u32 s16, s4, s7
	s_mov_b32 s17, -2
	s_mov_b64 s[4:5], 0
	v_add_u32_e32 v138, 0, v3
	v_mov_b32_e32 v3, v2
	v_mov_b32_e32 v4, v2
	v_mov_b32_e32 v5, v2
	v_mov_b32_e32 v6, v2
	v_mov_b32_e32 v7, v2
	v_mov_b32_e32 v8, v2
	v_mov_b32_e32 v9, v2
	v_mov_b32_e32 v10, v2
	v_mov_b32_e32 v11, v2
	v_mov_b32_e32 v12, v2
	v_mov_b32_e32 v13, v2
	v_mov_b32_e32 v14, v2
	v_mov_b32_e32 v15, v2
	v_mov_b32_e32 v16, v2
	v_mov_b32_e32 v17, v2
	v_mov_b32_e32 v18, v2
	v_mov_b32_e32 v19, v2
	v_mov_b32_e32 v20, v2
	v_mov_b32_e32 v21, v2
	v_mov_b32_e32 v22, v2
	v_mov_b32_e32 v23, v2
	v_mov_b32_e32 v24, v2
	v_mov_b32_e32 v25, v2
	v_mov_b32_e32 v26, v2
	v_mov_b32_e32 v27, v2
	v_mov_b32_e32 v28, v2
	s_waitcnt lgkmcnt(0)
	v_mov_b32_e32 v29, v2
	v_mov_b32_e32 v30, v2
	v_mov_b32_e32 v31, v2
	v_mov_b32_e32 v32, v2
	v_mov_b32_e32 v33, v2
	v_mov_b32_e32 v34, v2
	v_mov_b32_e32 v35, v2
	v_mov_b32_e32 v36, v2
	v_mov_b32_e32 v37, v2
	v_mov_b32_e32 v38, v2
	v_mov_b32_e32 v39, v2
	v_mov_b32_e32 v40, v2
	v_mov_b32_e32 v41, v2
	v_mov_b32_e32 v42, v2
	v_mov_b32_e32 v43, v2
	v_mov_b32_e32 v44, v2
	v_mov_b32_e32 v45, v2
	v_mov_b32_e32 v46, v2
	v_mov_b32_e32 v47, v2
	v_mov_b32_e32 v48, v2
	v_mov_b32_e32 v49, v2
	v_mov_b32_e32 v50, v2
	v_mov_b32_e32 v51, v2
	v_mov_b32_e32 v52, v2
	v_mov_b32_e32 v53, v2
	v_mov_b32_e32 v54, v2
	v_mov_b32_e32 v55, v2
	v_mov_b32_e32 v56, v2
	v_mov_b32_e32 v57, v2
	v_mov_b32_e32 v58, v2
	v_mov_b32_e32 v59, v2
	v_mov_b32_e32 v60, v2
	v_mov_b32_e32 v61, v2
	v_mov_b32_e32 v62, v2
	v_mov_b32_e32 v63, v2
	v_mov_b32_e32 v64, v2
	v_mov_b32_e32 v65, v2
	v_mov_b32_e32 v66, v2
	v_mov_b32_e32 v67, v2
	v_mov_b32_e32 v68, v2
	v_mov_b32_e32 v69, v2
	v_mov_b32_e32 v70, v2
	v_mov_b32_e32 v71, v2
	v_mov_b32_e32 v72, v2
	v_mov_b32_e32 v73, v2
	v_mov_b32_e32 v74, v2
	v_mov_b32_e32 v75, v2
	v_mov_b32_e32 v76, v2
	v_mov_b32_e32 v77, v2
	v_mov_b32_e32 v78, v2
	v_mov_b32_e32 v79, v2
	v_mov_b32_e32 v80, v2
	v_mov_b32_e32 v81, v2
	v_mov_b32_e32 v82, v2
	v_mov_b32_e32 v83, v2
	v_mov_b32_e32 v84, v2
	v_mov_b32_e32 v85, v2
	v_mov_b32_e32 v86, v2
	v_mov_b32_e32 v87, v2
	v_mov_b32_e32 v88, v2
	v_mov_b32_e32 v89, v2
	v_mov_b32_e32 v90, v2
	v_mov_b32_e32 v91, v2
	v_mov_b32_e32 v92, v2
	v_mov_b32_e32 v93, v2
	v_mov_b32_e32 v94, v2
	v_mov_b32_e32 v95, v2
	v_mov_b32_e32 v96, v2
	v_mov_b32_e32 v97, v2
	v_mov_b32_e32 v98, v2
	v_mov_b32_e32 v99, v2
	v_mov_b32_e32 v100, v2
	v_mov_b32_e32 v101, v2
	v_mov_b32_e32 v102, v2
	v_mov_b32_e32 v103, v2
	v_mov_b32_e32 v104, v2
	v_mov_b32_e32 v105, v2
	v_mov_b32_e32 v106, v2
	v_mov_b32_e32 v107, v2
	v_mov_b32_e32 v108, v2
	v_mov_b32_e32 v109, v2
	v_mov_b32_e32 v110, v2
	v_mov_b32_e32 v111, v2
	v_mov_b32_e32 v112, v2
	v_mov_b32_e32 v113, v2
	v_mov_b32_e32 v114, v2
	v_mov_b32_e32 v115, v2
	v_mov_b32_e32 v116, v2
	v_mov_b32_e32 v117, v2
	v_mov_b32_e32 v118, v2
	v_mov_b32_e32 v119, v2
	v_mov_b32_e32 v120, v2
	v_mov_b32_e32 v121, v2
	v_mov_b32_e32 v122, v2
	v_mov_b32_e32 v123, v2
	v_mov_b32_e32 v124, v2
	v_mov_b32_e32 v125, v2
	v_mov_b32_e32 v126, v2
	v_mov_b32_e32 v127, v2
	v_mov_b32_e32 v128, v2
	v_mov_b32_e32 v129, v2
	v_readfirstlane_b32 s24, v130
	v_readfirstlane_b32 s25, v131
	v_readfirstlane_b32 s22, v132
	v_readfirstlane_b32 s23, v133
	s_barrier
	s_barrier
; #define WAIT_L(n) asm volatile("s_waitcnt lgkmcnt(" #n ")" ::: "memory")
; #define BAR __builtin_amdgcn_s_barrier()
; #define SCHED __builtin_amdgcn_sched_barrier(0)
; #define STG_A(b, h, kt) stage_half_s(lds0 + ((b) * 2 + (h)) * HT_B, ((h) ? A1 : Ap) + (kt) * BK, off0, off1)
; #define STG_B(b, h, kt) stage_half_s(lds0 + (4 + (b) * 2 + (h)) * HT_B, ((h) ? B1p : Bp) + (kt) * BK, off0, off1)
; #define STG_A(b, h, kt) stage_half_s(lds0 + ((b) * 2 + (h)) * HT_B, ((h) ? A1 : Ap) + (kt) * BK, off0, off1)
; #define STG_B(b, h, kt) stage_half_s(lds0 + (4 + (b) * 2 + (h)) * HT_B, ((h) ? B1p : Bp) + (kt) * BK, off0, off1)
; #define LDA8(b, h) _Pragma("unroll") for (int m = 0; m < 4; ++m) _Pragma("unroll") for (int k = 0; k < 2; ++k) \
;     At[m][k] = *(const bf16x8*)(SA_(shm, b, h) + abase + (m * 2 + k) * 1024)
; #define LDB8(dst, b, h) _Pragma("unroll") for (int n = 0; n < 2; ++n) _Pragma("unroll") for (int k = 0; k < 2; ++k) \
;     dst[n][k] = *(const bf16x8*)(SB_(shm, b, h) + bbase + (n * 2 + k) * 1024)
; #define MMA8(ai, bj, Bx) do { __builtin_amdgcn_s_setprio(1); \
;     _Pragma("unroll") for (int m = 0; m < 4; ++m) _Pragma("unroll") for (int n = 0; n < 2; ++n) _Pragma("unroll") for (int k = 0; k < 2; ++k) \
;       acc[ai][bj][m][n] = __builtin_amdgcn_mfma_f32_16x16x32_bf16(At[m][k], Bx[n][k], acc[ai][bj][m][n], 0, 0, 0); \
;     __builtin_amdgcn_s_setprio(0); } while (0)
; template <bool HS>
; __device__ __forceinline__ void gemm_tile8(const u16* __restrict__ Ap, const u16* __restrict__ Bp, int K,
;                                            f32x4 (&acc)[2][2][4][2], char* shm, const int tid, const float* hsr = nullptr) {
;     ...
;     LDB8(B0, 0, 0); SCHED; LDA8(0, 0); STG_A(1, 1, t + 1);
;     WAIT_L(8); BAR; WAIT_L(0); MMA8(0, 0, B0); BAR; SCHED;
;     LDB8(B1, 0, 1); STG_B(0, 0, t + 2);
;     BAR; WAIT_L(0); MMA8(0, 1, B1); BAR;
;     LDA8(0, 1); STG_A(0, 0, t + 2);
;     BAR; WAIT_L(0); MMA8(1, 0, B0); BAR; SCHED;
;     STG_B(0, 1, t + 2);
.Lk_conv_in:
	v_add_u32_e32 v154, 0x10000, v141
	ds_read_b128 v[142:145], v154
	ds_read_b128 v[146:149], v154 offset:1024
	ds_read_b128 v[150:153], v154 offset:2048
	ds_read_b128 v[154:157], v154 offset:3072
	ds_read_b128 v[158:161], v138
	ds_read_b128 v[162:165], v138 offset:1024
	ds_read_b128 v[166:169], v138 offset:2048
	ds_read_b128 v[170:173], v138 offset:3072
	ds_read_b128 v[174:177], v138 offset:4096
	ds_read_b128 v[180:183], v138 offset:5120
	ds_read_b128 v[184:187], v138 offset:6144
	ds_read_b128 v[188:191], v138 offset:7168
	v_add_u32_e32 v204, 0x14000, v141
	ds_read_b128 v[192:195], v204
	ds_read_b128 v[196:199], v204 offset:1024
	ds_read_b128 v[200:203], v204 offset:2048
	ds_read_b128 v[204:207], v204 offset:3072
	s_add_u32 s20, s15, s4
	s_addc_u32 s21, s16, s5
	s_add_u32 s20, s20, 0x80
	s_addc_u32 s21, s21, 0
	s_add_i32 s18, s11, 0xc000
	s_mov_b32 m0, s18
	s_nop 0
	global_load_lds_dwordx4 v140, s[20:21]
	s_add_i32 s18, s11, 0xe000
	s_mov_b32 m0, s18
	s_nop 0
	global_load_lds_dwordx4 v139, s[20:21]
	s_waitcnt vmcnt(8) lgkmcnt(0)
	s_barrier
	s_setprio 1
	v_mfma_f32_16x16x32_bf16 v[126:129], v[158:161], v[142:145], v[126:129]
	v_mfma_f32_16x16x32_bf16 v[122:125], v[158:161], v[150:153], v[122:125]
	v_mfma_f32_16x16x32_bf16 v[118:121], v[166:169], v[142:145], v[118:121]
	v_mfma_f32_16x16x32_bf16 v[114:117], v[166:169], v[150:153], v[114:117]
	v_mfma_f32_16x16x32_bf16 v[110:113], v[174:177], v[142:145], v[110:113]
	v_mfma_f32_16x16x32_bf16 v[106:109], v[174:177], v[150:153], v[106:109]
	v_mfma_f32_16x16x32_bf16 v[102:105], v[184:187], v[142:145], v[102:105]
	v_mfma_f32_16x16x32_bf16 v[98:101], v[184:187], v[150:153], v[98:101]
	v_mfma_f32_16x16x32_bf16 v[126:129], v[162:165], v[146:149], v[126:129]
	v_mfma_f32_16x16x32_bf16 v[122:125], v[162:165], v[154:157], v[122:125]
	v_mfma_f32_16x16x32_bf16 v[118:121], v[170:173], v[146:149], v[118:121]
	v_mfma_f32_16x16x32_bf16 v[114:117], v[170:173], v[154:157], v[114:117]
	v_mfma_f32_16x16x32_bf16 v[110:113], v[180:183], v[146:149], v[110:113]
	v_mfma_f32_16x16x32_bf16 v[106:109], v[180:183], v[154:157], v[106:109]
	v_mfma_f32_16x16x32_bf16 v[102:105], v[188:191], v[146:149], v[102:105]
	v_mfma_f32_16x16x32_bf16 v[98:101], v[188:191], v[154:157], v[98:101]
	v_mfma_f32_16x16x32_bf16 v[94:97], v[158:161], v[192:195], v[94:97]
	v_mfma_f32_16x16x32_bf16 v[90:93], v[158:161], v[200:203], v[90:93]
	v_mfma_f32_16x16x32_bf16 v[86:89], v[166:169], v[192:195], v[86:89]
	v_mfma_f32_16x16x32_bf16 v[82:85], v[166:169], v[200:203], v[82:85]
	v_mfma_f32_16x16x32_bf16 v[78:81], v[174:177], v[192:195], v[78:81]
	v_mfma_f32_16x16x32_bf16 v[74:77], v[174:177], v[200:203], v[74:77]
	v_mfma_f32_16x16x32_bf16 v[70:73], v[184:187], v[192:195], v[70:73]
	v_mfma_f32_16x16x32_bf16 v[66:69], v[184:187], v[200:203], v[66:69]
	v_mfma_f32_16x16x32_bf16 v[94:97], v[162:165], v[196:199], v[94:97]
	v_mfma_f32_16x16x32_bf16 v[90:93], v[162:165], v[204:207], v[90:93]
	v_mfma_f32_16x16x32_bf16 v[86:89], v[170:173], v[196:199], v[86:89]
	v_mfma_f32_16x16x32_bf16 v[82:85], v[170:173], v[204:207], v[82:85]
	v_mfma_f32_16x16x32_bf16 v[78:81], v[180:183], v[196:199], v[78:81]
	v_mfma_f32_16x16x32_bf16 v[74:77], v[180:183], v[204:207], v[74:77]
	v_mfma_f32_16x16x32_bf16 v[70:73], v[188:191], v[196:199], v[70:73]
	v_mfma_f32_16x16x32_bf16 v[66:69], v[188:191], v[204:207], v[66:69]
	s_setprio 0
	s_barrier
	ds_read_b128 v[158:161], v138 offset:16384
	ds_read_b128 v[162:165], v138 offset:17408
	ds_read_b128 v[166:169], v138 offset:18432
	ds_read_b128 v[170:173], v138 offset:19456
	ds_read_b128 v[174:177], v138 offset:20480
	ds_read_b128 v[180:183], v138 offset:21504
	ds_read_b128 v[184:187], v138 offset:22528
	ds_read_b128 v[188:191], v138 offset:23552
	s_add_u32 s20, s24, s4
	s_addc_u32 s21, s25, s5
	s_add_u32 s20, s20, 0x100
	s_addc_u32 s21, s21, 0
	s_add_i32 s18, s11, 0x10000
	s_mov_b32 m0, s18
	s_nop 0
	global_load_lds_dwordx4 v140, s[20:21]
	s_add_i32 s18, s11, 0x12000
	s_mov_b32 m0, s18
	s_nop 0
	global_load_lds_dwordx4 v139, s[20:21]
	s_add_u32 s20, s8, s4
	s_addc_u32 s21, s9, s5
	s_add_u32 s20, s20, 0x100
	s_addc_u32 s21, s21, 0
	s_mov_b32 m0, s11
	s_nop 0
	global_load_lds_dwordx4 v140, s[20:21]
	s_add_i32 s18, s11, 0x2000
	s_mov_b32 m0, s18
	s_nop 0
	global_load_lds_dwordx4 v139, s[20:21]
	s_add_u32 s20, s22, s4
	s_addc_u32 s21, s23, s5
	s_add_u32 s20, s20, 0x100
	s_addc_u32 s21, s21, 0
	s_add_i32 s18, s11, 0x14000
	s_mov_b32 m0, s18
	s_nop 0
	global_load_lds_dwordx4 v140, s[20:21]
	s_add_i32 s18, s11, 0x16000
	s_mov_b32 m0, s18
	s_nop 0
	global_load_lds_dwordx4 v139, s[20:21]
	s_waitcnt vmcnt(8) lgkmcnt(0)
	s_barrier
; #define WAIT_V(n) asm volatile("s_waitcnt vmcnt(" #n ")" ::: "memory")
; #define WAIT_L(n) asm volatile("s_waitcnt lgkmcnt(" #n ")" ::: "memory")
; #define BAR __builtin_amdgcn_s_barrier()
; #define SCHED __builtin_amdgcn_sched_barrier(0)
; #define STG_A(b, h, kt) stage_half_s(lds0 + ((b) * 2 + (h)) * HT_B, ((h) ? A1 : Ap) + (kt) * BK, off0, off1)
; #define STG_B(b, h, kt) stage_half_s(lds0 + (4 + (b) * 2 + (h)) * HT_B, ((h) ? B1p : Bp) + (kt) * BK, off0, off1)
; #define STG_A(b, h, kt) stage_half_s(lds0 + ((b) * 2 + (h)) * HT_B, ((h) ? A1 : Ap) + (kt) * BK, off0, off1)
; #define STG_B(b, h, kt) stage_half_s(lds0 + (4 + (b) * 2 + (h)) * HT_B, ((h) ? B1p : Bp) + (kt) * BK, off0, off1)
; #define LDA8(b, h) _Pragma("unroll") for (int m = 0; m < 4; ++m) _Pragma("unroll") for (int k = 0; k < 2; ++k) \
;     At[m][k] = *(const bf16x8*)(SA_(shm, b, h) + abase + (m * 2 + k) * 1024)
; #define LDB8(dst, b, h) _Pragma("unroll") for (int n = 0; n < 2; ++n) _Pragma("unroll") for (int k = 0; k < 2; ++k) \
;     dst[n][k] = *(const bf16x8*)(SB_(shm, b, h) + bbase + (n * 2 + k) * 1024)
; #define MMA8(ai, bj, Bx) do { __builtin_amdgcn_s_setprio(1); \
;     _Pragma("unroll") for (int m = 0; m < 4; ++m) _Pragma("unroll") for (int n = 0; n < 2; ++n) _Pragma("unroll") for (int k = 0; k < 2; ++k) \
;       acc[ai][bj][m][n] = __builtin_amdgcn_mfma_f32_16x16x32_bf16(At[m][k], Bx[n][k], acc[ai][bj][m][n], 0, 0, 0); \
;     __builtin_amdgcn_s_setprio(0); } while (0)
; template <bool HS>
; __device__ __forceinline__ void gemm_tile8(const u16* __restrict__ Ap, const u16* __restrict__ Bp, int K,
;                                            f32x4 (&acc)[2][2][4][2], char* shm, const int tid, const float* hsr = nullptr) {
;     ...
;     BAR; WAIT_L(0); MMA8(1, 0, B0); BAR; SCHED;
;     STG_B(0, 1, t + 2);
;     WAIT_V(6); BAR; MMA8(1, 1, B1); BAR;
;     LDB8(B0, 1, 0); SCHED; LDA8(1, 0); STG_A(0, 1, t + 2);
;     WAIT_L(8); BAR; WAIT_L(0); MMA8(0, 0, B0); BAR; SCHED;
;     LDB8(B1, 1, 1); STG_B(1, 0, t + 3);
;     BAR; WAIT_L(0); MMA8(0, 1, B1); BAR;
	s_setprio 1
	v_mfma_f32_16x16x32_bf16 v[62:65], v[158:161], v[142:145], v[62:65]
	v_mfma_f32_16x16x32_bf16 v[58:61], v[158:161], v[150:153], v[58:61]
	v_mfma_f32_16x16x32_bf16 v[54:57], v[166:169], v[142:145], v[54:57]
	v_mfma_f32_16x16x32_bf16 v[50:53], v[166:169], v[150:153], v[50:53]
	v_mfma_f32_16x16x32_bf16 v[46:49], v[174:177], v[142:145], v[46:49]
	v_mfma_f32_16x16x32_bf16 v[42:45], v[174:177], v[150:153], v[42:45]
	v_mfma_f32_16x16x32_bf16 v[38:41], v[184:187], v[142:145], v[38:41]
	v_mfma_f32_16x16x32_bf16 v[34:37], v[184:187], v[150:153], v[34:37]
	v_mfma_f32_16x16x32_bf16 v[62:65], v[162:165], v[146:149], v[62:65]
	v_mfma_f32_16x16x32_bf16 v[58:61], v[162:165], v[154:157], v[58:61]
	v_mfma_f32_16x16x32_bf16 v[54:57], v[170:173], v[146:149], v[54:57]
	v_mfma_f32_16x16x32_bf16 v[50:53], v[170:173], v[154:157], v[50:53]
	v_mfma_f32_16x16x32_bf16 v[46:49], v[180:183], v[146:149], v[46:49]
	v_mfma_f32_16x16x32_bf16 v[42:45], v[180:183], v[154:157], v[42:45]
	v_mfma_f32_16x16x32_bf16 v[38:41], v[188:191], v[146:149], v[38:41]
	v_mfma_f32_16x16x32_bf16 v[34:37], v[188:191], v[154:157], v[34:37]
	v_mfma_f32_16x16x32_bf16 v[30:33], v[158:161], v[192:195], v[30:33]
	v_mfma_f32_16x16x32_bf16 v[26:29], v[158:161], v[200:203], v[26:29]
	v_mfma_f32_16x16x32_bf16 v[22:25], v[166:169], v[192:195], v[22:25]
	v_mfma_f32_16x16x32_bf16 v[18:21], v[166:169], v[200:203], v[18:21]
	v_mfma_f32_16x16x32_bf16 v[14:17], v[174:177], v[192:195], v[14:17]
	v_mfma_f32_16x16x32_bf16 v[10:13], v[174:177], v[200:203], v[10:13]
	v_mfma_f32_16x16x32_bf16 v[6:9], v[184:187], v[192:195], v[6:9]
	v_mfma_f32_16x16x32_bf16 v[2:5], v[184:187], v[200:203], v[2:5]
	v_mfma_f32_16x16x32_bf16 v[30:33], v[162:165], v[196:199], v[30:33]
	v_mfma_f32_16x16x32_bf16 v[26:29], v[162:165], v[204:207], v[26:29]
	v_mfma_f32_16x16x32_bf16 v[22:25], v[170:173], v[196:199], v[22:25]
	v_mfma_f32_16x16x32_bf16 v[18:21], v[170:173], v[204:207], v[18:21]
	v_mfma_f32_16x16x32_bf16 v[14:17], v[180:183], v[196:199], v[14:17]
	v_mfma_f32_16x16x32_bf16 v[10:13], v[180:183], v[204:207], v[10:13]
	v_mfma_f32_16x16x32_bf16 v[6:9], v[188:191], v[196:199], v[6:9]
	v_mfma_f32_16x16x32_bf16 v[2:5], v[188:191], v[204:207], v[2:5]
	s_setprio 0
	s_barrier
	v_add_u32_e32 v154, 0x18000, v141
	ds_read_b128 v[142:145], v154
	ds_read_b128 v[146:149], v154 offset:1024
	ds_read_b128 v[150:153], v154 offset:2048
	ds_read_b128 v[154:157], v154 offset:3072
	ds_read_b128 v[158:161], v138 offset:32768
	ds_read_b128 v[162:165], v138 offset:33792
	ds_read_b128 v[166:169], v138 offset:34816
	ds_read_b128 v[170:173], v138 offset:35840
	ds_read_b128 v[174:177], v138 offset:36864
	ds_read_b128 v[180:183], v138 offset:37888
	ds_read_b128 v[184:187], v138 offset:38912
	ds_read_b128 v[188:191], v138 offset:39936
	v_add_u32_e32 v204, 0x1c000, v141
	ds_read_b128 v[192:195], v204
	ds_read_b128 v[196:199], v204 offset:1024
	ds_read_b128 v[200:203], v204 offset:2048
	ds_read_b128 v[204:207], v204 offset:3072
	s_add_u32 s20, s15, s4
	s_addc_u32 s21, s16, s5
	s_add_u32 s20, s20, 0x100
	s_addc_u32 s21, s21, 0
	s_add_i32 s18, s11, 0x4000
	s_mov_b32 m0, s18
	s_nop 0
	global_load_lds_dwordx4 v140, s[20:21]
	s_add_i32 s18, s11, 0x6000
	s_mov_b32 m0, s18
	s_nop 0
	global_load_lds_dwordx4 v139, s[20:21]
	s_waitcnt vmcnt(8) lgkmcnt(0)
	s_barrier
	s_setprio 1
	v_mfma_f32_16x16x32_bf16 v[126:129], v[158:161], v[142:145], v[126:129]
	v_mfma_f32_16x16x32_bf16 v[122:125], v[158:161], v[150:153], v[122:125]
	v_mfma_f32_16x16x32_bf16 v[118:121], v[166:169], v[142:145], v[118:121]
	v_mfma_f32_16x16x32_bf16 v[114:117], v[166:169], v[150:153], v[114:117]
	v_mfma_f32_16x16x32_bf16 v[110:113], v[174:177], v[142:145], v[110:113]
	v_mfma_f32_16x16x32_bf16 v[106:109], v[174:177], v[150:153], v[106:109]
	v_mfma_f32_16x16x32_bf16 v[102:105], v[184:187], v[142:145], v[102:105]
	v_mfma_f32_16x16x32_bf16 v[98:101], v[184:187], v[150:153], v[98:101]
	v_mfma_f32_16x16x32_bf16 v[126:129], v[162:165], v[146:149], v[126:129]
	v_mfma_f32_16x16x32_bf16 v[122:125], v[162:165], v[154:157], v[122:125]
	v_mfma_f32_16x16x32_bf16 v[118:121], v[170:173], v[146:149], v[118:121]
	v_mfma_f32_16x16x32_bf16 v[114:117], v[170:173], v[154:157], v[114:117]
	v_mfma_f32_16x16x32_bf16 v[110:113], v[180:183], v[146:149], v[110:113]
	v_mfma_f32_16x16x32_bf16 v[106:109], v[180:183], v[154:157], v[106:109]
	v_mfma_f32_16x16x32_bf16 v[102:105], v[188:191], v[146:149], v[102:105]
	v_mfma_f32_16x16x32_bf16 v[98:101], v[188:191], v[154:157], v[98:101]
	v_mfma_f32_16x16x32_bf16 v[94:97], v[158:161], v[192:195], v[94:97]
	v_mfma_f32_16x16x32_bf16 v[90:93], v[158:161], v[200:203], v[90:93]
	v_mfma_f32_16x16x32_bf16 v[86:89], v[166:169], v[192:195], v[86:89]
	v_mfma_f32_16x16x32_bf16 v[82:85], v[166:169], v[200:203], v[82:85]
	v_mfma_f32_16x16x32_bf16 v[78:81], v[174:177], v[192:195], v[78:81]
	v_mfma_f32_16x16x32_bf16 v[74:77], v[174:177], v[200:203], v[74:77]
	v_mfma_f32_16x16x32_bf16 v[70:73], v[184:187], v[192:195], v[70:73]
	v_mfma_f32_16x16x32_bf16 v[66:69], v[184:187], v[200:203], v[66:69]
	v_mfma_f32_16x16x32_bf16 v[94:97], v[162:165], v[196:199], v[94:97]
	v_mfma_f32_16x16x32_bf16 v[90:93], v[162:165], v[204:207], v[90:93]
	v_mfma_f32_16x16x32_bf16 v[86:89], v[170:173], v[196:199], v[86:89]
	v_mfma_f32_16x16x32_bf16 v[82:85], v[170:173], v[204:207], v[82:85]
	v_mfma_f32_16x16x32_bf16 v[78:81], v[180:183], v[196:199], v[78:81]
	v_mfma_f32_16x16x32_bf16 v[74:77], v[180:183], v[204:207], v[74:77]
	v_mfma_f32_16x16x32_bf16 v[70:73], v[188:191], v[196:199], v[70:73]
	v_mfma_f32_16x16x32_bf16 v[66:69], v[188:191], v[204:207], v[66:69]
	s_setprio 0
	s_barrier
; #define WAIT_V(n) asm volatile("s_waitcnt vmcnt(" #n ")" ::: "memory")
; #define WAIT_L(n) asm volatile("s_waitcnt lgkmcnt(" #n ")" ::: "memory")
; #define BAR __builtin_amdgcn_s_barrier()
; #define SCHED __builtin_amdgcn_sched_barrier(0)
; #define STG_A(b, h, kt) stage_half_s(lds0 + ((b) * 2 + (h)) * HT_B, ((h) ? A1 : Ap) + (kt) * BK, off0, off1)
; #define STG_B(b, h, kt) stage_half_s(lds0 + (4 + (b) * 2 + (h)) * HT_B, ((h) ? B1p : Bp) + (kt) * BK, off0, off1)
; #define STG_A(b, h, kt) stage_half_s(lds0 + ((b) * 2 + (h)) * HT_B, ((h) ? A1 : Ap) + (kt) * BK, off0, off1)
; #define STG_B(b, h, kt) stage_half_s(lds0 + (4 + (b) * 2 + (h)) * HT_B, ((h) ? B1p : Bp) + (kt) * BK, off0, off1)
; #define LDA8(b, h) _Pragma("unroll") for (int m = 0; m < 4; ++m) _Pragma("unroll") for (int k = 0; k < 2; ++k) \
;     At[m][k] = *(const bf16x8*)(SA_(shm, b, h) + abase + (m * 2 + k) * 1024)
; #define LDB8(dst, b, h) _Pragma("unroll") for (int n = 0; n < 2; ++n) _Pragma("unroll") for (int k = 0; k < 2; ++k) \
;     dst[n][k] = *(const bf16x8*)(SB_(shm, b, h) + bbase + (n * 2 + k) * 1024)
; #define MMA8(ai, bj, Bx) do { __builtin_amdgcn_s_setprio(1); \
;     _Pragma("unroll") for (int m = 0; m < 4; ++m) _Pragma("unroll") for (int n = 0; n < 2; ++n) _Pragma("unroll") for (int k = 0; k < 2; ++k) \
;       acc[ai][bj][m][n] = __builtin_amdgcn_mfma_f32_16x16x32_bf16(At[m][k], Bx[n][k], acc[ai][bj][m][n], 0, 0, 0); \
;     __builtin_amdgcn_s_setprio(0); } while (0)
; template <bool HS>
; __device__ __forceinline__ void gemm_tile8(const u16* __restrict__ Ap, const u16* __restrict__ Bp, int K,
;                                            f32x4 (&acc)[2][2][4][2], char* shm, const int tid, const float* hsr = nullptr) {
;     ...
;     LDA8(1, 1); STG_A(1, 0, t + 3);
;     BAR; WAIT_L(0); MMA8(1, 0, B0); BAR; SCHED;
;     STG_B(1, 1, t + 3);
;     WAIT_V(6); BAR; MMA8(1, 1, B1); BAR;
;   }
;   { LDB8(B0, 0, 0); LDA8(0, 0); STG_A(1, 1, nt - 1);
;     BAR; WAIT_L(0); MMA8(0, 0, B0); BAR;
	ds_read_b128 v[158:161], v138 offset:49152
	ds_read_b128 v[162:165], v138 offset:50176
	ds_read_b128 v[166:169], v138 offset:51200
	ds_read_b128 v[170:173], v138 offset:52224
	ds_read_b128 v[174:177], v138 offset:53248
	ds_read_b128 v[180:183], v138 offset:54272
	ds_read_b128 v[184:187], v138 offset:55296
	ds_read_b128 v[188:191], v138 offset:56320
	s_add_u32 s20, s24, s4
	s_addc_u32 s21, s25, s5
	s_add_u32 s20, s20, 0x180
	s_addc_u32 s21, s21, 0
	s_add_i32 s18, s11, 0x18000
	s_mov_b32 m0, s18
	s_nop 0
	global_load_lds_dwordx4 v140, s[20:21]
	s_add_i32 s18, s11, 0x1a000
	s_mov_b32 m0, s18
	s_nop 0
	global_load_lds_dwordx4 v139, s[20:21]
	s_add_u32 s20, s8, s4
	s_addc_u32 s21, s9, s5
	s_add_u32 s20, s20, 0x180
	s_addc_u32 s21, s21, 0
	s_add_i32 s18, s11, 0x8000
	s_mov_b32 m0, s18
	s_nop 0
	global_load_lds_dwordx4 v140, s[20:21]
	s_add_i32 s18, s11, 0xa000
	s_mov_b32 m0, s18
	s_nop 0
	global_load_lds_dwordx4 v139, s[20:21]
	s_add_u32 s20, s22, s4
	s_addc_u32 s21, s23, s5
	s_add_u32 s20, s20, 0x180
	s_addc_u32 s21, s21, 0
	s_add_i32 s18, s11, 0x1c000
	s_mov_b32 m0, s18
	s_nop 0
	global_load_lds_dwordx4 v140, s[20:21]
	s_add_i32 s18, s11, 0x1e000
	s_mov_b32 m0, s18
	s_nop 0
	global_load_lds_dwordx4 v139, s[20:21]
	s_waitcnt vmcnt(8) lgkmcnt(0)
	s_barrier
	s_setprio 1
	v_mfma_f32_16x16x32_bf16 v[62:65], v[158:161], v[142:145], v[62:65]
	v_mfma_f32_16x16x32_bf16 v[58:61], v[158:161], v[150:153], v[58:61]
	v_mfma_f32_16x16x32_bf16 v[54:57], v[166:169], v[142:145], v[54:57]
	v_mfma_f32_16x16x32_bf16 v[50:53], v[166:169], v[150:153], v[50:53]
	v_mfma_f32_16x16x32_bf16 v[46:49], v[174:177], v[142:145], v[46:49]
	v_mfma_f32_16x16x32_bf16 v[42:45], v[174:177], v[150:153], v[42:45]
	v_mfma_f32_16x16x32_bf16 v[38:41], v[184:187], v[142:145], v[38:41]
	v_mfma_f32_16x16x32_bf16 v[34:37], v[184:187], v[150:153], v[34:37]
	v_mfma_f32_16x16x32_bf16 v[62:65], v[162:165], v[146:149], v[62:65]
	v_mfma_f32_16x16x32_bf16 v[58:61], v[162:165], v[154:157], v[58:61]
	v_mfma_f32_16x16x32_bf16 v[54:57], v[170:173], v[146:149], v[54:57]
	v_mfma_f32_16x16x32_bf16 v[50:53], v[170:173], v[154:157], v[50:53]
	v_mfma_f32_16x16x32_bf16 v[46:49], v[180:183], v[146:149], v[46:49]
	v_mfma_f32_16x16x32_bf16 v[42:45], v[180:183], v[154:157], v[42:45]
	v_mfma_f32_16x16x32_bf16 v[38:41], v[188:191], v[146:149], v[38:41]
	v_mfma_f32_16x16x32_bf16 v[34:37], v[188:191], v[154:157], v[34:37]
	v_mfma_f32_16x16x32_bf16 v[30:33], v[158:161], v[192:195], v[30:33]
	v_mfma_f32_16x16x32_bf16 v[26:29], v[158:161], v[200:203], v[26:29]
	v_mfma_f32_16x16x32_bf16 v[22:25], v[166:169], v[192:195], v[22:25]
	v_mfma_f32_16x16x32_bf16 v[18:21], v[166:169], v[200:203], v[18:21]
	v_mfma_f32_16x16x32_bf16 v[14:17], v[174:177], v[192:195], v[14:17]
	v_mfma_f32_16x16x32_bf16 v[10:13], v[174:177], v[200:203], v[10:13]
	v_mfma_f32_16x16x32_bf16 v[6:9], v[184:187], v[192:195], v[6:9]
	v_mfma_f32_16x16x32_bf16 v[2:5], v[184:187], v[200:203], v[2:5]
	v_mfma_f32_16x16x32_bf16 v[30:33], v[162:165], v[196:199], v[30:33]
	v_mfma_f32_16x16x32_bf16 v[26:29], v[162:165], v[204:207], v[26:29]
	v_mfma_f32_16x16x32_bf16 v[22:25], v[170:173], v[196:199], v[22:25]
	v_mfma_f32_16x16x32_bf16 v[18:21], v[170:173], v[204:207], v[18:21]
	v_mfma_f32_16x16x32_bf16 v[14:17], v[180:183], v[196:199], v[14:17]
	v_mfma_f32_16x16x32_bf16 v[10:13], v[180:183], v[204:207], v[10:13]
	v_mfma_f32_16x16x32_bf16 v[6:9], v[188:191], v[196:199], v[6:9]
	v_mfma_f32_16x16x32_bf16 v[2:5], v[188:191], v[204:207], v[2:5]
	s_setprio 0
	s_add_i32 s17, s17, 2
	s_add_u32 s4, s4, 0x100
	s_addc_u32 s5, s5, 0
	s_cmp_lt_u32 s17, 12
	s_barrier
	s_cbranch_scc1 .Lk_conv_in
	s_waitcnt vmcnt(6)
	s_add_i32 s18, s11, 0xc000
	s_add_i32 s19, s11, 0xe000
	v_add_u32_e32 v220, 0, v141
	v_add_u32_e32 v141, 0x10000, v220
	ds_read_b128 v[130:133], v141
	ds_read_b128 v[142:145], v141 offset:1024
	ds_read_b128 v[146:149], v141 offset:2048
	ds_read_b128 v[150:153], v141 offset:3072
	ds_read_b128 v[154:157], v138
	ds_read_b128 v[158:161], v138 offset:1024
	ds_read_b128 v[162:165], v138 offset:2048
	ds_read_b128 v[166:169], v138 offset:3072
	ds_read_b128 v[170:173], v138 offset:4096
	ds_read_b128 v[174:177], v138 offset:5120
	ds_read_b128 v[180:183], v138 offset:6144
	ds_read_b128 v[184:187], v138 offset:7168
	s_add_u32 s4, s8, 0x40780
	s_addc_u32 s5, s9, 0
	s_mov_b32 m0, s18
	s_nop 0
	global_load_lds_dwordx4 v140, s[4:5]
	s_nop 0
	s_mov_b32 m0, s19
	s_nop 0
	global_load_lds_dwordx4 v139, s[4:5]
	s_barrier
	s_waitcnt lgkmcnt(0)
	s_setprio 1
	s_waitcnt lgkmcnt(7)
	v_mfma_f32_16x16x32_bf16 v[126:129], v[154:157], v[130:133], v[126:129]
	v_mfma_f32_16x16x32_bf16 v[122:125], v[154:157], v[146:149], v[122:125]
	s_waitcnt lgkmcnt(3)
	v_mfma_f32_16x16x32_bf16 v[110:113], v[170:173], v[130:133], v[110:113]
	v_mfma_f32_16x16x32_bf16 v[106:109], v[170:173], v[146:149], v[106:109]
	v_mfma_f32_16x16x32_bf16 v[126:129], v[158:161], v[142:145], v[126:129]
	v_mfma_f32_16x16x32_bf16 v[122:125], v[158:161], v[150:153], v[122:125]
	v_mfma_f32_16x16x32_bf16 v[118:121], v[162:165], v[130:133], v[118:121]
	v_mfma_f32_16x16x32_bf16 v[114:117], v[162:165], v[146:149], v[114:117]
	s_waitcnt lgkmcnt(2)
	v_mfma_f32_16x16x32_bf16 v[110:113], v[174:177], v[142:145], v[110:113]
	v_mfma_f32_16x16x32_bf16 v[106:109], v[174:177], v[150:153], v[106:109]
	s_waitcnt lgkmcnt(1)
	v_mfma_f32_16x16x32_bf16 v[102:105], v[180:183], v[130:133], v[102:105]
	v_mfma_f32_16x16x32_bf16 v[98:101], v[180:183], v[146:149], v[98:101]
	v_mfma_f32_16x16x32_bf16 v[188:191], v[166:169], v[142:145], v[118:121]
	v_mfma_f32_16x16x32_bf16 v[192:195], v[166:169], v[150:153], v[114:117]
	s_waitcnt lgkmcnt(0)
	v_mfma_f32_16x16x32_bf16 v[196:199], v[184:187], v[142:145], v[102:105]
	v_mfma_f32_16x16x32_bf16 v[200:203], v[184:187], v[150:153], v[98:101]
	s_setprio 0
	v_add_u32_e32 v118, 0x14000, v220
	s_barrier
; #define WAIT_V(n) asm volatile("s_waitcnt vmcnt(" #n ")" ::: "memory")
; #define WAIT_L(n) asm volatile("s_waitcnt lgkmcnt(" #n ")" ::: "memory")
; #define BAR __builtin_amdgcn_s_barrier()
; #define LDA8(b, h) _Pragma("unroll") for (int m = 0; m < 4; ++m) _Pragma("unroll") for (int k = 0; k < 2; ++k) \
;     At[m][k] = *(const bf16x8*)(SA_(shm, b, h) + abase + (m * 2 + k) * 1024)
; #define LDB8(dst, b, h) _Pragma("unroll") for (int n = 0; n < 2; ++n) _Pragma("unroll") for (int k = 0; k < 2; ++k) \
;     dst[n][k] = *(const bf16x8*)(SB_(shm, b, h) + bbase + (n * 2 + k) * 1024)
; #define MMA8(ai, bj, Bx) do { __builtin_amdgcn_s_setprio(1); \
;     _Pragma("unroll") for (int m = 0; m < 4; ++m) _Pragma("unroll") for (int n = 0; n < 2; ++n) _Pragma("unroll") for (int k = 0; k < 2; ++k) \
;       acc[ai][bj][m][n] = __builtin_amdgcn_mfma_f32_16x16x32_bf16(At[m][k], Bx[n][k], acc[ai][bj][m][n], 0, 0, 0); \
;     __builtin_amdgcn_s_setprio(0); } while (0)
; template <bool HS>
; __device__ __forceinline__ void gemm_tile8(const u16* __restrict__ Ap, const u16* __restrict__ Bp, int K,
;                                            f32x4 (&acc)[2][2][4][2], char* shm, const int tid, const float* hsr = nullptr) {
;     ...
;     BAR; WAIT_L(0); MMA8(0, 0, B0); BAR;
;     LDB8(B1, 0, 1); BAR; WAIT_L(0); MMA8(0, 1, B1); BAR;
;     LDA8(0, 1); WAIT_V(4); BAR; WAIT_L(0); MMA8(1, 0, B0); MMA8(1, 1, B1); BAR; }
;   { LDB8(B0, 1, 0); LDA8(1, 0); WAIT_V(2); BAR; WAIT_L(0); MMA8(0, 0, B0); BAR;
	ds_read_b128 v[98:101], v118
	ds_read_b128 v[102:105], v118 offset:1024
	ds_read_b128 v[114:117], v118 offset:2048
	ds_read_b128 v[118:121], v118 offset:3072
	s_barrier
	s_waitcnt lgkmcnt(0)
	s_setprio 1
	s_waitcnt lgkmcnt(3)
	v_mfma_f32_16x16x32_bf16 v[94:97], v[154:157], v[98:101], v[94:97]
	s_waitcnt lgkmcnt(1)
	v_mfma_f32_16x16x32_bf16 v[90:93], v[154:157], v[114:117], v[90:93]
	v_mfma_f32_16x16x32_bf16 v[78:81], v[170:173], v[98:101], v[78:81]
	v_mfma_f32_16x16x32_bf16 v[74:77], v[170:173], v[114:117], v[74:77]
	v_mfma_f32_16x16x32_bf16 v[94:97], v[158:161], v[102:105], v[94:97]
	s_waitcnt lgkmcnt(0)
	v_mfma_f32_16x16x32_bf16 v[90:93], v[158:161], v[118:121], v[90:93]
	v_mfma_f32_16x16x32_bf16 v[86:89], v[162:165], v[98:101], v[86:89]
	v_mfma_f32_16x16x32_bf16 v[82:85], v[162:165], v[114:117], v[82:85]
	v_mfma_f32_16x16x32_bf16 v[78:81], v[174:177], v[102:105], v[78:81]
	v_mfma_f32_16x16x32_bf16 v[74:77], v[174:177], v[118:121], v[74:77]
	v_mfma_f32_16x16x32_bf16 v[70:73], v[180:183], v[98:101], v[70:73]
	v_mfma_f32_16x16x32_bf16 v[66:69], v[180:183], v[114:117], v[66:69]
	v_mfma_f32_16x16x32_bf16 v[154:157], v[166:169], v[102:105], v[86:89]
	v_mfma_f32_16x16x32_bf16 v[158:161], v[166:169], v[118:121], v[82:85]
	v_mfma_f32_16x16x32_bf16 v[162:165], v[184:187], v[102:105], v[70:73]
	v_mfma_f32_16x16x32_bf16 v[166:169], v[184:187], v[118:121], v[66:69]
	s_setprio 0
	s_barrier
	s_nop 1
	ds_read_b128 v[66:69], v138 offset:16384
	ds_read_b128 v[70:73], v138 offset:17408
	ds_read_b128 v[82:85], v138 offset:18432
	ds_read_b128 v[86:89], v138 offset:19456
	ds_read_b128 v[170:173], v138 offset:20480
	ds_read_b128 v[174:177], v138 offset:21504
	ds_read_b128 v[180:183], v138 offset:22528
	ds_read_b128 v[184:187], v138 offset:23552
	s_waitcnt vmcnt(4)
	s_barrier
	s_waitcnt lgkmcnt(0)
	s_setprio 1
	s_waitcnt lgkmcnt(7)
	v_mfma_f32_16x16x32_bf16 v[62:65], v[66:69], v[130:133], v[62:65]
	s_waitcnt lgkmcnt(5)
	v_mfma_f32_16x16x32_bf16 v[54:57], v[82:85], v[130:133], v[54:57]
	s_waitcnt lgkmcnt(3)
	v_mfma_f32_16x16x32_bf16 v[46:49], v[170:173], v[130:133], v[46:49]
	s_waitcnt lgkmcnt(1)
	v_mfma_f32_16x16x32_bf16 v[38:41], v[180:183], v[130:133], v[38:41]
	v_mfma_f32_16x16x32_bf16 v[62:65], v[70:73], v[142:145], v[62:65]
	v_mfma_f32_16x16x32_bf16 v[58:61], v[66:69], v[146:149], v[58:61]
	v_mfma_f32_16x16x32_bf16 v[54:57], v[86:89], v[142:145], v[54:57]
	v_mfma_f32_16x16x32_bf16 v[50:53], v[82:85], v[146:149], v[50:53]
	v_mfma_f32_16x16x32_bf16 v[46:49], v[174:177], v[142:145], v[46:49]
	v_mfma_f32_16x16x32_bf16 v[42:45], v[170:173], v[146:149], v[42:45]
	s_waitcnt lgkmcnt(0)
	v_mfma_f32_16x16x32_bf16 v[38:41], v[184:187], v[142:145], v[38:41]
	v_mfma_f32_16x16x32_bf16 v[34:37], v[180:183], v[146:149], v[34:37]
	v_mfma_f32_16x16x32_bf16 v[204:207], v[70:73], v[150:153], v[58:61]
	v_mfma_f32_16x16x32_bf16 v[208:211], v[86:89], v[150:153], v[50:53]
	v_mfma_f32_16x16x32_bf16 v[212:215], v[174:177], v[150:153], v[42:45]
	v_mfma_f32_16x16x32_bf16 v[130:133], v[184:187], v[150:153], v[34:37]
	s_setprio 0
	s_setprio 1
	v_mfma_f32_16x16x32_bf16 v[30:33], v[66:69], v[98:101], v[30:33]
	v_mfma_f32_16x16x32_bf16 v[22:25], v[82:85], v[98:101], v[22:25]
	v_mfma_f32_16x16x32_bf16 v[14:17], v[170:173], v[98:101], v[14:17]
	v_mfma_f32_16x16x32_bf16 v[6:9], v[180:183], v[98:101], v[6:9]
	v_mfma_f32_16x16x32_bf16 v[30:33], v[70:73], v[102:105], v[30:33]
	v_mfma_f32_16x16x32_bf16 v[26:29], v[66:69], v[114:117], v[26:29]
	v_mfma_f32_16x16x32_bf16 v[22:25], v[86:89], v[102:105], v[22:25]
	v_mfma_f32_16x16x32_bf16 v[18:21], v[82:85], v[114:117], v[18:21]
	v_mfma_f32_16x16x32_bf16 v[14:17], v[174:177], v[102:105], v[14:17]
	v_mfma_f32_16x16x32_bf16 v[10:13], v[170:173], v[114:117], v[10:13]
	v_mfma_f32_16x16x32_bf16 v[6:9], v[184:187], v[102:105], v[6:9]
	v_mfma_f32_16x16x32_bf16 v[2:5], v[180:183], v[114:117], v[2:5]
	v_mfma_f32_16x16x32_bf16 v[140:143], v[70:73], v[118:121], v[26:29]
	v_mfma_f32_16x16x32_bf16 v[144:147], v[86:89], v[118:121], v[18:21]
	v_mfma_f32_16x16x32_bf16 v[148:151], v[174:177], v[118:121], v[10:13]
	v_mfma_f32_16x16x32_bf16 v[170:173], v[184:187], v[118:121], v[2:5]
	s_setprio 0
	v_add_u32_e32 v18, 0x18000, v220
	s_barrier
	s_nop 0
	ds_read_b128 v[2:5], v18
	ds_read_b128 v[10:13], v18 offset:1024
	ds_read_b128 v[174:177], v18 offset:2048
	ds_read_b128 v[180:183], v18 offset:3072
	ds_read_b128 v[18:21], v138 offset:32768
	ds_read_b128 v[26:29], v138 offset:33792
	ds_read_b128 v[34:37], v138 offset:34816
	ds_read_b128 v[42:45], v138 offset:35840
	ds_read_b128 v[50:53], v138 offset:36864
	ds_read_b128 v[58:61], v138 offset:37888
	ds_read_b128 v[184:187], v138 offset:38912
	ds_read_b128 v[216:219], v138 offset:39936
	s_waitcnt vmcnt(2)
	s_barrier
; #define WAIT_V(n) asm volatile("s_waitcnt vmcnt(" #n ")" ::: "memory")
; #define WAIT_L(n) asm volatile("s_waitcnt lgkmcnt(" #n ")" ::: "memory")
; #define BAR __builtin_amdgcn_s_barrier()
; #define LDA8(b, h) _Pragma("unroll") for (int m = 0; m < 4; ++m) _Pragma("unroll") for (int k = 0; k < 2; ++k) \
;     At[m][k] = *(const bf16x8*)(SA_(shm, b, h) + abase + (m * 2 + k) * 1024)
; #define LDB8(dst, b, h) _Pragma("unroll") for (int n = 0; n < 2; ++n) _Pragma("unroll") for (int k = 0; k < 2; ++k) \
;     dst[n][k] = *(const bf16x8*)(SB_(shm, b, h) + bbase + (n * 2 + k) * 1024)
; #define MMA8(ai, bj, Bx) do { __builtin_amdgcn_s_setprio(1); \
;     _Pragma("unroll") for (int m = 0; m < 4; ++m) _Pragma("unroll") for (int n = 0; n < 2; ++n) _Pragma("unroll") for (int k = 0; k < 2; ++k) \
;       acc[ai][bj][m][n] = __builtin_amdgcn_mfma_f32_16x16x32_bf16(At[m][k], Bx[n][k], acc[ai][bj][m][n], 0, 0, 0); \
;     __builtin_amdgcn_s_setprio(0); } while (0)
; template <bool HS>
; __device__ __forceinline__ void gemm_tile8(const u16* __restrict__ Ap, const u16* __restrict__ Bp, int K,
;                                            f32x4 (&acc)[2][2][4][2], char* shm, const int tid, const float* hsr = nullptr) {
;     ...
;   { LDB8(B0, 1, 0); LDA8(1, 0); WAIT_V(2); BAR; WAIT_L(0); MMA8(0, 0, B0); BAR;
;     LDB8(B1, 1, 1); WAIT_V(0); BAR; WAIT_L(0); MMA8(0, 1, B1); BAR;
;     LDA8(1, 1); BAR; WAIT_L(0); MMA8(1, 0, B0); MMA8(1, 1, B1); BAR; }
;   if (wr == 0) BAR;
	s_waitcnt lgkmcnt(0)
	s_setprio 1
	s_waitcnt lgkmcnt(7)
	v_mfma_f32_16x16x32_bf16 v[66:69], v[18:21], v[2:5], v[126:129]
	s_waitcnt lgkmcnt(6)
	v_mfma_f32_16x16x32_bf16 v[118:121], v[26:29], v[10:13], v[66:69]
	v_mfma_f32_16x16x32_bf16 v[66:69], v[18:21], v[174:177], v[122:125]
	v_mfma_f32_16x16x32_bf16 v[114:117], v[26:29], v[180:183], v[66:69]
	s_waitcnt lgkmcnt(5)
	v_mfma_f32_16x16x32_bf16 v[66:69], v[34:37], v[2:5], v[188:191]
	s_waitcnt lgkmcnt(4)
	v_mfma_f32_16x16x32_bf16 v[102:105], v[42:45], v[10:13], v[66:69]
	v_mfma_f32_16x16x32_bf16 v[66:69], v[34:37], v[174:177], v[192:195]
	v_mfma_f32_16x16x32_bf16 v[98:101], v[42:45], v[180:183], v[66:69]
	s_waitcnt lgkmcnt(3)
	v_mfma_f32_16x16x32_bf16 v[66:69], v[50:53], v[2:5], v[110:113]
	s_waitcnt lgkmcnt(2)
	v_mfma_f32_16x16x32_bf16 v[86:89], v[58:61], v[10:13], v[66:69]
	v_mfma_f32_16x16x32_bf16 v[66:69], v[50:53], v[174:177], v[106:109]
	v_mfma_f32_16x16x32_bf16 v[82:85], v[58:61], v[180:183], v[66:69]
	s_waitcnt lgkmcnt(1)
	v_mfma_f32_16x16x32_bf16 v[66:69], v[184:187], v[2:5], v[196:199]
	s_waitcnt lgkmcnt(0)
	v_mfma_f32_16x16x32_bf16 v[70:73], v[216:219], v[10:13], v[66:69]
	v_mfma_f32_16x16x32_bf16 v[66:69], v[184:187], v[174:177], v[200:203]
	v_mfma_f32_16x16x32_bf16 v[66:69], v[216:219], v[180:183], v[66:69]
	s_setprio 0
	v_add_u32_e32 v106, 0x1c000, v220
	s_barrier
	ds_read_b128 v[188:191], v106
	ds_read_b128 v[192:195], v106 offset:1024
	ds_read_b128 v[196:199], v106 offset:2048
	ds_read_b128 v[200:203], v106 offset:3072
	s_waitcnt vmcnt(0)
	s_barrier
	s_waitcnt lgkmcnt(0)
	s_setprio 1
	s_waitcnt lgkmcnt(3)
	v_mfma_f32_16x16x32_bf16 v[94:97], v[18:21], v[188:191], v[94:97]
	s_waitcnt lgkmcnt(1)
	v_mfma_f32_16x16x32_bf16 v[18:21], v[18:21], v[196:199], v[90:93]
	s_waitcnt lgkmcnt(0)
	v_mfma_f32_16x16x32_bf16 v[122:125], v[26:29], v[200:203], v[18:21]
	v_mfma_f32_16x16x32_bf16 v[18:21], v[34:37], v[188:191], v[154:157]
	v_mfma_f32_16x16x32_bf16 v[110:113], v[42:45], v[192:195], v[18:21]
	v_mfma_f32_16x16x32_bf16 v[18:21], v[34:37], v[196:199], v[158:161]
	v_mfma_f32_16x16x32_bf16 v[106:109], v[42:45], v[200:203], v[18:21]
	v_mfma_f32_16x16x32_bf16 v[18:21], v[50:53], v[188:191], v[78:81]
	v_mfma_f32_16x16x32_bf16 v[126:129], v[26:29], v[192:195], v[94:97]
	v_mfma_f32_16x16x32_bf16 v[94:97], v[58:61], v[192:195], v[18:21]
	v_mfma_f32_16x16x32_bf16 v[18:21], v[50:53], v[196:199], v[74:77]
	v_mfma_f32_16x16x32_bf16 v[90:93], v[58:61], v[200:203], v[18:21]
	v_mfma_f32_16x16x32_bf16 v[18:21], v[184:187], v[188:191], v[162:165]
	v_mfma_f32_16x16x32_bf16 v[78:81], v[216:219], v[192:195], v[18:21]
	v_mfma_f32_16x16x32_bf16 v[18:21], v[184:187], v[196:199], v[166:169]
	v_mfma_f32_16x16x32_bf16 v[74:77], v[216:219], v[200:203], v[18:21]
	s_setprio 0
	s_barrier
	ds_read_b128 v[152:155], v138 offset:49152
	ds_read_b128 v[156:159], v138 offset:50176
	ds_read_b128 v[160:163], v138 offset:51200
	ds_read_b128 v[164:167], v138 offset:52224
	ds_read_b128 v[184:187], v138 offset:53248
	ds_read_b128 v[216:219], v138 offset:54272
	ds_read_b128 v[220:223], v138 offset:55296
	ds_read_b128 v[224:227], v138 offset:56320
	s_barrier
	s_waitcnt lgkmcnt(0)
	s_setprio 1
	s_waitcnt lgkmcnt(7)
	v_mfma_f32_16x16x32_bf16 v[18:21], v[152:155], v[2:5], v[62:65]
	s_waitcnt lgkmcnt(6)
	v_mfma_f32_16x16x32_bf16 v[58:61], v[156:159], v[10:13], v[18:21]
	v_mfma_f32_16x16x32_bf16 v[18:21], v[152:155], v[174:177], v[204:207]
	v_mfma_f32_16x16x32_bf16 v[50:53], v[156:159], v[180:183], v[18:21]
	s_waitcnt lgkmcnt(5)
	v_mfma_f32_16x16x32_bf16 v[18:21], v[160:163], v[2:5], v[54:57]
	s_waitcnt lgkmcnt(4)
	v_mfma_f32_16x16x32_bf16 v[42:45], v[164:167], v[10:13], v[18:21]
	v_mfma_f32_16x16x32_bf16 v[18:21], v[160:163], v[174:177], v[208:211]
	v_mfma_f32_16x16x32_bf16 v[34:37], v[164:167], v[180:183], v[18:21]
	s_waitcnt lgkmcnt(3)
	v_mfma_f32_16x16x32_bf16 v[18:21], v[184:187], v[2:5], v[46:49]
	s_waitcnt lgkmcnt(1)
	v_mfma_f32_16x16x32_bf16 v[2:5], v[220:223], v[2:5], v[38:41]
	v_mfma_f32_16x16x32_bf16 v[26:29], v[216:219], v[10:13], v[18:21]
	v_mfma_f32_16x16x32_bf16 v[18:21], v[184:187], v[174:177], v[212:215]
	s_waitcnt lgkmcnt(0)
	v_mfma_f32_16x16x32_bf16 v[10:13], v[224:227], v[10:13], v[2:5]
	v_mfma_f32_16x16x32_bf16 v[2:5], v[220:223], v[174:177], v[130:133]
	v_mfma_f32_16x16x32_bf16 v[18:21], v[216:219], v[180:183], v[18:21]
	v_mfma_f32_16x16x32_bf16 v[2:5], v[224:227], v[180:183], v[2:5]
	s_setprio 0
	s_setprio 1
	v_mfma_f32_16x16x32_bf16 v[30:33], v[152:155], v[188:191], v[30:33]
	v_mfma_f32_16x16x32_bf16 v[62:65], v[156:159], v[192:195], v[30:33]
	v_mfma_f32_16x16x32_bf16 v[30:33], v[152:155], v[196:199], v[140:143]
	v_mfma_f32_16x16x32_bf16 v[22:25], v[160:163], v[188:191], v[22:25]
	v_mfma_f32_16x16x32_bf16 v[14:17], v[184:187], v[188:191], v[14:17]
	v_mfma_f32_16x16x32_bf16 v[54:57], v[156:159], v[200:203], v[30:33]
	v_mfma_f32_16x16x32_bf16 v[46:49], v[164:167], v[192:195], v[22:25]
	v_mfma_f32_16x16x32_bf16 v[22:25], v[160:163], v[196:199], v[144:147]
	v_mfma_f32_16x16x32_bf16 v[30:33], v[216:219], v[192:195], v[14:17]
	v_mfma_f32_16x16x32_bf16 v[14:17], v[184:187], v[196:199], v[148:151]
	v_mfma_f32_16x16x32_bf16 v[6:9], v[220:223], v[188:191], v[6:9]
	v_mfma_f32_16x16x32_bf16 v[38:41], v[164:167], v[200:203], v[22:25]
	v_mfma_f32_16x16x32_bf16 v[22:25], v[216:219], v[200:203], v[14:17]
	v_mfma_f32_16x16x32_bf16 v[14:17], v[224:227], v[192:195], v[6:9]
	v_mfma_f32_16x16x32_bf16 v[6:9], v[220:223], v[196:199], v[170:173]
	v_mfma_f32_16x16x32_bf16 v[6:9], v[224:227], v[200:203], v[6:9]
	s_setprio 0
	s_movk_i32 s4, 0x100
	v_cmp_gt_u32_e32 vcc, s4, v0
	s_barrier
	s_and_saveexec_b64 s[4:5], vcc
	s_cbranch_execz .LBB0_321
	s_barrier

; #define WAIT_L(n) asm volatile("s_waitcnt lgkmcnt(" #n ")" ::: "memory")
; #define BAR __builtin_amdgcn_s_barrier()
; #define SCHED __builtin_amdgcn_sched_barrier(0)
; #define STG_A(b, h, kt) stage_half_s(lds0 + ((b) * 2 + (h)) * HT_B, ((h) ? A1 : Ap) + (kt) * BK, off0, off1)
; #define STG_B(b, h, kt) stage_half_s(lds0 + (4 + (b) * 2 + (h)) * HT_B, ((h) ? B1p : Bp) + (kt) * BK, off0, off1)
; #define STG_A(b, h, kt) stage_half_s(lds0 + ((b) * 2 + (h)) * HT_B, ((h) ? A1 : Ap) + (kt) * BK, off0, off1)
; #define STG_B(b, h, kt) stage_half_s(lds0 + (4 + (b) * 2 + (h)) * HT_B, ((h) ? B1p : Bp) + (kt) * BK, off0, off1)
; #define LDA8(b, h) _Pragma("unroll") for (int m = 0; m < 4; ++m) _Pragma("unroll") for (int k = 0; k < 2; ++k) \
;     At[m][k] = *(const bf16x8*)(SA_(shm, b, h) + abase + (m * 2 + k) * 1024)
; #define LDB8(dst, b, h) _Pragma("unroll") for (int n = 0; n < 2; ++n) _Pragma("unroll") for (int k = 0; k < 2; ++k) \
;     dst[n][k] = *(const bf16x8*)(SB_(shm, b, h) + bbase + (n * 2 + k) * 1024)
; #define MMA8(ai, bj, Bx) do { __builtin_amdgcn_s_setprio(1); \
;     _Pragma("unroll") for (int m = 0; m < 4; ++m) _Pragma("unroll") for (int n = 0; n < 2; ++n) _Pragma("unroll") for (int k = 0; k < 2; ++k) \
;       acc[ai][bj][m][n] = __builtin_amdgcn_mfma_f32_16x16x32_bf16(At[m][k], Bx[n][k], acc[ai][bj][m][n], 0, 0, 0); \
;     __builtin_amdgcn_s_setprio(0); } while (0)
; template <bool HS>
; __device__ __forceinline__ void gemm_tile8(const u16* __restrict__ Ap, const u16* __restrict__ Bp, int K,
;                                            f32x4 (&acc)[2][2][4][2], char* shm, const int tid, const float* hsr = nullptr) {
;     ...
;     LDB8(B0, 0, 0); SCHED; LDA8(0, 0); STG_A(1, 1, t + 1);
;     WAIT_L(8); BAR; WAIT_L(0); MMA8(0, 0, B0); BAR; SCHED;
;     LDB8(B1, 0, 1); STG_B(0, 0, t + 2);
;     BAR; WAIT_L(0); MMA8(0, 1, B1); BAR;
;     LDA8(0, 1); STG_A(0, 0, t + 2);
;     BAR; WAIT_L(0); MMA8(1, 0, B0); BAR; SCHED;
;     STG_B(0, 1, t + 2);
.Lk_ret_in:
	v_add_u32_e32 v154, 0x10000, v133
	ds_read_b128 v[142:145], v154
	ds_read_b128 v[146:149], v154 offset:1024
	ds_read_b128 v[150:153], v154 offset:2048
	ds_read_b128 v[154:157], v154 offset:3072
	ds_read_b128 v[158:161], v130
	ds_read_b128 v[164:167], v130 offset:1024
	ds_read_b128 v[168:171], v130 offset:2048
	ds_read_b128 v[172:175], v130 offset:3072
	ds_read_b128 v[180:183], v130 offset:4096
	ds_read_b128 v[184:187], v130 offset:5120
	ds_read_b128 v[188:191], v130 offset:6144
	ds_read_b128 v[192:195], v130 offset:7168
	v_add_u32_e32 v208, 0x14000, v133
	ds_read_b128 v[196:199], v208
	ds_read_b128 v[200:203], v208 offset:1024
	ds_read_b128 v[204:207], v208 offset:2048
	ds_read_b128 v[208:211], v208 offset:3072
	s_add_u32 s24, s18, s6
	s_addc_u32 s25, s19, s7
	s_add_u32 s24, s24, 0x80
	s_addc_u32 s25, s25, 0
	s_add_i32 s23, s15, 0xc000
	s_mov_b32 m0, s23
	s_nop 0
	global_load_lds_dwordx4 v132, s[24:25]
	s_add_i32 s23, s15, 0xe000
	s_mov_b32 m0, s23
	s_nop 0
	global_load_lds_dwordx4 v131, s[24:25]
	s_waitcnt vmcnt(8) lgkmcnt(0)
	s_barrier
	s_setprio 1
	v_mfma_f32_16x16x32_bf16 v[126:129], v[158:161], v[142:145], v[126:129]
	v_mfma_f32_16x16x32_bf16 v[122:125], v[158:161], v[150:153], v[122:125]
	v_mfma_f32_16x16x32_bf16 v[118:121], v[168:171], v[142:145], v[118:121]
	v_mfma_f32_16x16x32_bf16 v[114:117], v[168:171], v[150:153], v[114:117]
	v_mfma_f32_16x16x32_bf16 v[110:113], v[180:183], v[142:145], v[110:113]
	v_mfma_f32_16x16x32_bf16 v[106:109], v[180:183], v[150:153], v[106:109]
	v_mfma_f32_16x16x32_bf16 v[102:105], v[188:191], v[142:145], v[102:105]
	v_mfma_f32_16x16x32_bf16 v[98:101], v[188:191], v[150:153], v[98:101]
	v_mfma_f32_16x16x32_bf16 v[126:129], v[164:167], v[146:149], v[126:129]
	v_mfma_f32_16x16x32_bf16 v[122:125], v[164:167], v[154:157], v[122:125]
	v_mfma_f32_16x16x32_bf16 v[118:121], v[172:175], v[146:149], v[118:121]
	v_mfma_f32_16x16x32_bf16 v[114:117], v[172:175], v[154:157], v[114:117]
	v_mfma_f32_16x16x32_bf16 v[110:113], v[184:187], v[146:149], v[110:113]
	v_mfma_f32_16x16x32_bf16 v[106:109], v[184:187], v[154:157], v[106:109]
	v_mfma_f32_16x16x32_bf16 v[102:105], v[192:195], v[146:149], v[102:105]
	v_mfma_f32_16x16x32_bf16 v[98:101], v[192:195], v[154:157], v[98:101]
	v_mfma_f32_16x16x32_bf16 v[94:97], v[158:161], v[196:199], v[94:97]
	v_mfma_f32_16x16x32_bf16 v[90:93], v[158:161], v[204:207], v[90:93]
	v_mfma_f32_16x16x32_bf16 v[86:89], v[168:171], v[196:199], v[86:89]
	v_mfma_f32_16x16x32_bf16 v[82:85], v[168:171], v[204:207], v[82:85]
	v_mfma_f32_16x16x32_bf16 v[78:81], v[180:183], v[196:199], v[78:81]
	v_mfma_f32_16x16x32_bf16 v[74:77], v[180:183], v[204:207], v[74:77]
	v_mfma_f32_16x16x32_bf16 v[70:73], v[188:191], v[196:199], v[70:73]
	v_mfma_f32_16x16x32_bf16 v[66:69], v[188:191], v[204:207], v[66:69]
	v_mfma_f32_16x16x32_bf16 v[94:97], v[164:167], v[200:203], v[94:97]
	v_mfma_f32_16x16x32_bf16 v[90:93], v[164:167], v[208:211], v[90:93]
	v_mfma_f32_16x16x32_bf16 v[86:89], v[172:175], v[200:203], v[86:89]
	v_mfma_f32_16x16x32_bf16 v[82:85], v[172:175], v[208:211], v[82:85]
	v_mfma_f32_16x16x32_bf16 v[78:81], v[184:187], v[200:203], v[78:81]
	v_mfma_f32_16x16x32_bf16 v[74:77], v[184:187], v[208:211], v[74:77]
	v_mfma_f32_16x16x32_bf16 v[70:73], v[192:195], v[200:203], v[70:73]
	v_mfma_f32_16x16x32_bf16 v[66:69], v[192:195], v[208:211], v[66:69]
	s_setprio 0
	s_barrier
	ds_read_b128 v[158:161], v130 offset:16384
	ds_read_b128 v[164:167], v130 offset:17408
	ds_read_b128 v[168:171], v130 offset:18432
	ds_read_b128 v[172:175], v130 offset:19456
	ds_read_b128 v[180:183], v130 offset:20480
	ds_read_b128 v[184:187], v130 offset:21504
	ds_read_b128 v[188:191], v130 offset:22528
	ds_read_b128 v[192:195], v130 offset:23552
	s_add_u32 s24, s3, s6
	s_addc_u32 s25, s10, s7
	s_add_u32 s24, s24, 0x100
	s_addc_u32 s25, s25, 0
	s_add_i32 s23, s15, 0x10000
	s_mov_b32 m0, s23
	s_nop 0
	global_load_lds_dwordx4 v132, s[24:25]
	s_add_i32 s23, s15, 0x12000
	s_mov_b32 m0, s23
	s_nop 0
	global_load_lds_dwordx4 v131, s[24:25]
	s_add_u32 s24, s8, s6
	s_addc_u32 s25, s9, s7
	s_add_u32 s24, s24, 0x100
	s_addc_u32 s25, s25, 0
	s_mov_b32 m0, s15
	s_nop 0
	global_load_lds_dwordx4 v132, s[24:25]
	s_add_i32 s23, s15, 0x2000
	s_mov_b32 m0, s23
	s_nop 0
	global_load_lds_dwordx4 v131, s[24:25]
	s_add_u32 s24, s13, s6
	s_addc_u32 s25, s14, s7
	s_add_u32 s24, s24, 0x100
	s_addc_u32 s25, s25, 0
	s_add_i32 s23, s15, 0x14000
	s_mov_b32 m0, s23
	s_nop 0
	global_load_lds_dwordx4 v132, s[24:25]
	s_add_i32 s23, s15, 0x16000
	s_mov_b32 m0, s23
	s_nop 0
	global_load_lds_dwordx4 v131, s[24:25]
	s_waitcnt vmcnt(8) lgkmcnt(0)
	s_barrier
; #define WAIT_V(n) asm volatile("s_waitcnt vmcnt(" #n ")" ::: "memory")
; #define WAIT_L(n) asm volatile("s_waitcnt lgkmcnt(" #n ")" ::: "memory")
; #define BAR __builtin_amdgcn_s_barrier()
; #define SCHED __builtin_amdgcn_sched_barrier(0)
; #define STG_A(b, h, kt) stage_half_s(lds0 + ((b) * 2 + (h)) * HT_B, ((h) ? A1 : Ap) + (kt) * BK, off0, off1)
; #define STG_B(b, h, kt) stage_half_s(lds0 + (4 + (b) * 2 + (h)) * HT_B, ((h) ? B1p : Bp) + (kt) * BK, off0, off1)
; #define STG_A(b, h, kt) stage_half_s(lds0 + ((b) * 2 + (h)) * HT_B, ((h) ? A1 : Ap) + (kt) * BK, off0, off1)
; #define STG_B(b, h, kt) stage_half_s(lds0 + (4 + (b) * 2 + (h)) * HT_B, ((h) ? B1p : Bp) + (kt) * BK, off0, off1)
; #define LDA8(b, h) _Pragma("unroll") for (int m = 0; m < 4; ++m) _Pragma("unroll") for (int k = 0; k < 2; ++k) \
;     At[m][k] = *(const bf16x8*)(SA_(shm, b, h) + abase + (m * 2 + k) * 1024)
; #define LDB8(dst, b, h) _Pragma("unroll") for (int n = 0; n < 2; ++n) _Pragma("unroll") for (int k = 0; k < 2; ++k) \
;     dst[n][k] = *(const bf16x8*)(SB_(shm, b, h) + bbase + (n * 2 + k) * 1024)
; #define MMA8(ai, bj, Bx) do { __builtin_amdgcn_s_setprio(1); \
;     _Pragma("unroll") for (int m = 0; m < 4; ++m) _Pragma("unroll") for (int n = 0; n < 2; ++n) _Pragma("unroll") for (int k = 0; k < 2; ++k) \
;       acc[ai][bj][m][n] = __builtin_amdgcn_mfma_f32_16x16x32_bf16(At[m][k], Bx[n][k], acc[ai][bj][m][n], 0, 0, 0); \
;     __builtin_amdgcn_s_setprio(0); } while (0)
; template <bool HS>
; __device__ __forceinline__ void gemm_tile8(const u16* __restrict__ Ap, const u16* __restrict__ Bp, int K,
;                                            f32x4 (&acc)[2][2][4][2], char* shm, const int tid, const float* hsr = nullptr) {
;     ...
;     BAR; WAIT_L(0); MMA8(1, 0, B0); BAR; SCHED;
;     STG_B(0, 1, t + 2);
;     WAIT_V(6); BAR; MMA8(1, 1, B1); BAR;
;     LDB8(B0, 1, 0); SCHED; LDA8(1, 0); STG_A(0, 1, t + 2);
;     WAIT_L(8); BAR; WAIT_L(0); MMA8(0, 0, B0); BAR; SCHED;
;     LDB8(B1, 1, 1); STG_B(1, 0, t + 3);
;     BAR; WAIT_L(0); MMA8(0, 1, B1); BAR;
	s_setprio 1
	v_mfma_f32_16x16x32_bf16 v[62:65], v[158:161], v[142:145], v[62:65]
	v_mfma_f32_16x16x32_bf16 v[58:61], v[158:161], v[150:153], v[58:61]
	v_mfma_f32_16x16x32_bf16 v[54:57], v[168:171], v[142:145], v[54:57]
	v_mfma_f32_16x16x32_bf16 v[50:53], v[168:171], v[150:153], v[50:53]
	v_mfma_f32_16x16x32_bf16 v[46:49], v[180:183], v[142:145], v[46:49]
	v_mfma_f32_16x16x32_bf16 v[42:45], v[180:183], v[150:153], v[42:45]
	v_mfma_f32_16x16x32_bf16 v[38:41], v[188:191], v[142:145], v[38:41]
	v_mfma_f32_16x16x32_bf16 v[34:37], v[188:191], v[150:153], v[34:37]
	v_mfma_f32_16x16x32_bf16 v[62:65], v[164:167], v[146:149], v[62:65]
	v_mfma_f32_16x16x32_bf16 v[58:61], v[164:167], v[154:157], v[58:61]
	v_mfma_f32_16x16x32_bf16 v[54:57], v[172:175], v[146:149], v[54:57]
	v_mfma_f32_16x16x32_bf16 v[50:53], v[172:175], v[154:157], v[50:53]
	v_mfma_f32_16x16x32_bf16 v[46:49], v[184:187], v[146:149], v[46:49]
	v_mfma_f32_16x16x32_bf16 v[42:45], v[184:187], v[154:157], v[42:45]
	v_mfma_f32_16x16x32_bf16 v[38:41], v[192:195], v[146:149], v[38:41]
	v_mfma_f32_16x16x32_bf16 v[34:37], v[192:195], v[154:157], v[34:37]
	v_mfma_f32_16x16x32_bf16 v[30:33], v[158:161], v[196:199], v[30:33]
	v_mfma_f32_16x16x32_bf16 v[26:29], v[158:161], v[204:207], v[26:29]
	v_mfma_f32_16x16x32_bf16 v[22:25], v[168:171], v[196:199], v[22:25]
	v_mfma_f32_16x16x32_bf16 v[18:21], v[168:171], v[204:207], v[18:21]
	v_mfma_f32_16x16x32_bf16 v[14:17], v[180:183], v[196:199], v[14:17]
	v_mfma_f32_16x16x32_bf16 v[10:13], v[180:183], v[204:207], v[10:13]
	v_mfma_f32_16x16x32_bf16 v[6:9], v[188:191], v[196:199], v[6:9]
	v_mfma_f32_16x16x32_bf16 v[2:5], v[188:191], v[204:207], v[2:5]
	v_mfma_f32_16x16x32_bf16 v[30:33], v[164:167], v[200:203], v[30:33]
	v_mfma_f32_16x16x32_bf16 v[26:29], v[164:167], v[208:211], v[26:29]
	v_mfma_f32_16x16x32_bf16 v[22:25], v[172:175], v[200:203], v[22:25]
	v_mfma_f32_16x16x32_bf16 v[18:21], v[172:175], v[208:211], v[18:21]
	v_mfma_f32_16x16x32_bf16 v[14:17], v[184:187], v[200:203], v[14:17]
	v_mfma_f32_16x16x32_bf16 v[10:13], v[184:187], v[208:211], v[10:13]
	v_mfma_f32_16x16x32_bf16 v[6:9], v[192:195], v[200:203], v[6:9]
	v_mfma_f32_16x16x32_bf16 v[2:5], v[192:195], v[208:211], v[2:5]
	s_setprio 0
	s_barrier
	v_add_u32_e32 v154, 0x18000, v133
	ds_read_b128 v[142:145], v154
	ds_read_b128 v[146:149], v154 offset:1024
	ds_read_b128 v[150:153], v154 offset:2048
	ds_read_b128 v[154:157], v154 offset:3072
	ds_read_b128 v[158:161], v130 offset:32768
	ds_read_b128 v[164:167], v130 offset:33792
	ds_read_b128 v[168:171], v130 offset:34816
	ds_read_b128 v[172:175], v130 offset:35840
	ds_read_b128 v[180:183], v130 offset:36864
	ds_read_b128 v[184:187], v130 offset:37888
	ds_read_b128 v[188:191], v130 offset:38912
	ds_read_b128 v[192:195], v130 offset:39936
	v_add_u32_e32 v208, 0x1c000, v133
	ds_read_b128 v[196:199], v208
	ds_read_b128 v[200:203], v208 offset:1024
	ds_read_b128 v[204:207], v208 offset:2048
	ds_read_b128 v[208:211], v208 offset:3072
	s_add_u32 s24, s18, s6
	s_addc_u32 s25, s19, s7
	s_add_u32 s24, s24, 0x100
	s_addc_u32 s25, s25, 0
	s_add_i32 s23, s15, 0x4000
	s_mov_b32 m0, s23
	s_nop 0
	global_load_lds_dwordx4 v132, s[24:25]
	s_add_i32 s23, s15, 0x6000
	s_mov_b32 m0, s23
	s_nop 0
	global_load_lds_dwordx4 v131, s[24:25]
	s_waitcnt vmcnt(8) lgkmcnt(0)
	s_barrier
	s_setprio 1
	v_mfma_f32_16x16x32_bf16 v[126:129], v[158:161], v[142:145], v[126:129]
	v_mfma_f32_16x16x32_bf16 v[122:125], v[158:161], v[150:153], v[122:125]
	v_mfma_f32_16x16x32_bf16 v[118:121], v[168:171], v[142:145], v[118:121]
	v_mfma_f32_16x16x32_bf16 v[114:117], v[168:171], v[150:153], v[114:117]
	v_mfma_f32_16x16x32_bf16 v[110:113], v[180:183], v[142:145], v[110:113]
	v_mfma_f32_16x16x32_bf16 v[106:109], v[180:183], v[150:153], v[106:109]
	v_mfma_f32_16x16x32_bf16 v[102:105], v[188:191], v[142:145], v[102:105]
	v_mfma_f32_16x16x32_bf16 v[98:101], v[188:191], v[150:153], v[98:101]
	v_mfma_f32_16x16x32_bf16 v[126:129], v[164:167], v[146:149], v[126:129]
	v_mfma_f32_16x16x32_bf16 v[122:125], v[164:167], v[154:157], v[122:125]
	v_mfma_f32_16x16x32_bf16 v[118:121], v[172:175], v[146:149], v[118:121]
	v_mfma_f32_16x16x32_bf16 v[114:117], v[172:175], v[154:157], v[114:117]
	v_mfma_f32_16x16x32_bf16 v[110:113], v[184:187], v[146:149], v[110:113]
	v_mfma_f32_16x16x32_bf16 v[106:109], v[184:187], v[154:157], v[106:109]
	v_mfma_f32_16x16x32_bf16 v[102:105], v[192:195], v[146:149], v[102:105]
	v_mfma_f32_16x16x32_bf16 v[98:101], v[192:195], v[154:157], v[98:101]
	v_mfma_f32_16x16x32_bf16 v[94:97], v[158:161], v[196:199], v[94:97]
	v_mfma_f32_16x16x32_bf16 v[90:93], v[158:161], v[204:207], v[90:93]
	v_mfma_f32_16x16x32_bf16 v[86:89], v[168:171], v[196:199], v[86:89]
	v_mfma_f32_16x16x32_bf16 v[82:85], v[168:171], v[204:207], v[82:85]
	v_mfma_f32_16x16x32_bf16 v[78:81], v[180:183], v[196:199], v[78:81]
	v_mfma_f32_16x16x32_bf16 v[74:77], v[180:183], v[204:207], v[74:77]
	v_mfma_f32_16x16x32_bf16 v[70:73], v[188:191], v[196:199], v[70:73]
	v_mfma_f32_16x16x32_bf16 v[66:69], v[188:191], v[204:207], v[66:69]
	v_mfma_f32_16x16x32_bf16 v[94:97], v[164:167], v[200:203], v[94:97]
	v_mfma_f32_16x16x32_bf16 v[90:93], v[164:167], v[208:211], v[90:93]
	v_mfma_f32_16x16x32_bf16 v[86:89], v[172:175], v[200:203], v[86:89]
	v_mfma_f32_16x16x32_bf16 v[82:85], v[172:175], v[208:211], v[82:85]
	v_mfma_f32_16x16x32_bf16 v[78:81], v[184:187], v[200:203], v[78:81]
	v_mfma_f32_16x16x32_bf16 v[74:77], v[184:187], v[208:211], v[74:77]
	v_mfma_f32_16x16x32_bf16 v[70:73], v[192:195], v[200:203], v[70:73]
	v_mfma_f32_16x16x32_bf16 v[66:69], v[192:195], v[208:211], v[66:69]
	s_setprio 0
	s_barrier
; #define WAIT_V(n) asm volatile("s_waitcnt vmcnt(" #n ")" ::: "memory")
; #define WAIT_L(n) asm volatile("s_waitcnt lgkmcnt(" #n ")" ::: "memory")
; #define BAR __builtin_amdgcn_s_barrier()
; #define SCHED __builtin_amdgcn_sched_barrier(0)
; #define STG_A(b, h, kt) stage_half_s(lds0 + ((b) * 2 + (h)) * HT_B, ((h) ? A1 : Ap) + (kt) * BK, off0, off1)
; #define STG_B(b, h, kt) stage_half_s(lds0 + (4 + (b) * 2 + (h)) * HT_B, ((h) ? B1p : Bp) + (kt) * BK, off0, off1)
; #define STG_A(b, h, kt) stage_half_s(lds0 + ((b) * 2 + (h)) * HT_B, ((h) ? A1 : Ap) + (kt) * BK, off0, off1)
; #define STG_B(b, h, kt) stage_half_s(lds0 + (4 + (b) * 2 + (h)) * HT_B, ((h) ? B1p : Bp) + (kt) * BK, off0, off1)
; #define LDA8(b, h) _Pragma("unroll") for (int m = 0; m < 4; ++m) _Pragma("unroll") for (int k = 0; k < 2; ++k) \
;     At[m][k] = *(const bf16x8*)(SA_(shm, b, h) + abase + (m * 2 + k) * 1024)
; #define LDB8(dst, b, h) _Pragma("unroll") for (int n = 0; n < 2; ++n) _Pragma("unroll") for (int k = 0; k < 2; ++k) \
;     dst[n][k] = *(const bf16x8*)(SB_(shm, b, h) + bbase + (n * 2 + k) * 1024)
; #define MMA8(ai, bj, Bx) do { __builtin_amdgcn_s_setprio(1); \
;     _Pragma("unroll") for (int m = 0; m < 4; ++m) _Pragma("unroll") for (int n = 0; n < 2; ++n) _Pragma("unroll") for (int k = 0; k < 2; ++k) \
;       acc[ai][bj][m][n] = __builtin_amdgcn_mfma_f32_16x16x32_bf16(At[m][k], Bx[n][k], acc[ai][bj][m][n], 0, 0, 0); \
;     __builtin_amdgcn_s_setprio(0); } while (0)
; template <bool HS>
; __device__ __forceinline__ void gemm_tile8(const u16* __restrict__ Ap, const u16* __restrict__ Bp, int K,
;                                            f32x4 (&acc)[2][2][4][2], char* shm, const int tid, const float* hsr = nullptr) {
;     ...
;     LDA8(1, 1); STG_A(1, 0, t + 3);
;     BAR; WAIT_L(0); MMA8(1, 0, B0); BAR; SCHED;
;     STG_B(1, 1, t + 3);
;     WAIT_V(6); BAR; MMA8(1, 1, B1); BAR;
;   }
;   { LDB8(B0, 0, 0); LDA8(0, 0); STG_A(1, 1, nt - 1);
;     BAR; WAIT_L(0); MMA8(0, 0, B0); BAR;
	ds_read_b128 v[158:161], v130 offset:49152
	ds_read_b128 v[164:167], v130 offset:50176
	ds_read_b128 v[168:171], v130 offset:51200
	ds_read_b128 v[172:175], v130 offset:52224
	ds_read_b128 v[180:183], v130 offset:53248
	ds_read_b128 v[184:187], v130 offset:54272
	ds_read_b128 v[188:191], v130 offset:55296
	ds_read_b128 v[192:195], v130 offset:56320
	s_add_u32 s24, s3, s6
	s_addc_u32 s25, s10, s7
	s_add_u32 s24, s24, 0x180
	s_addc_u32 s25, s25, 0
	s_add_i32 s23, s15, 0x18000
	s_mov_b32 m0, s23
	s_nop 0
	global_load_lds_dwordx4 v132, s[24:25]
	s_add_i32 s23, s15, 0x1a000
	s_mov_b32 m0, s23
	s_nop 0
	global_load_lds_dwordx4 v131, s[24:25]
	s_add_u32 s24, s8, s6
	s_addc_u32 s25, s9, s7
	s_add_u32 s24, s24, 0x180
	s_addc_u32 s25, s25, 0
	s_add_i32 s23, s15, 0x8000
	s_mov_b32 m0, s23
	s_nop 0
	global_load_lds_dwordx4 v132, s[24:25]
	s_add_i32 s23, s15, 0xa000
	s_mov_b32 m0, s23
	s_nop 0
	global_load_lds_dwordx4 v131, s[24:25]
	s_add_u32 s24, s13, s6
	s_addc_u32 s25, s14, s7
	s_add_u32 s24, s24, 0x180
	s_addc_u32 s25, s25, 0
	s_add_i32 s23, s15, 0x1c000
	s_mov_b32 m0, s23
	s_nop 0
	global_load_lds_dwordx4 v132, s[24:25]
	s_add_i32 s23, s15, 0x1e000
	s_mov_b32 m0, s23
	s_nop 0
	global_load_lds_dwordx4 v131, s[24:25]
	s_waitcnt vmcnt(8) lgkmcnt(0)
	s_barrier
	s_setprio 1
	v_mfma_f32_16x16x32_bf16 v[62:65], v[158:161], v[142:145], v[62:65]
	v_mfma_f32_16x16x32_bf16 v[58:61], v[158:161], v[150:153], v[58:61]
	v_mfma_f32_16x16x32_bf16 v[54:57], v[168:171], v[142:145], v[54:57]
	v_mfma_f32_16x16x32_bf16 v[50:53], v[168:171], v[150:153], v[50:53]
	v_mfma_f32_16x16x32_bf16 v[46:49], v[180:183], v[142:145], v[46:49]
	v_mfma_f32_16x16x32_bf16 v[42:45], v[180:183], v[150:153], v[42:45]
	v_mfma_f32_16x16x32_bf16 v[38:41], v[188:191], v[142:145], v[38:41]
	v_mfma_f32_16x16x32_bf16 v[34:37], v[188:191], v[150:153], v[34:37]
	v_mfma_f32_16x16x32_bf16 v[62:65], v[164:167], v[146:149], v[62:65]
	v_mfma_f32_16x16x32_bf16 v[58:61], v[164:167], v[154:157], v[58:61]
	v_mfma_f32_16x16x32_bf16 v[54:57], v[172:175], v[146:149], v[54:57]
	v_mfma_f32_16x16x32_bf16 v[50:53], v[172:175], v[154:157], v[50:53]
	v_mfma_f32_16x16x32_bf16 v[46:49], v[184:187], v[146:149], v[46:49]
	v_mfma_f32_16x16x32_bf16 v[42:45], v[184:187], v[154:157], v[42:45]
	v_mfma_f32_16x16x32_bf16 v[38:41], v[192:195], v[146:149], v[38:41]
	v_mfma_f32_16x16x32_bf16 v[34:37], v[192:195], v[154:157], v[34:37]
	v_mfma_f32_16x16x32_bf16 v[30:33], v[158:161], v[196:199], v[30:33]
	v_mfma_f32_16x16x32_bf16 v[26:29], v[158:161], v[204:207], v[26:29]
	v_mfma_f32_16x16x32_bf16 v[22:25], v[168:171], v[196:199], v[22:25]
	v_mfma_f32_16x16x32_bf16 v[18:21], v[168:171], v[204:207], v[18:21]
	v_mfma_f32_16x16x32_bf16 v[14:17], v[180:183], v[196:199], v[14:17]
	v_mfma_f32_16x16x32_bf16 v[10:13], v[180:183], v[204:207], v[10:13]
	v_mfma_f32_16x16x32_bf16 v[6:9], v[188:191], v[196:199], v[6:9]
	v_mfma_f32_16x16x32_bf16 v[2:5], v[188:191], v[204:207], v[2:5]
	v_mfma_f32_16x16x32_bf16 v[30:33], v[164:167], v[200:203], v[30:33]
	v_mfma_f32_16x16x32_bf16 v[26:29], v[164:167], v[208:211], v[26:29]
	v_mfma_f32_16x16x32_bf16 v[22:25], v[172:175], v[200:203], v[22:25]
	v_mfma_f32_16x16x32_bf16 v[18:21], v[172:175], v[208:211], v[18:21]
	v_mfma_f32_16x16x32_bf16 v[14:17], v[184:187], v[200:203], v[14:17]
	v_mfma_f32_16x16x32_bf16 v[10:13], v[184:187], v[208:211], v[10:13]
	v_mfma_f32_16x16x32_bf16 v[6:9], v[192:195], v[200:203], v[6:9]
	v_mfma_f32_16x16x32_bf16 v[2:5], v[192:195], v[208:211], v[2:5]
	s_setprio 0
	s_add_i32 s20, s20, 2
	s_add_u32 s6, s6, 0x100
	s_addc_u32 s7, s7, 0
	s_cmp_lt_u32 s20, 12
	s_barrier
	s_cbranch_scc1 .Lk_ret_in
	s_waitcnt vmcnt(6)
	s_add_i32 s21, s15, 0xc000
	s_add_i32 s22, s15, 0xe000
	s_mov_b32 s89, 0x10000
	v_add_u32_e32 v133, 0, v133
	v_add_u32_e32 v135, 0x10000, v133
	ds_read_b128 v[142:145], v135
	ds_read_b128 v[146:149], v135 offset:1024
	ds_read_b128 v[150:153], v135 offset:2048
	ds_read_b128 v[154:157], v135 offset:3072
	ds_read_b128 v[158:161], v130
	ds_read_b128 v[164:167], v130 offset:1024
	ds_read_b128 v[168:171], v130 offset:2048
	ds_read_b128 v[172:175], v130 offset:3072
	ds_read_b128 v[180:183], v130 offset:4096
	ds_read_b128 v[184:187], v130 offset:5120
	ds_read_b128 v[188:191], v130 offset:6144
	ds_read_b128 v[192:195], v130 offset:7168
	s_add_u32 s6, s8, 0x40780
	s_addc_u32 s7, s9, 0
	s_mov_b32 m0, s21
	s_nop 0
	global_load_lds_dwordx4 v132, s[6:7]
	s_nop 0
	s_mov_b32 m0, s22
	s_nop 0
	global_load_lds_dwordx4 v131, s[6:7]
	s_barrier
	s_waitcnt lgkmcnt(0)
	s_setprio 1
	s_waitcnt lgkmcnt(7)
	v_mfma_f32_16x16x32_bf16 v[126:129], v[158:161], v[142:145], v[126:129]
	s_waitcnt lgkmcnt(5)
	v_mfma_f32_16x16x32_bf16 v[118:121], v[168:171], v[142:145], v[118:121]
	v_mfma_f32_16x16x32_bf16 v[114:117], v[168:171], v[150:153], v[114:117]
	s_waitcnt lgkmcnt(1)
	v_mfma_f32_16x16x32_bf16 v[102:105], v[188:191], v[142:145], v[102:105]
	v_mfma_f32_16x16x32_bf16 v[98:101], v[188:191], v[150:153], v[98:101]
	v_mfma_f32_16x16x32_bf16 v[126:129], v[164:167], v[146:149], v[126:129]
	v_mfma_f32_16x16x32_bf16 v[122:125], v[158:161], v[150:153], v[122:125]
	v_mfma_f32_16x16x32_bf16 v[118:121], v[172:175], v[146:149], v[118:121]
	v_mfma_f32_16x16x32_bf16 v[114:117], v[172:175], v[154:157], v[114:117]
	v_mfma_f32_16x16x32_bf16 v[110:113], v[180:183], v[142:145], v[110:113]
	v_mfma_f32_16x16x32_bf16 v[106:109], v[180:183], v[150:153], v[106:109]
	s_waitcnt lgkmcnt(0)
	v_mfma_f32_16x16x32_bf16 v[102:105], v[192:195], v[146:149], v[102:105]
	v_mfma_f32_16x16x32_bf16 v[98:101], v[192:195], v[154:157], v[98:101]
	v_mfma_f32_16x16x32_bf16 v[196:199], v[164:167], v[154:157], v[122:125]
	v_mfma_f32_16x16x32_bf16 v[200:203], v[184:187], v[146:149], v[110:113]
	v_mfma_f32_16x16x32_bf16 v[204:207], v[184:187], v[154:157], v[106:109]
	s_setprio 0
	v_add_u32_e32 v131, 0x14000, v133
	s_barrier
; #define WAIT_V(n) asm volatile("s_waitcnt vmcnt(" #n ")" ::: "memory")
; #define WAIT_L(n) asm volatile("s_waitcnt lgkmcnt(" #n ")" ::: "memory")
; #define BAR __builtin_amdgcn_s_barrier()
; #define LDA8(b, h) _Pragma("unroll") for (int m = 0; m < 4; ++m) _Pragma("unroll") for (int k = 0; k < 2; ++k) \
;     At[m][k] = *(const bf16x8*)(SA_(shm, b, h) + abase + (m * 2 + k) * 1024)
; #define LDB8(dst, b, h) _Pragma("unroll") for (int n = 0; n < 2; ++n) _Pragma("unroll") for (int k = 0; k < 2; ++k) \
;     dst[n][k] = *(const bf16x8*)(SB_(shm, b, h) + bbase + (n * 2 + k) * 1024)
; #define MMA8(ai, bj, Bx) do { __builtin_amdgcn_s_setprio(1); \
;     _Pragma("unroll") for (int m = 0; m < 4; ++m) _Pragma("unroll") for (int n = 0; n < 2; ++n) _Pragma("unroll") for (int k = 0; k < 2; ++k) \
;       acc[ai][bj][m][n] = __builtin_amdgcn_mfma_f32_16x16x32_bf16(At[m][k], Bx[n][k], acc[ai][bj][m][n], 0, 0, 0); \
;     __builtin_amdgcn_s_setprio(0); } while (0)
; template <bool HS>
; __device__ __forceinline__ void gemm_tile8(const u16* __restrict__ Ap, const u16* __restrict__ Bp, int K,
;                                            f32x4 (&acc)[2][2][4][2], char* shm, const int tid, const float* hsr = nullptr) {
;     ...
;     BAR; WAIT_L(0); MMA8(0, 0, B0); BAR;
;     LDB8(B1, 0, 1); BAR; WAIT_L(0); MMA8(0, 1, B1); BAR;
;     LDA8(0, 1); WAIT_V(4); BAR; WAIT_L(0); MMA8(1, 0, B0); MMA8(1, 1, B1); BAR; }
;   { LDB8(B0, 1, 0); LDA8(1, 0); WAIT_V(2); BAR; WAIT_L(0); MMA8(0, 0, B0); BAR;
	ds_read_b128 v[106:109], v131
	ds_read_b128 v[110:113], v131 offset:1024
	ds_read_b128 v[122:125], v131 offset:2048
	ds_read_b128 v[208:211], v131 offset:3072
	s_barrier
	s_waitcnt lgkmcnt(0)
	s_setprio 1
	s_waitcnt lgkmcnt(3)
	v_mfma_f32_16x16x32_bf16 v[86:89], v[168:171], v[106:109], v[86:89]
	s_waitcnt lgkmcnt(1)
	v_mfma_f32_16x16x32_bf16 v[82:85], v[168:171], v[122:125], v[82:85]
	v_mfma_f32_16x16x32_bf16 v[70:73], v[188:191], v[106:109], v[70:73]
	v_mfma_f32_16x16x32_bf16 v[94:97], v[158:161], v[106:109], v[94:97]
	v_mfma_f32_16x16x32_bf16 v[90:93], v[158:161], v[122:125], v[90:93]
	v_mfma_f32_16x16x32_bf16 v[86:89], v[172:175], v[110:113], v[86:89]
	s_waitcnt lgkmcnt(0)
	v_mfma_f32_16x16x32_bf16 v[82:85], v[172:175], v[208:211], v[82:85]
	v_mfma_f32_16x16x32_bf16 v[78:81], v[180:183], v[106:109], v[78:81]
	v_mfma_f32_16x16x32_bf16 v[74:77], v[180:183], v[122:125], v[74:77]
	v_mfma_f32_16x16x32_bf16 v[70:73], v[192:195], v[110:113], v[70:73]
	v_mfma_f32_16x16x32_bf16 v[66:69], v[188:191], v[122:125], v[66:69]
	v_mfma_f32_16x16x32_bf16 v[212:215], v[164:167], v[110:113], v[94:97]
	v_mfma_f32_16x16x32_bf16 v[158:161], v[164:167], v[208:211], v[90:93]
	v_mfma_f32_16x16x32_bf16 v[164:167], v[184:187], v[110:113], v[78:81]
	v_mfma_f32_16x16x32_bf16 v[168:171], v[184:187], v[208:211], v[74:77]
	v_mfma_f32_16x16x32_bf16 v[172:175], v[192:195], v[208:211], v[66:69]
	s_setprio 0
	s_barrier
	s_nop 0
	ds_read_b128 v[66:69], v130 offset:16384
	ds_read_b128 v[74:77], v130 offset:17408
	ds_read_b128 v[78:81], v130 offset:18432
	ds_read_b128 v[90:93], v130 offset:19456
	ds_read_b128 v[94:97], v130 offset:20480
	ds_read_b128 v[180:183], v130 offset:21504
	ds_read_b128 v[184:187], v130 offset:22528
	ds_read_b128 v[188:191], v130 offset:23552
	s_waitcnt vmcnt(4)
	s_barrier
	s_waitcnt lgkmcnt(0)
	s_setprio 1
	s_waitcnt lgkmcnt(7)
	v_mfma_f32_16x16x32_bf16 v[62:65], v[66:69], v[142:145], v[62:65]
	s_waitcnt lgkmcnt(5)
	v_mfma_f32_16x16x32_bf16 v[54:57], v[78:81], v[142:145], v[54:57]
	v_mfma_f32_16x16x32_bf16 v[50:53], v[78:81], v[150:153], v[50:53]
	s_waitcnt lgkmcnt(1)
	v_mfma_f32_16x16x32_bf16 v[38:41], v[184:187], v[142:145], v[38:41]
	v_mfma_f32_16x16x32_bf16 v[34:37], v[184:187], v[150:153], v[34:37]
	v_mfma_f32_16x16x32_bf16 v[62:65], v[74:77], v[146:149], v[62:65]
	v_mfma_f32_16x16x32_bf16 v[58:61], v[66:69], v[150:153], v[58:61]
	v_mfma_f32_16x16x32_bf16 v[54:57], v[90:93], v[146:149], v[54:57]
	v_mfma_f32_16x16x32_bf16 v[50:53], v[90:93], v[154:157], v[50:53]
	v_mfma_f32_16x16x32_bf16 v[46:49], v[94:97], v[142:145], v[46:49]
	v_mfma_f32_16x16x32_bf16 v[42:45], v[94:97], v[150:153], v[42:45]
	s_waitcnt lgkmcnt(0)
	v_mfma_f32_16x16x32_bf16 v[38:41], v[188:191], v[146:149], v[38:41]
	v_mfma_f32_16x16x32_bf16 v[34:37], v[188:191], v[154:157], v[34:37]
	v_mfma_f32_16x16x32_bf16 v[192:195], v[74:77], v[154:157], v[58:61]
	v_mfma_f32_16x16x32_bf16 v[220:223], v[180:183], v[146:149], v[46:49]
	v_mfma_f32_16x16x32_bf16 v[224:227], v[180:183], v[154:157], v[42:45]
	s_setprio 0
	s_setprio 1
	v_mfma_f32_16x16x32_bf16 v[22:25], v[78:81], v[106:109], v[22:25]
	v_mfma_f32_16x16x32_bf16 v[18:21], v[78:81], v[122:125], v[18:21]
	v_mfma_f32_16x16x32_bf16 v[6:9], v[184:187], v[106:109], v[6:9]
	v_mfma_f32_16x16x32_bf16 v[30:33], v[66:69], v[106:109], v[30:33]
	v_mfma_f32_16x16x32_bf16 v[26:29], v[66:69], v[122:125], v[26:29]
	v_mfma_f32_16x16x32_bf16 v[22:25], v[90:93], v[110:113], v[22:25]
	v_mfma_f32_16x16x32_bf16 v[18:21], v[90:93], v[208:211], v[18:21]
	v_mfma_f32_16x16x32_bf16 v[14:17], v[94:97], v[106:109], v[14:17]
	v_mfma_f32_16x16x32_bf16 v[10:13], v[94:97], v[122:125], v[10:13]
	v_mfma_f32_16x16x32_bf16 v[6:9], v[188:191], v[110:113], v[6:9]
	v_mfma_f32_16x16x32_bf16 v[2:5], v[184:187], v[122:125], v[2:5]
	v_mfma_f32_16x16x32_bf16 v[142:145], v[74:77], v[110:113], v[30:33]
	v_mfma_f32_16x16x32_bf16 v[146:149], v[74:77], v[208:211], v[26:29]
	v_mfma_f32_16x16x32_bf16 v[150:153], v[180:183], v[110:113], v[14:17]
	v_mfma_f32_16x16x32_bf16 v[154:157], v[180:183], v[208:211], v[10:13]
	v_mfma_f32_16x16x32_bf16 v[180:183], v[188:191], v[208:211], v[2:5]
	s_setprio 0
	v_add_u32_e32 v26, 0x18000, v133
	s_barrier
	ds_read_b128 v[2:5], v26
	ds_read_b128 v[10:13], v26 offset:1024
	ds_read_b128 v[14:17], v26 offset:2048
	ds_read_b128 v[184:187], v26 offset:3072
	ds_read_b128 v[26:29], v130 offset:32768
	ds_read_b128 v[30:33], v130 offset:33792
	ds_read_b128 v[42:45], v130 offset:34816
	ds_read_b128 v[46:49], v130 offset:35840
	ds_read_b128 v[58:61], v130 offset:36864
	ds_read_b128 v[66:69], v130 offset:37888
	ds_read_b128 v[188:191], v130 offset:38912
	ds_read_b128 v[208:211], v130 offset:39936
	s_waitcnt vmcnt(2)
	s_barrier
; #define WAIT_V(n) asm volatile("s_waitcnt vmcnt(" #n ")" ::: "memory")
; #define WAIT_L(n) asm volatile("s_waitcnt lgkmcnt(" #n ")" ::: "memory")
; #define BAR __builtin_amdgcn_s_barrier()
; #define LDA8(b, h) _Pragma("unroll") for (int m = 0; m < 4; ++m) _Pragma("unroll") for (int k = 0; k < 2; ++k) \
;     At[m][k] = *(const bf16x8*)(SA_(shm, b, h) + abase + (m * 2 + k) * 1024)
; #define LDB8(dst, b, h) _Pragma("unroll") for (int n = 0; n < 2; ++n) _Pragma("unroll") for (int k = 0; k < 2; ++k) \
;     dst[n][k] = *(const bf16x8*)(SB_(shm, b, h) + bbase + (n * 2 + k) * 1024)
; #define MMA8(ai, bj, Bx) do { __builtin_amdgcn_s_setprio(1); \
;     _Pragma("unroll") for (int m = 0; m < 4; ++m) _Pragma("unroll") for (int n = 0; n < 2; ++n) _Pragma("unroll") for (int k = 0; k < 2; ++k) \
;       acc[ai][bj][m][n] = __builtin_amdgcn_mfma_f32_16x16x32_bf16(At[m][k], Bx[n][k], acc[ai][bj][m][n], 0, 0, 0); \
;     __builtin_amdgcn_s_setprio(0); } while (0)
; template <bool HS>
; __device__ __forceinline__ void gemm_tile8(const u16* __restrict__ Ap, const u16* __restrict__ Bp, int K,
;                                            f32x4 (&acc)[2][2][4][2], char* shm, const int tid, const float* hsr = nullptr) {
;     ...
;   { LDB8(B0, 1, 0); LDA8(1, 0); WAIT_V(2); BAR; WAIT_L(0); MMA8(0, 0, B0); BAR;
;     LDB8(B1, 1, 1); WAIT_V(0); BAR; WAIT_L(0); MMA8(0, 1, B1); BAR;
;     LDA8(1, 1); BAR; WAIT_L(0); MMA8(1, 0, B0); MMA8(1, 1, B1); BAR; }
;   if (wr == 0) BAR;
	s_waitcnt lgkmcnt(0)
	s_setprio 1
	s_waitcnt lgkmcnt(7)
	v_mfma_f32_16x16x32_bf16 v[74:77], v[26:29], v[2:5], v[126:129]
	s_waitcnt lgkmcnt(6)
	v_mfma_f32_16x16x32_bf16 v[122:125], v[30:33], v[10:13], v[74:77]
	v_mfma_f32_16x16x32_bf16 v[74:77], v[26:29], v[14:17], v[196:199]
	v_mfma_f32_16x16x32_bf16 v[126:129], v[30:33], v[184:187], v[74:77]
	s_waitcnt lgkmcnt(5)
	v_mfma_f32_16x16x32_bf16 v[74:77], v[42:45], v[2:5], v[118:121]
	s_waitcnt lgkmcnt(4)
	v_mfma_f32_16x16x32_bf16 v[106:109], v[46:49], v[10:13], v[74:77]
	v_mfma_f32_16x16x32_bf16 v[74:77], v[42:45], v[14:17], v[114:117]
	v_mfma_f32_16x16x32_bf16 v[110:113], v[46:49], v[184:187], v[74:77]
	s_waitcnt lgkmcnt(3)
	v_mfma_f32_16x16x32_bf16 v[74:77], v[58:61], v[2:5], v[200:203]
	s_waitcnt lgkmcnt(2)
	v_mfma_f32_16x16x32_bf16 v[90:93], v[66:69], v[10:13], v[74:77]
	v_mfma_f32_16x16x32_bf16 v[74:77], v[58:61], v[14:17], v[204:207]
	v_mfma_f32_16x16x32_bf16 v[94:97], v[66:69], v[184:187], v[74:77]
	s_waitcnt lgkmcnt(1)
	v_mfma_f32_16x16x32_bf16 v[74:77], v[188:191], v[2:5], v[102:105]
	v_mfma_f32_16x16x32_bf16 v[78:81], v[188:191], v[14:17], v[98:101]
	s_waitcnt lgkmcnt(0)
	v_mfma_f32_16x16x32_bf16 v[74:77], v[208:211], v[10:13], v[74:77]
	v_mfma_f32_16x16x32_bf16 v[78:81], v[208:211], v[184:187], v[78:81]
	s_setprio 0
	v_add_u32_e32 v98, 0x1c000, v133
	s_barrier
	ds_read_b128 v[196:199], v98
	ds_read_b128 v[200:203], v98 offset:1024
	ds_read_b128 v[204:207], v98 offset:2048
	ds_read_b128 v[228:231], v98 offset:3072
	s_waitcnt vmcnt(0)
	s_barrier
	s_waitcnt lgkmcnt(0)
	s_setprio 1
	s_waitcnt lgkmcnt(3)
	v_mfma_f32_16x16x32_bf16 v[98:101], v[26:29], v[196:199], v[212:215]
	s_waitcnt lgkmcnt(1)
	v_mfma_f32_16x16x32_bf16 v[26:29], v[26:29], v[204:207], v[158:161]
	s_waitcnt lgkmcnt(0)
	v_mfma_f32_16x16x32_bf16 v[118:121], v[30:33], v[228:231], v[26:29]
	v_mfma_f32_16x16x32_bf16 v[26:29], v[42:45], v[196:199], v[86:89]
	v_mfma_f32_16x16x32_bf16 v[114:117], v[30:33], v[200:203], v[98:101]
	v_mfma_f32_16x16x32_bf16 v[98:101], v[46:49], v[200:203], v[26:29]
	v_mfma_f32_16x16x32_bf16 v[26:29], v[42:45], v[204:207], v[82:85]
	v_mfma_f32_16x16x32_bf16 v[102:105], v[46:49], v[228:231], v[26:29]
	v_mfma_f32_16x16x32_bf16 v[26:29], v[58:61], v[196:199], v[164:167]
	v_mfma_f32_16x16x32_bf16 v[82:85], v[66:69], v[200:203], v[26:29]
	v_mfma_f32_16x16x32_bf16 v[26:29], v[58:61], v[204:207], v[168:171]
	v_mfma_f32_16x16x32_bf16 v[86:89], v[66:69], v[228:231], v[26:29]
	v_mfma_f32_16x16x32_bf16 v[26:29], v[188:191], v[196:199], v[70:73]
	v_mfma_f32_16x16x32_bf16 v[66:69], v[208:211], v[200:203], v[26:29]
	v_mfma_f32_16x16x32_bf16 v[26:29], v[188:191], v[204:207], v[172:175]
	v_mfma_f32_16x16x32_bf16 v[70:73], v[208:211], v[228:231], v[26:29]
	s_setprio 0
	s_barrier
	ds_read_b128 v[158:161], v130 offset:49152
	ds_read_b128 v[164:167], v130 offset:50176
	ds_read_b128 v[168:171], v130 offset:51200
	ds_read_b128 v[172:175], v130 offset:52224
	ds_read_b128 v[188:191], v130 offset:53248
	ds_read_b128 v[208:211], v130 offset:54272
	ds_read_b128 v[212:215], v130 offset:55296
	ds_read_b128 v[130:133], v130 offset:56320
	s_barrier
	s_waitcnt lgkmcnt(0)
	s_setprio 1
	s_waitcnt lgkmcnt(7)
	v_mfma_f32_16x16x32_bf16 v[26:29], v[158:161], v[2:5], v[62:65]
	s_waitcnt lgkmcnt(6)
	v_mfma_f32_16x16x32_bf16 v[58:61], v[164:167], v[10:13], v[26:29]
	v_mfma_f32_16x16x32_bf16 v[26:29], v[158:161], v[14:17], v[192:195]
	v_mfma_f32_16x16x32_bf16 v[62:65], v[164:167], v[184:187], v[26:29]
	s_waitcnt lgkmcnt(5)
	v_mfma_f32_16x16x32_bf16 v[26:29], v[168:171], v[2:5], v[54:57]
	s_waitcnt lgkmcnt(4)
	v_mfma_f32_16x16x32_bf16 v[42:45], v[172:175], v[10:13], v[26:29]
	v_mfma_f32_16x16x32_bf16 v[26:29], v[168:171], v[14:17], v[50:53]
	v_mfma_f32_16x16x32_bf16 v[46:49], v[172:175], v[184:187], v[26:29]
	s_waitcnt lgkmcnt(3)
	v_mfma_f32_16x16x32_bf16 v[26:29], v[188:191], v[2:5], v[220:223]
	s_waitcnt lgkmcnt(1)
	v_mfma_f32_16x16x32_bf16 v[2:5], v[212:215], v[2:5], v[38:41]
	v_mfma_f32_16x16x32_bf16 v[26:29], v[208:211], v[10:13], v[26:29]
	v_mfma_f32_16x16x32_bf16 v[30:33], v[188:191], v[14:17], v[224:227]
	s_waitcnt lgkmcnt(0)
	v_mfma_f32_16x16x32_bf16 v[10:13], v[130:133], v[10:13], v[2:5]
	v_mfma_f32_16x16x32_bf16 v[2:5], v[212:215], v[14:17], v[34:37]
	v_mfma_f32_16x16x32_bf16 v[30:33], v[208:211], v[184:187], v[30:33]
	v_mfma_f32_16x16x32_bf16 v[14:17], v[130:133], v[184:187], v[2:5]
	s_setprio 0
	s_setprio 1
	v_mfma_f32_16x16x32_bf16 v[2:5], v[158:161], v[196:199], v[142:145]
	v_mfma_f32_16x16x32_bf16 v[50:53], v[164:167], v[200:203], v[2:5]
	v_mfma_f32_16x16x32_bf16 v[2:5], v[158:161], v[204:207], v[146:149]
	v_mfma_f32_16x16x32_bf16 v[54:57], v[164:167], v[228:231], v[2:5]
	v_mfma_f32_16x16x32_bf16 v[2:5], v[168:171], v[196:199], v[22:25]
	v_mfma_f32_16x16x32_bf16 v[34:37], v[172:175], v[200:203], v[2:5]
	v_mfma_f32_16x16x32_bf16 v[2:5], v[168:171], v[204:207], v[18:21]
	v_mfma_f32_16x16x32_bf16 v[38:41], v[172:175], v[228:231], v[2:5]
	v_mfma_f32_16x16x32_bf16 v[2:5], v[188:191], v[196:199], v[150:153]
	v_mfma_f32_16x16x32_bf16 v[18:21], v[208:211], v[200:203], v[2:5]
	v_mfma_f32_16x16x32_bf16 v[2:5], v[188:191], v[204:207], v[154:157]
	v_mfma_f32_16x16x32_bf16 v[22:25], v[208:211], v[228:231], v[2:5]
	v_mfma_f32_16x16x32_bf16 v[2:5], v[212:215], v[196:199], v[6:9]
	v_mfma_f32_16x16x32_bf16 v[6:9], v[212:215], v[204:207], v[180:183]
	v_mfma_f32_16x16x32_bf16 v[2:5], v[130:133], v[200:203], v[2:5]
	v_mfma_f32_16x16x32_bf16 v[6:9], v[130:133], v[228:231], v[6:9]
	s_setprio 0
	s_movk_i32 s3, 0x100
	v_cmp_gt_u32_e32 vcc, s3, v0
	s_barrier
	s_and_saveexec_b64 s[6:7], vcc
	s_cbranch_execz .LBB0_586
	s_barrier

; #define WAIT_V(n) asm volatile("s_waitcnt vmcnt(" #n ")" ::: "memory")
; #define BAR __builtin_amdgcn_s_barrier()
; template <bool HS>
; __device__ __forceinline__ void gemm_tile8(const u16* __restrict__ Ap, const u16* __restrict__ Bp, int K,
;                                            f32x4 (&acc)[2][2][4][2], char* shm, const int tid, const float* hsr = nullptr) {
;   const int wid = tid >> 6, lane = tid & 63, wr = wid >> 2, wc = wid & 3, fr = lane & 15, fq = lane >> 4;
;   int r0, c0, r1, c1;
;   stage_rc(tid * 16, r0, c0);
;   stage_rc(tid * 16 + 8192, r1, c1);
;   const unsigned off0 = (unsigned)(r0 * K + c0) * 2u, off1 = (unsigned)(r1 * K + c1) * 2u;
;   const int wvoff = __builtin_amdgcn_readfirstlane(tid >> 6) * 1024;
;   const u16* A1 = Ap + (size_t)128 * K;
;   const u16* B1p = Bp + (size_t)128 * K;
; #pragma unroll
;   for (int a = 0; a < 2; ++a)
; #pragma unroll
;     for (int b = 0; b < 2; ++b)
; #pragma unroll
;       for (int m = 0; m < 4; ++m)
; #pragma unroll
;         for (int n = 0; n < 2; ++n) acc[a][b][m][n] = f32x4{0.f, 0.f, 0.f, 0.f};
;   const int abase = lds_byte(wr * 64 + fr, fq * 8), bbase = lds_byte(wc * 32 + fr, fq * 8);
;   bf16x8 At[4][2], B0[2][2], B1[2][2];
;   const unsigned lds0 = (unsigned)(size_t)(__attribute__((address_space(3))) char*)shm + (unsigned)wvoff;
;     ...
;   const int nt = K / BK;
;   WAIT_V(0);
;   if (wr == 1) BAR;
;   BAR;
;   BAR;
.LBB0_650:
	s_or_b64 exec, exec, s[0:1]
	v_bfe_i32 v6, v0, 27, 1
	v_lshlrev_b32_e32 v4, 4, v0
	v_lshrrev_b32_e32 v6, 22, v6
	v_add_u32_e32 v6, v4, v6
	v_and_b32_e32 v6, 0xfffffc00, v6
	v_ashrrev_i32_e32 v5, 31, v0
	v_sub_u32_e32 v6, v4, v6
	v_lshrrev_b32_e32 v5, 26, v5
	v_lshrrev_b32_e32 v7, 4, v6
	v_add_u32_e32 v5, v0, v5
	v_bitop3_b32 v7, v7, v6, 32 bitop3:0x6c
	v_ashrrev_i32_e32 v6, 31, v6
	v_ashrrev_i32_e32 v5, 6, v5
	v_lshrrev_b32_e32 v6, 26, v6
	v_lshlrev_b32_e32 v8, 3, v5
	v_add_u32_e32 v6, v7, v6
	v_and_b32_e32 v8, 0xfffff0, v8
	v_ashrrev_i32_e32 v6, 6, v6
	v_add_u32_e32 v8, v6, v8
	v_mul_i32_i24_e32 v6, 64, v6
	v_add_u32_e32 v4, 0x2000, v4
	v_sub_u32_e32 v6, v7, v6
	v_ashrrev_i32_e32 v7, 31, v4
	v_lshrrev_b32_e32 v7, 22, v7
	v_add_u32_e32 v7, v4, v7
	v_ashrrev_i32_e32 v7, 10, v7
	v_mul_i32_i24_e32 v9, 0x400, v7
	v_sub_u32_e32 v4, v4, v9
	v_lshrrev_b32_e32 v9, 4, v4
	s_ashr_i32 s5, s4, 31
	s_mul_i32 s1, s4, 0x1600
	v_bitop3_b32 v4, v9, v4, 32 bitop3:0x6c
	s_mul_hi_i32 s0, s4, 0x1600
	s_add_u32 s3, s90, s1
	v_ashrrev_i32_e32 v10, 31, v4
	s_addc_u32 s8, s91, s0
	s_mul_i32 s0, s10, 0x160000
	v_lshrrev_b32_e32 v10, 26, v10
	s_ashr_i32 s1, s0, 31
	v_lshlrev_b32_e32 v9, 3, v7
	v_add_u32_e32 v10, v4, v10
	v_lshl_add_u64 v[130:131], v[146:147], 0, s[0:1]
	v_and_b32_e32 v9, 0xfffff0, v9
	v_lshrrev_b32_e32 v11, 6, v10
	v_and_b32_e32 v10, 0xc0, v10
	s_movk_i32 s0, 0xb00
	v_lshlrev_b32_e32 v5, 5, v5
	v_add_u32_e32 v9, v11, v9
	v_sub_u32_e32 v4, v4, v10
	v_mul_lo_u32 v8, v8, s0
	v_lshlrev_b32_e32 v7, 5, v7
	v_ashrrev_i16_sdwa v4, v178, sext(v4) dst_sel:DWORD dst_unused:UNUSED_PAD src0_sel:DWORD src1_sel:BYTE_0
	v_and_or_b32 v5, v5, 32, v8
	v_mul_lo_u32 v8, v9, s0
	v_ashrrev_i16_sdwa v6, v178, sext(v6) dst_sel:DWORD dst_unused:UNUSED_PAD src0_sel:DWORD src1_sel:BYTE_0
	v_bfe_i32 v4, v4, 0, 16
	v_and_or_b32 v7, v7, 32, v8
	v_bfe_i32 v6, v6, 0, 16
	s_add_u32 s9, s3, 0xb0000
	v_and_b32_e32 v8, 15, v0
	v_add_lshl_u32 v135, v7, v4, 1
	v_lshlrev_b32_e32 v7, 2, v0
	s_addc_u32 s11, s8, 0
	v_add_lshl_u32 v136, v5, v6, 1
	s_lshl_b32 s12, s12, 10
	s_mov_b64 s[0:1], 0xb0000
	v_and_b32_e32 v4, 48, v0
	v_lshlrev_b32_e32 v5, 6, v8
	v_and_b32_e32 v7, 32, v7
	v_lshl_add_u64 v[132:133], v[130:131], 0, s[0:1]
	v_or_b32_e32 v6, v5, v4
	v_lshlrev_b32_e32 v3, 13, v3
	v_bitop3_b32 v4, v5, v7, v4 bitop3:0x36
	v_lshlrev_b32_e32 v2, 12, v2
	s_movk_i32 s0, 0x3000
	s_add_i32 s13, s12, 0
	v_bitop3_b32 v3, v6, v3, v7 bitop3:0xde
	v_and_or_b32 v137, v2, s0, v4
	s_add_u32 s14, s3, 0xb0100
	v_mov_b32_e32 v2, 0
	s_addc_u32 s15, s8, 0
	s_mov_b32 s16, -2
	s_mov_b64 s[0:1], 0
	v_add_u32_e32 v134, 0, v3
	v_mov_b32_e32 v3, v2
	v_mov_b32_e32 v4, v2
	v_mov_b32_e32 v5, v2
	v_mov_b32_e32 v6, v2
	v_mov_b32_e32 v7, v2
	v_mov_b32_e32 v8, v2
	v_mov_b32_e32 v9, v2
	v_mov_b32_e32 v10, v2
	v_mov_b32_e32 v11, v2
	v_mov_b32_e32 v12, v2
	v_mov_b32_e32 v13, v2
	v_mov_b32_e32 v14, v2
	v_mov_b32_e32 v15, v2
	v_mov_b32_e32 v16, v2
	v_mov_b32_e32 v17, v2
	v_mov_b32_e32 v18, v2
	v_mov_b32_e32 v19, v2
	v_mov_b32_e32 v20, v2
	v_mov_b32_e32 v21, v2
	v_mov_b32_e32 v22, v2
	v_mov_b32_e32 v23, v2
	v_mov_b32_e32 v24, v2
	v_mov_b32_e32 v25, v2
	v_mov_b32_e32 v26, v2
	v_mov_b32_e32 v27, v2
	v_mov_b32_e32 v28, v2
	s_waitcnt lgkmcnt(0)
	v_mov_b32_e32 v29, v2
	v_mov_b32_e32 v30, v2
	v_mov_b32_e32 v31, v2
	v_mov_b32_e32 v32, v2
	v_mov_b32_e32 v33, v2
	v_mov_b32_e32 v34, v2
	v_mov_b32_e32 v35, v2
	v_mov_b32_e32 v36, v2
	v_mov_b32_e32 v37, v2
	v_mov_b32_e32 v38, v2
	v_mov_b32_e32 v39, v2
	v_mov_b32_e32 v40, v2
	v_mov_b32_e32 v41, v2
	v_mov_b32_e32 v42, v2
	v_mov_b32_e32 v43, v2
	v_mov_b32_e32 v44, v2
	v_mov_b32_e32 v45, v2
	v_mov_b32_e32 v46, v2
	v_mov_b32_e32 v47, v2
	v_mov_b32_e32 v48, v2
	v_mov_b32_e32 v49, v2
	v_mov_b32_e32 v50, v2
	v_mov_b32_e32 v51, v2
	v_mov_b32_e32 v52, v2
	v_mov_b32_e32 v53, v2
	v_mov_b32_e32 v54, v2
	v_mov_b32_e32 v55, v2
	v_mov_b32_e32 v56, v2
	v_mov_b32_e32 v57, v2
	v_mov_b32_e32 v58, v2
	v_mov_b32_e32 v59, v2
	v_mov_b32_e32 v60, v2
	v_mov_b32_e32 v61, v2
	v_mov_b32_e32 v62, v2
	v_mov_b32_e32 v63, v2
	v_mov_b32_e32 v64, v2
	v_mov_b32_e32 v65, v2
	v_mov_b32_e32 v66, v2
	v_mov_b32_e32 v67, v2
	v_mov_b32_e32 v68, v2
	v_mov_b32_e32 v69, v2
	v_mov_b32_e32 v70, v2
	v_mov_b32_e32 v71, v2
	v_mov_b32_e32 v72, v2
	v_mov_b32_e32 v73, v2
	v_mov_b32_e32 v74, v2
	v_mov_b32_e32 v75, v2
	v_mov_b32_e32 v76, v2
	v_mov_b32_e32 v77, v2
	v_mov_b32_e32 v78, v2
	v_mov_b32_e32 v79, v2
	v_mov_b32_e32 v80, v2
	v_mov_b32_e32 v81, v2
	v_mov_b32_e32 v82, v2
	v_mov_b32_e32 v83, v2
	v_mov_b32_e32 v84, v2
	v_mov_b32_e32 v85, v2
	v_mov_b32_e32 v86, v2
	v_mov_b32_e32 v87, v2
	v_mov_b32_e32 v88, v2
	v_mov_b32_e32 v89, v2
	v_mov_b32_e32 v90, v2
	v_mov_b32_e32 v91, v2
	v_mov_b32_e32 v92, v2
	v_mov_b32_e32 v93, v2
	v_mov_b32_e32 v94, v2
	v_mov_b32_e32 v95, v2
	v_mov_b32_e32 v96, v2
	v_mov_b32_e32 v97, v2
	v_mov_b32_e32 v98, v2
	v_mov_b32_e32 v99, v2
	v_mov_b32_e32 v100, v2
	v_mov_b32_e32 v101, v2
	v_mov_b32_e32 v102, v2
	v_mov_b32_e32 v103, v2
	v_mov_b32_e32 v104, v2
	v_mov_b32_e32 v105, v2
	v_mov_b32_e32 v106, v2
	v_mov_b32_e32 v107, v2
	v_mov_b32_e32 v108, v2
	v_mov_b32_e32 v109, v2
	v_mov_b32_e32 v110, v2
	v_mov_b32_e32 v111, v2
	v_mov_b32_e32 v112, v2
	v_mov_b32_e32 v113, v2
	v_mov_b32_e32 v114, v2
	v_mov_b32_e32 v115, v2
	v_mov_b32_e32 v116, v2
	v_mov_b32_e32 v117, v2
	v_mov_b32_e32 v118, v2
	v_mov_b32_e32 v119, v2
	v_mov_b32_e32 v120, v2
	v_mov_b32_e32 v121, v2
	v_mov_b32_e32 v122, v2
	v_mov_b32_e32 v123, v2
	v_mov_b32_e32 v124, v2
	v_mov_b32_e32 v125, v2
	v_mov_b32_e32 v126, v2
	v_mov_b32_e32 v127, v2
	v_mov_b32_e32 v128, v2
	v_mov_b32_e32 v129, v2
	v_readfirstlane_b32 s22, v130
	v_readfirstlane_b32 s23, v131
	v_readfirstlane_b32 s18, v132
	v_readfirstlane_b32 s19, v133
	s_barrier
	s_barrier
; #define WAIT_V(n) asm volatile("s_waitcnt vmcnt(" #n ")" ::: "memory")
; #define WAIT_L(n) asm volatile("s_waitcnt lgkmcnt(" #n ")" ::: "memory")
; #define BAR __builtin_amdgcn_s_barrier()
; #define SCHED __builtin_amdgcn_sched_barrier(0)
; #define STG_A(b, h, kt) stage_half_s(lds0 + ((b) * 2 + (h)) * HT_B, ((h) ? A1 : Ap) + (kt) * BK, off0, off1)
; #define STG_B(b, h, kt) stage_half_s(lds0 + (4 + (b) * 2 + (h)) * HT_B, ((h) ? B1p : Bp) + (kt) * BK, off0, off1)
; #define STG_A(b, h, kt) stage_half_s(lds0 + ((b) * 2 + (h)) * HT_B, ((h) ? A1 : Ap) + (kt) * BK, off0, off1)
; #define STG_B(b, h, kt) stage_half_s(lds0 + (4 + (b) * 2 + (h)) * HT_B, ((h) ? B1p : Bp) + (kt) * BK, off0, off1)
; #define LDA8(b, h) _Pragma("unroll") for (int m = 0; m < 4; ++m) _Pragma("unroll") for (int k = 0; k < 2; ++k) \
;     At[m][k] = *(const bf16x8*)(SA_(shm, b, h) + abase + (m * 2 + k) * 1024)
; #define LDB8(dst, b, h) _Pragma("unroll") for (int n = 0; n < 2; ++n) _Pragma("unroll") for (int k = 0; k < 2; ++k) \
;     dst[n][k] = *(const bf16x8*)(SB_(shm, b, h) + bbase + (n * 2 + k) * 1024)
; #define MMA8(ai, bj, Bx) do { __builtin_amdgcn_s_setprio(1); \
;     _Pragma("unroll") for (int m = 0; m < 4; ++m) _Pragma("unroll") for (int n = 0; n < 2; ++n) _Pragma("unroll") for (int k = 0; k < 2; ++k) \
;       acc[ai][bj][m][n] = __builtin_amdgcn_mfma_f32_16x16x32_bf16(At[m][k], Bx[n][k], acc[ai][bj][m][n], 0, 0, 0); \
;     __builtin_amdgcn_s_setprio(0); } while (0)
; template <bool HS>
; __device__ __forceinline__ void gemm_tile8(const u16* __restrict__ Ap, const u16* __restrict__ Bp, int K,
;                                            f32x4 (&acc)[2][2][4][2], char* shm, const int tid, const float* hsr = nullptr) {
;     ...
;     LDB8(B0, 0, 0); SCHED; LDA8(0, 0); STG_A(1, 1, t + 1);
;     WAIT_L(8); BAR; WAIT_L(0); MMA8(0, 0, B0); BAR; SCHED;
;     LDB8(B1, 0, 1); STG_B(0, 0, t + 2);
;     BAR; WAIT_L(0); MMA8(0, 1, B1); BAR;
;     LDA8(0, 1); STG_A(0, 0, t + 2);
;     BAR; WAIT_L(0); MMA8(1, 0, B0); BAR; SCHED;
;     STG_B(0, 1, t + 2);
;     WAIT_V(6); BAR; MMA8(1, 1, B1); BAR;
.Lk_ffn_out:
	v_add_u32_e32 v164, 0x10000, v137
	ds_read_b128 v[138:141], v164
	ds_read_b128 v[142:145], v164 offset:1024
	ds_read_b128 v[156:159], v164 offset:2048
	ds_read_b128 v[164:167], v164 offset:3072
	ds_read_b128 v[168:171], v134
	ds_read_b128 v[172:175], v134 offset:1024
	ds_read_b128 v[180:183], v134 offset:2048
	ds_read_b128 v[184:187], v134 offset:3072
	ds_read_b128 v[188:191], v134 offset:4096
	ds_read_b128 v[192:195], v134 offset:5120
	ds_read_b128 v[196:199], v134 offset:6144
	ds_read_b128 v[200:203], v134 offset:7168
	v_add_u32_e32 v220, 0x14000, v137
	ds_read_b128 v[204:207], v220
	ds_read_b128 v[208:211], v220 offset:1024
	ds_read_b128 v[212:215], v220 offset:2048
	ds_read_b128 v[220:223], v220 offset:3072
	s_add_u32 s20, s9, s0
	s_addc_u32 s21, s11, s1
	s_add_u32 s20, s20, 0x80
	s_addc_u32 s21, s21, 0
	s_add_i32 s17, s13, 0xc000
	s_mov_b32 m0, s17
	s_nop 0
	global_load_lds_dwordx4 v136, s[20:21]
	s_add_i32 s17, s13, 0xe000
	s_mov_b32 m0, s17
	s_nop 0
	global_load_lds_dwordx4 v135, s[20:21]
	s_waitcnt vmcnt(8) lgkmcnt(0)
	s_barrier
	s_setprio 1
	v_mfma_f32_16x16x32_bf16 v[126:129], v[168:171], v[138:141], v[126:129]
	v_mfma_f32_16x16x32_bf16 v[122:125], v[168:171], v[156:159], v[122:125]
	v_mfma_f32_16x16x32_bf16 v[118:121], v[180:183], v[138:141], v[118:121]
	v_mfma_f32_16x16x32_bf16 v[114:117], v[180:183], v[156:159], v[114:117]
	v_mfma_f32_16x16x32_bf16 v[110:113], v[188:191], v[138:141], v[110:113]
	v_mfma_f32_16x16x32_bf16 v[106:109], v[188:191], v[156:159], v[106:109]
	v_mfma_f32_16x16x32_bf16 v[102:105], v[196:199], v[138:141], v[102:105]
	v_mfma_f32_16x16x32_bf16 v[98:101], v[196:199], v[156:159], v[98:101]
	v_mfma_f32_16x16x32_bf16 v[126:129], v[172:175], v[142:145], v[126:129]
	v_mfma_f32_16x16x32_bf16 v[122:125], v[172:175], v[164:167], v[122:125]
	v_mfma_f32_16x16x32_bf16 v[118:121], v[184:187], v[142:145], v[118:121]
	v_mfma_f32_16x16x32_bf16 v[114:117], v[184:187], v[164:167], v[114:117]
	v_mfma_f32_16x16x32_bf16 v[110:113], v[192:195], v[142:145], v[110:113]
	v_mfma_f32_16x16x32_bf16 v[106:109], v[192:195], v[164:167], v[106:109]
	v_mfma_f32_16x16x32_bf16 v[102:105], v[200:203], v[142:145], v[102:105]
	v_mfma_f32_16x16x32_bf16 v[98:101], v[200:203], v[164:167], v[98:101]
	v_mfma_f32_16x16x32_bf16 v[94:97], v[168:171], v[204:207], v[94:97]
	v_mfma_f32_16x16x32_bf16 v[90:93], v[168:171], v[212:215], v[90:93]
	v_mfma_f32_16x16x32_bf16 v[86:89], v[180:183], v[204:207], v[86:89]
	v_mfma_f32_16x16x32_bf16 v[82:85], v[180:183], v[212:215], v[82:85]
	v_mfma_f32_16x16x32_bf16 v[78:81], v[188:191], v[204:207], v[78:81]
	v_mfma_f32_16x16x32_bf16 v[74:77], v[188:191], v[212:215], v[74:77]
	v_mfma_f32_16x16x32_bf16 v[70:73], v[196:199], v[204:207], v[70:73]
	v_mfma_f32_16x16x32_bf16 v[66:69], v[196:199], v[212:215], v[66:69]
	v_mfma_f32_16x16x32_bf16 v[94:97], v[172:175], v[208:211], v[94:97]
	v_mfma_f32_16x16x32_bf16 v[90:93], v[172:175], v[220:223], v[90:93]
	v_mfma_f32_16x16x32_bf16 v[86:89], v[184:187], v[208:211], v[86:89]
	v_mfma_f32_16x16x32_bf16 v[82:85], v[184:187], v[220:223], v[82:85]
	v_mfma_f32_16x16x32_bf16 v[78:81], v[192:195], v[208:211], v[78:81]
	v_mfma_f32_16x16x32_bf16 v[74:77], v[192:195], v[220:223], v[74:77]
	v_mfma_f32_16x16x32_bf16 v[70:73], v[200:203], v[208:211], v[70:73]
	v_mfma_f32_16x16x32_bf16 v[66:69], v[200:203], v[220:223], v[66:69]
	s_setprio 0
	s_barrier
	ds_read_b128 v[168:171], v134 offset:16384
	ds_read_b128 v[172:175], v134 offset:17408
	ds_read_b128 v[180:183], v134 offset:18432
	ds_read_b128 v[184:187], v134 offset:19456
	ds_read_b128 v[188:191], v134 offset:20480
	ds_read_b128 v[192:195], v134 offset:21504
	ds_read_b128 v[196:199], v134 offset:22528
	ds_read_b128 v[200:203], v134 offset:23552
	s_add_u32 s20, s22, s0
	s_addc_u32 s21, s23, s1
	s_add_u32 s20, s20, 0x100
	s_addc_u32 s21, s21, 0
	s_add_i32 s17, s13, 0x10000
	s_mov_b32 m0, s17
	s_nop 0
	global_load_lds_dwordx4 v136, s[20:21]
	s_add_i32 s17, s13, 0x12000
	s_mov_b32 m0, s17
	s_nop 0
	global_load_lds_dwordx4 v135, s[20:21]
	s_add_u32 s20, s3, s0
	s_addc_u32 s21, s8, s1
	s_add_u32 s20, s20, 0x100
	s_addc_u32 s21, s21, 0
	s_mov_b32 m0, s13
	s_nop 0
	global_load_lds_dwordx4 v136, s[20:21]
	s_add_i32 s17, s13, 0x2000
	s_mov_b32 m0, s17
	s_nop 0
	global_load_lds_dwordx4 v135, s[20:21]
	s_add_u32 s20, s18, s0
	s_addc_u32 s21, s19, s1
	s_add_u32 s20, s20, 0x100
	s_addc_u32 s21, s21, 0
	s_add_i32 s17, s13, 0x14000
	s_mov_b32 m0, s17
	s_nop 0
	global_load_lds_dwordx4 v136, s[20:21]
	s_add_i32 s17, s13, 0x16000
	s_mov_b32 m0, s17
	s_nop 0
	global_load_lds_dwordx4 v135, s[20:21]
	s_waitcnt vmcnt(8) lgkmcnt(0)
	s_barrier
; #define WAIT_V(n) asm volatile("s_waitcnt vmcnt(" #n ")" ::: "memory")
; #define WAIT_L(n) asm volatile("s_waitcnt lgkmcnt(" #n ")" ::: "memory")
; #define BAR __builtin_amdgcn_s_barrier()
; #define SCHED __builtin_amdgcn_sched_barrier(0)
; #define STG_A(b, h, kt) stage_half_s(lds0 + ((b) * 2 + (h)) * HT_B, ((h) ? A1 : Ap) + (kt) * BK, off0, off1)
; #define STG_B(b, h, kt) stage_half_s(lds0 + (4 + (b) * 2 + (h)) * HT_B, ((h) ? B1p : Bp) + (kt) * BK, off0, off1)
; #define STG_A(b, h, kt) stage_half_s(lds0 + ((b) * 2 + (h)) * HT_B, ((h) ? A1 : Ap) + (kt) * BK, off0, off1)
; #define STG_B(b, h, kt) stage_half_s(lds0 + (4 + (b) * 2 + (h)) * HT_B, ((h) ? B1p : Bp) + (kt) * BK, off0, off1)
; #define LDA8(b, h) _Pragma("unroll") for (int m = 0; m < 4; ++m) _Pragma("unroll") for (int k = 0; k < 2; ++k) \
;     At[m][k] = *(const bf16x8*)(SA_(shm, b, h) + abase + (m * 2 + k) * 1024)
; #define LDB8(dst, b, h) _Pragma("unroll") for (int n = 0; n < 2; ++n) _Pragma("unroll") for (int k = 0; k < 2; ++k) \
;     dst[n][k] = *(const bf16x8*)(SB_(shm, b, h) + bbase + (n * 2 + k) * 1024)
; #define MMA8(ai, bj, Bx) do { __builtin_amdgcn_s_setprio(1); \
;     _Pragma("unroll") for (int m = 0; m < 4; ++m) _Pragma("unroll") for (int n = 0; n < 2; ++n) _Pragma("unroll") for (int k = 0; k < 2; ++k) \
;       acc[ai][bj][m][n] = __builtin_amdgcn_mfma_f32_16x16x32_bf16(At[m][k], Bx[n][k], acc[ai][bj][m][n], 0, 0, 0); \
;     __builtin_amdgcn_s_setprio(0); } while (0)
; template <bool HS>
; __device__ __forceinline__ void gemm_tile8(const u16* __restrict__ Ap, const u16* __restrict__ Bp, int K,
;                                            f32x4 (&acc)[2][2][4][2], char* shm, const int tid, const float* hsr = nullptr) {
;     ...
;     BAR; WAIT_L(0); MMA8(1, 0, B0); BAR; SCHED;
;     STG_B(0, 1, t + 2);
;     WAIT_V(6); BAR; MMA8(1, 1, B1); BAR;
;     LDB8(B0, 1, 0); SCHED; LDA8(1, 0); STG_A(0, 1, t + 2);
;     WAIT_L(8); BAR; WAIT_L(0); MMA8(0, 0, B0); BAR; SCHED;
;     LDB8(B1, 1, 1); STG_B(1, 0, t + 3);
;     BAR; WAIT_L(0); MMA8(0, 1, B1); BAR;
	s_setprio 1
	v_mfma_f32_16x16x32_bf16 v[62:65], v[168:171], v[138:141], v[62:65]
	v_mfma_f32_16x16x32_bf16 v[58:61], v[168:171], v[156:159], v[58:61]
	v_mfma_f32_16x16x32_bf16 v[54:57], v[180:183], v[138:141], v[54:57]
	v_mfma_f32_16x16x32_bf16 v[50:53], v[180:183], v[156:159], v[50:53]
	v_mfma_f32_16x16x32_bf16 v[46:49], v[188:191], v[138:141], v[46:49]
	v_mfma_f32_16x16x32_bf16 v[42:45], v[188:191], v[156:159], v[42:45]
	v_mfma_f32_16x16x32_bf16 v[38:41], v[196:199], v[138:141], v[38:41]
	v_mfma_f32_16x16x32_bf16 v[34:37], v[196:199], v[156:159], v[34:37]
	v_mfma_f32_16x16x32_bf16 v[62:65], v[172:175], v[142:145], v[62:65]
	v_mfma_f32_16x16x32_bf16 v[58:61], v[172:175], v[164:167], v[58:61]
	v_mfma_f32_16x16x32_bf16 v[54:57], v[184:187], v[142:145], v[54:57]
	v_mfma_f32_16x16x32_bf16 v[50:53], v[184:187], v[164:167], v[50:53]
	v_mfma_f32_16x16x32_bf16 v[46:49], v[192:195], v[142:145], v[46:49]
	v_mfma_f32_16x16x32_bf16 v[42:45], v[192:195], v[164:167], v[42:45]
	v_mfma_f32_16x16x32_bf16 v[38:41], v[200:203], v[142:145], v[38:41]
	v_mfma_f32_16x16x32_bf16 v[34:37], v[200:203], v[164:167], v[34:37]
	v_mfma_f32_16x16x32_bf16 v[30:33], v[168:171], v[204:207], v[30:33]
	v_mfma_f32_16x16x32_bf16 v[26:29], v[168:171], v[212:215], v[26:29]
	v_mfma_f32_16x16x32_bf16 v[22:25], v[180:183], v[204:207], v[22:25]
	v_mfma_f32_16x16x32_bf16 v[18:21], v[180:183], v[212:215], v[18:21]
	v_mfma_f32_16x16x32_bf16 v[14:17], v[188:191], v[204:207], v[14:17]
	v_mfma_f32_16x16x32_bf16 v[10:13], v[188:191], v[212:215], v[10:13]
	v_mfma_f32_16x16x32_bf16 v[6:9], v[196:199], v[204:207], v[6:9]
	v_mfma_f32_16x16x32_bf16 v[2:5], v[196:199], v[212:215], v[2:5]
	v_mfma_f32_16x16x32_bf16 v[30:33], v[172:175], v[208:211], v[30:33]
	v_mfma_f32_16x16x32_bf16 v[26:29], v[172:175], v[220:223], v[26:29]
	v_mfma_f32_16x16x32_bf16 v[22:25], v[184:187], v[208:211], v[22:25]
	v_mfma_f32_16x16x32_bf16 v[18:21], v[184:187], v[220:223], v[18:21]
	v_mfma_f32_16x16x32_bf16 v[14:17], v[192:195], v[208:211], v[14:17]
	v_mfma_f32_16x16x32_bf16 v[10:13], v[192:195], v[220:223], v[10:13]
	v_mfma_f32_16x16x32_bf16 v[6:9], v[200:203], v[208:211], v[6:9]
	v_mfma_f32_16x16x32_bf16 v[2:5], v[200:203], v[220:223], v[2:5]
	s_setprio 0
	s_barrier
	v_add_u32_e32 v164, 0x18000, v137
	ds_read_b128 v[138:141], v164
	ds_read_b128 v[142:145], v164 offset:1024
	ds_read_b128 v[156:159], v164 offset:2048
	ds_read_b128 v[164:167], v164 offset:3072
	ds_read_b128 v[168:171], v134 offset:32768
	ds_read_b128 v[172:175], v134 offset:33792
	ds_read_b128 v[180:183], v134 offset:34816
	ds_read_b128 v[184:187], v134 offset:35840
	ds_read_b128 v[188:191], v134 offset:36864
	ds_read_b128 v[192:195], v134 offset:37888
	ds_read_b128 v[196:199], v134 offset:38912
	ds_read_b128 v[200:203], v134 offset:39936
	v_add_u32_e32 v220, 0x1c000, v137
	ds_read_b128 v[204:207], v220
	ds_read_b128 v[208:211], v220 offset:1024
	ds_read_b128 v[212:215], v220 offset:2048
	ds_read_b128 v[220:223], v220 offset:3072
	s_add_u32 s20, s9, s0
	s_addc_u32 s21, s11, s1
	s_add_u32 s20, s20, 0x100
	s_addc_u32 s21, s21, 0
	s_add_i32 s17, s13, 0x4000
	s_mov_b32 m0, s17
	s_nop 0
	global_load_lds_dwordx4 v136, s[20:21]
	s_add_i32 s17, s13, 0x6000
	s_mov_b32 m0, s17
	s_nop 0
	global_load_lds_dwordx4 v135, s[20:21]
	s_waitcnt vmcnt(8) lgkmcnt(0)
	s_barrier
	s_setprio 1
	v_mfma_f32_16x16x32_bf16 v[126:129], v[168:171], v[138:141], v[126:129]
	v_mfma_f32_16x16x32_bf16 v[122:125], v[168:171], v[156:159], v[122:125]
	v_mfma_f32_16x16x32_bf16 v[118:121], v[180:183], v[138:141], v[118:121]
	v_mfma_f32_16x16x32_bf16 v[114:117], v[180:183], v[156:159], v[114:117]
	v_mfma_f32_16x16x32_bf16 v[110:113], v[188:191], v[138:141], v[110:113]
	v_mfma_f32_16x16x32_bf16 v[106:109], v[188:191], v[156:159], v[106:109]
	v_mfma_f32_16x16x32_bf16 v[102:105], v[196:199], v[138:141], v[102:105]
	v_mfma_f32_16x16x32_bf16 v[98:101], v[196:199], v[156:159], v[98:101]
	v_mfma_f32_16x16x32_bf16 v[126:129], v[172:175], v[142:145], v[126:129]
	v_mfma_f32_16x16x32_bf16 v[122:125], v[172:175], v[164:167], v[122:125]
	v_mfma_f32_16x16x32_bf16 v[118:121], v[184:187], v[142:145], v[118:121]
	v_mfma_f32_16x16x32_bf16 v[114:117], v[184:187], v[164:167], v[114:117]
	v_mfma_f32_16x16x32_bf16 v[110:113], v[192:195], v[142:145], v[110:113]
	v_mfma_f32_16x16x32_bf16 v[106:109], v[192:195], v[164:167], v[106:109]
	v_mfma_f32_16x16x32_bf16 v[102:105], v[200:203], v[142:145], v[102:105]
	v_mfma_f32_16x16x32_bf16 v[98:101], v[200:203], v[164:167], v[98:101]
	v_mfma_f32_16x16x32_bf16 v[94:97], v[168:171], v[204:207], v[94:97]
	v_mfma_f32_16x16x32_bf16 v[90:93], v[168:171], v[212:215], v[90:93]
	v_mfma_f32_16x16x32_bf16 v[86:89], v[180:183], v[204:207], v[86:89]
	v_mfma_f32_16x16x32_bf16 v[82:85], v[180:183], v[212:215], v[82:85]
	v_mfma_f32_16x16x32_bf16 v[78:81], v[188:191], v[204:207], v[78:81]
	v_mfma_f32_16x16x32_bf16 v[74:77], v[188:191], v[212:215], v[74:77]
	v_mfma_f32_16x16x32_bf16 v[70:73], v[196:199], v[204:207], v[70:73]
	v_mfma_f32_16x16x32_bf16 v[66:69], v[196:199], v[212:215], v[66:69]
	v_mfma_f32_16x16x32_bf16 v[94:97], v[172:175], v[208:211], v[94:97]
	v_mfma_f32_16x16x32_bf16 v[90:93], v[172:175], v[220:223], v[90:93]
	v_mfma_f32_16x16x32_bf16 v[86:89], v[184:187], v[208:211], v[86:89]
	v_mfma_f32_16x16x32_bf16 v[82:85], v[184:187], v[220:223], v[82:85]
	v_mfma_f32_16x16x32_bf16 v[78:81], v[192:195], v[208:211], v[78:81]
	v_mfma_f32_16x16x32_bf16 v[74:77], v[192:195], v[220:223], v[74:77]
	v_mfma_f32_16x16x32_bf16 v[70:73], v[200:203], v[208:211], v[70:73]
	v_mfma_f32_16x16x32_bf16 v[66:69], v[200:203], v[220:223], v[66:69]
	s_setprio 0
	s_barrier
; #define WAIT_V(n) asm volatile("s_waitcnt vmcnt(" #n ")" ::: "memory")
; #define WAIT_L(n) asm volatile("s_waitcnt lgkmcnt(" #n ")" ::: "memory")
; #define BAR __builtin_amdgcn_s_barrier()
; #define SCHED __builtin_amdgcn_sched_barrier(0)
; #define STG_A(b, h, kt) stage_half_s(lds0 + ((b) * 2 + (h)) * HT_B, ((h) ? A1 : Ap) + (kt) * BK, off0, off1)
; #define STG_B(b, h, kt) stage_half_s(lds0 + (4 + (b) * 2 + (h)) * HT_B, ((h) ? B1p : Bp) + (kt) * BK, off0, off1)
; #define STG_A(b, h, kt) stage_half_s(lds0 + ((b) * 2 + (h)) * HT_B, ((h) ? A1 : Ap) + (kt) * BK, off0, off1)
; #define STG_B(b, h, kt) stage_half_s(lds0 + (4 + (b) * 2 + (h)) * HT_B, ((h) ? B1p : Bp) + (kt) * BK, off0, off1)
; #define LDA8(b, h) _Pragma("unroll") for (int m = 0; m < 4; ++m) _Pragma("unroll") for (int k = 0; k < 2; ++k) \
;     At[m][k] = *(const bf16x8*)(SA_(shm, b, h) + abase + (m * 2 + k) * 1024)
; #define LDB8(dst, b, h) _Pragma("unroll") for (int n = 0; n < 2; ++n) _Pragma("unroll") for (int k = 0; k < 2; ++k) \
;     dst[n][k] = *(const bf16x8*)(SB_(shm, b, h) + bbase + (n * 2 + k) * 1024)
; #define MMA8(ai, bj, Bx) do { __builtin_amdgcn_s_setprio(1); \
;     _Pragma("unroll") for (int m = 0; m < 4; ++m) _Pragma("unroll") for (int n = 0; n < 2; ++n) _Pragma("unroll") for (int k = 0; k < 2; ++k) \
;       acc[ai][bj][m][n] = __builtin_amdgcn_mfma_f32_16x16x32_bf16(At[m][k], Bx[n][k], acc[ai][bj][m][n], 0, 0, 0); \
;     __builtin_amdgcn_s_setprio(0); } while (0)
; template <bool HS>
; __device__ __forceinline__ void gemm_tile8(const u16* __restrict__ Ap, const u16* __restrict__ Bp, int K,
;                                            f32x4 (&acc)[2][2][4][2], char* shm, const int tid, const float* hsr = nullptr) {
;     ...
;     LDB8(B0, 1, 0); SCHED; LDA8(1, 0); STG_A(0, 1, t + 2);
;     WAIT_L(8); BAR; WAIT_L(0); MMA8(0, 0, B0); BAR; SCHED;
;     LDB8(B1, 1, 1); STG_B(1, 0, t + 3);
;     BAR; WAIT_L(0); MMA8(0, 1, B1); BAR;
;     LDA8(1, 1); STG_A(1, 0, t + 3);
;     BAR; WAIT_L(0); MMA8(1, 0, B0); BAR; SCHED;
;     STG_B(1, 1, t + 3);
;     WAIT_V(6); BAR; MMA8(1, 1, B1); BAR;
;   }
;   { LDB8(B0, 0, 0); LDA8(0, 0); STG_A(1, 1, nt - 1);
;     BAR; WAIT_L(0); MMA8(0, 0, B0); BAR;
;     LDB8(B1, 0, 1); BAR; WAIT_L(0); MMA8(0, 1, B1); BAR;
;     LDA8(0, 1); WAIT_V(4); BAR; WAIT_L(0); MMA8(1, 0, B0); MMA8(1, 1, B1); BAR; }
	ds_read_b128 v[168:171], v134 offset:49152
	ds_read_b128 v[172:175], v134 offset:50176
	ds_read_b128 v[180:183], v134 offset:51200
	ds_read_b128 v[184:187], v134 offset:52224
	ds_read_b128 v[188:191], v134 offset:53248
	ds_read_b128 v[192:195], v134 offset:54272
	ds_read_b128 v[196:199], v134 offset:55296
	ds_read_b128 v[200:203], v134 offset:56320
	s_add_u32 s20, s22, s0
	s_addc_u32 s21, s23, s1
	s_add_u32 s20, s20, 0x180
	s_addc_u32 s21, s21, 0
	s_add_i32 s17, s13, 0x18000
	s_mov_b32 m0, s17
	s_nop 0
	global_load_lds_dwordx4 v136, s[20:21]
	s_add_i32 s17, s13, 0x1a000
	s_mov_b32 m0, s17
	s_nop 0
	global_load_lds_dwordx4 v135, s[20:21]
	s_add_u32 s20, s3, s0
	s_addc_u32 s21, s8, s1
	s_add_u32 s20, s20, 0x180
	s_addc_u32 s21, s21, 0
	s_add_i32 s17, s13, 0x8000
	s_mov_b32 m0, s17
	s_nop 0
	global_load_lds_dwordx4 v136, s[20:21]
	s_add_i32 s17, s13, 0xa000
	s_mov_b32 m0, s17
	s_nop 0
	global_load_lds_dwordx4 v135, s[20:21]
	s_add_u32 s20, s18, s0
	s_addc_u32 s21, s19, s1
	s_add_u32 s20, s20, 0x180
	s_addc_u32 s21, s21, 0
	s_add_i32 s17, s13, 0x1c000
	s_mov_b32 m0, s17
	s_nop 0
	global_load_lds_dwordx4 v136, s[20:21]
	s_add_i32 s17, s13, 0x1e000
	s_mov_b32 m0, s17
	s_nop 0
	global_load_lds_dwordx4 v135, s[20:21]
	s_waitcnt vmcnt(8) lgkmcnt(0)
	s_barrier
	s_setprio 1
	v_mfma_f32_16x16x32_bf16 v[62:65], v[168:171], v[138:141], v[62:65]
	v_mfma_f32_16x16x32_bf16 v[58:61], v[168:171], v[156:159], v[58:61]
	v_mfma_f32_16x16x32_bf16 v[54:57], v[180:183], v[138:141], v[54:57]
	v_mfma_f32_16x16x32_bf16 v[50:53], v[180:183], v[156:159], v[50:53]
	v_mfma_f32_16x16x32_bf16 v[46:49], v[188:191], v[138:141], v[46:49]
	v_mfma_f32_16x16x32_bf16 v[42:45], v[188:191], v[156:159], v[42:45]
	v_mfma_f32_16x16x32_bf16 v[38:41], v[196:199], v[138:141], v[38:41]
	v_mfma_f32_16x16x32_bf16 v[34:37], v[196:199], v[156:159], v[34:37]
	v_mfma_f32_16x16x32_bf16 v[62:65], v[172:175], v[142:145], v[62:65]
	v_mfma_f32_16x16x32_bf16 v[58:61], v[172:175], v[164:167], v[58:61]
	v_mfma_f32_16x16x32_bf16 v[54:57], v[184:187], v[142:145], v[54:57]
	v_mfma_f32_16x16x32_bf16 v[50:53], v[184:187], v[164:167], v[50:53]
	v_mfma_f32_16x16x32_bf16 v[46:49], v[192:195], v[142:145], v[46:49]
	v_mfma_f32_16x16x32_bf16 v[42:45], v[192:195], v[164:167], v[42:45]
	v_mfma_f32_16x16x32_bf16 v[38:41], v[200:203], v[142:145], v[38:41]
	v_mfma_f32_16x16x32_bf16 v[34:37], v[200:203], v[164:167], v[34:37]
	v_mfma_f32_16x16x32_bf16 v[30:33], v[168:171], v[204:207], v[30:33]
	v_mfma_f32_16x16x32_bf16 v[26:29], v[168:171], v[212:215], v[26:29]
	v_mfma_f32_16x16x32_bf16 v[22:25], v[180:183], v[204:207], v[22:25]
	v_mfma_f32_16x16x32_bf16 v[18:21], v[180:183], v[212:215], v[18:21]
	v_mfma_f32_16x16x32_bf16 v[14:17], v[188:191], v[204:207], v[14:17]
	v_mfma_f32_16x16x32_bf16 v[10:13], v[188:191], v[212:215], v[10:13]
	v_mfma_f32_16x16x32_bf16 v[6:9], v[196:199], v[204:207], v[6:9]
	v_mfma_f32_16x16x32_bf16 v[2:5], v[196:199], v[212:215], v[2:5]
	v_mfma_f32_16x16x32_bf16 v[30:33], v[172:175], v[208:211], v[30:33]
	v_mfma_f32_16x16x32_bf16 v[26:29], v[172:175], v[220:223], v[26:29]
	v_mfma_f32_16x16x32_bf16 v[22:25], v[184:187], v[208:211], v[22:25]
	v_mfma_f32_16x16x32_bf16 v[18:21], v[184:187], v[220:223], v[18:21]
	v_mfma_f32_16x16x32_bf16 v[14:17], v[192:195], v[208:211], v[14:17]
	v_mfma_f32_16x16x32_bf16 v[10:13], v[192:195], v[220:223], v[10:13]
	v_mfma_f32_16x16x32_bf16 v[6:9], v[200:203], v[208:211], v[6:9]
	v_mfma_f32_16x16x32_bf16 v[2:5], v[200:203], v[220:223], v[2:5]
	s_setprio 0
	s_add_i32 s16, s16, 2
	s_add_u32 s0, s0, 0x100
	s_addc_u32 s1, s1, 0
	s_cmp_lt_u32 s16, 40
	s_barrier
	s_cbranch_scc1 .Lk_ffn_out
	s_waitcnt vmcnt(6)
	s_add_i32 s17, s13, 0xc000
	s_add_i32 s18, s13, 0xe000
	v_add_u32_e32 v160, 0, v137
	v_add_u32_e32 v137, 0x10000, v160
	ds_read_b128 v[130:133], v137
	ds_read_b128 v[138:141], v137 offset:1024
	ds_read_b128 v[142:145], v137 offset:2048
	ds_read_b128 v[156:159], v137 offset:3072
	ds_read_b128 v[164:167], v134
	ds_read_b128 v[168:171], v134 offset:1024
	ds_read_b128 v[172:175], v134 offset:2048
	ds_read_b128 v[180:183], v134 offset:3072
	ds_read_b128 v[184:187], v134 offset:4096
	ds_read_b128 v[188:191], v134 offset:5120
	ds_read_b128 v[192:195], v134 offset:6144
	ds_read_b128 v[196:199], v134 offset:7168
	s_add_u32 s0, s3, 0xb1580
	s_addc_u32 s1, s8, 0
	s_mov_b32 m0, s17
	s_nop 0
	global_load_lds_dwordx4 v136, s[0:1]
	s_nop 0
	s_mov_b32 m0, s18
	s_nop 0
	global_load_lds_dwordx4 v135, s[0:1]
	s_barrier
	s_waitcnt lgkmcnt(0)
	s_setprio 1
	s_waitcnt lgkmcnt(7)
	v_mfma_f32_16x16x32_bf16 v[126:129], v[164:167], v[130:133], v[126:129]
	s_waitcnt lgkmcnt(5)
	v_mfma_f32_16x16x32_bf16 v[118:121], v[172:175], v[130:133], v[118:121]
	v_mfma_f32_16x16x32_bf16 v[114:117], v[172:175], v[142:145], v[114:117]
	s_waitcnt lgkmcnt(1)
	v_mfma_f32_16x16x32_bf16 v[102:105], v[192:195], v[130:133], v[102:105]
	v_mfma_f32_16x16x32_bf16 v[98:101], v[192:195], v[142:145], v[98:101]
	v_mfma_f32_16x16x32_bf16 v[126:129], v[168:171], v[138:141], v[126:129]
	v_mfma_f32_16x16x32_bf16 v[122:125], v[164:167], v[142:145], v[122:125]
	v_mfma_f32_16x16x32_bf16 v[118:121], v[180:183], v[138:141], v[118:121]
	v_mfma_f32_16x16x32_bf16 v[114:117], v[180:183], v[156:159], v[114:117]
	v_mfma_f32_16x16x32_bf16 v[110:113], v[184:187], v[130:133], v[110:113]
	v_mfma_f32_16x16x32_bf16 v[106:109], v[184:187], v[142:145], v[106:109]
	s_waitcnt lgkmcnt(0)
	v_mfma_f32_16x16x32_bf16 v[102:105], v[196:199], v[138:141], v[102:105]
	v_mfma_f32_16x16x32_bf16 v[98:101], v[196:199], v[156:159], v[98:101]
	v_mfma_f32_16x16x32_bf16 v[200:203], v[168:171], v[156:159], v[122:125]
	v_mfma_f32_16x16x32_bf16 v[204:207], v[188:191], v[138:141], v[110:113]
	v_mfma_f32_16x16x32_bf16 v[208:211], v[188:191], v[156:159], v[106:109]
	s_setprio 0
	v_add_u32_e32 v135, 0x14000, v160
	s_barrier
; #define WAIT_V(n) asm volatile("s_waitcnt vmcnt(" #n ")" ::: "memory")
; #define WAIT_L(n) asm volatile("s_waitcnt lgkmcnt(" #n ")" ::: "memory")
; #define BAR __builtin_amdgcn_s_barrier()
; #define LDA8(b, h) _Pragma("unroll") for (int m = 0; m < 4; ++m) _Pragma("unroll") for (int k = 0; k < 2; ++k) \
;     At[m][k] = *(const bf16x8*)(SA_(shm, b, h) + abase + (m * 2 + k) * 1024)
; #define LDB8(dst, b, h) _Pragma("unroll") for (int n = 0; n < 2; ++n) _Pragma("unroll") for (int k = 0; k < 2; ++k) \
;     dst[n][k] = *(const bf16x8*)(SB_(shm, b, h) + bbase + (n * 2 + k) * 1024)
; #define MMA8(ai, bj, Bx) do { __builtin_amdgcn_s_setprio(1); \
;     _Pragma("unroll") for (int m = 0; m < 4; ++m) _Pragma("unroll") for (int n = 0; n < 2; ++n) _Pragma("unroll") for (int k = 0; k < 2; ++k) \
;       acc[ai][bj][m][n] = __builtin_amdgcn_mfma_f32_16x16x32_bf16(At[m][k], Bx[n][k], acc[ai][bj][m][n], 0, 0, 0); \
;     __builtin_amdgcn_s_setprio(0); } while (0)
; template <bool HS>
; __device__ __forceinline__ void gemm_tile8(const u16* __restrict__ Ap, const u16* __restrict__ Bp, int K,
;                                            f32x4 (&acc)[2][2][4][2], char* shm, const int tid, const float* hsr = nullptr) {
;     ...
;     BAR; WAIT_L(0); MMA8(0, 0, B0); BAR;
;     LDB8(B1, 0, 1); BAR; WAIT_L(0); MMA8(0, 1, B1); BAR;
;     LDA8(0, 1); WAIT_V(4); BAR; WAIT_L(0); MMA8(1, 0, B0); MMA8(1, 1, B1); BAR; }
;   { LDB8(B0, 1, 0); LDA8(1, 0); WAIT_V(2); BAR; WAIT_L(0); MMA8(0, 0, B0); BAR;
	ds_read_b128 v[106:109], v135
	ds_read_b128 v[110:113], v135 offset:1024
	ds_read_b128 v[122:125], v135 offset:2048
	ds_read_b128 v[212:215], v135 offset:3072
	s_barrier
	s_waitcnt lgkmcnt(0)
	s_setprio 1
	s_waitcnt lgkmcnt(3)
	v_mfma_f32_16x16x32_bf16 v[86:89], v[172:175], v[106:109], v[86:89]
	s_waitcnt lgkmcnt(1)
	v_mfma_f32_16x16x32_bf16 v[82:85], v[172:175], v[122:125], v[82:85]
	v_mfma_f32_16x16x32_bf16 v[70:73], v[192:195], v[106:109], v[70:73]
	v_mfma_f32_16x16x32_bf16 v[94:97], v[164:167], v[106:109], v[94:97]
	v_mfma_f32_16x16x32_bf16 v[90:93], v[164:167], v[122:125], v[90:93]
	v_mfma_f32_16x16x32_bf16 v[86:89], v[180:183], v[110:113], v[86:89]
	s_waitcnt lgkmcnt(0)
	v_mfma_f32_16x16x32_bf16 v[82:85], v[180:183], v[212:215], v[82:85]
	v_mfma_f32_16x16x32_bf16 v[78:81], v[184:187], v[106:109], v[78:81]
	v_mfma_f32_16x16x32_bf16 v[74:77], v[184:187], v[122:125], v[74:77]
	v_mfma_f32_16x16x32_bf16 v[70:73], v[196:199], v[110:113], v[70:73]
	v_mfma_f32_16x16x32_bf16 v[66:69], v[192:195], v[122:125], v[66:69]
	v_mfma_f32_16x16x32_bf16 v[220:223], v[168:171], v[110:113], v[94:97]
	v_mfma_f32_16x16x32_bf16 v[164:167], v[168:171], v[212:215], v[90:93]
	v_mfma_f32_16x16x32_bf16 v[168:171], v[188:191], v[110:113], v[78:81]
	v_mfma_f32_16x16x32_bf16 v[172:175], v[188:191], v[212:215], v[74:77]
	v_mfma_f32_16x16x32_bf16 v[180:183], v[196:199], v[212:215], v[66:69]
	s_setprio 0
	s_barrier
	s_nop 0
	ds_read_b128 v[66:69], v134 offset:16384
	ds_read_b128 v[74:77], v134 offset:17408
	ds_read_b128 v[78:81], v134 offset:18432
	ds_read_b128 v[90:93], v134 offset:19456
	ds_read_b128 v[94:97], v134 offset:20480
	ds_read_b128 v[184:187], v134 offset:21504
	ds_read_b128 v[188:191], v134 offset:22528
	ds_read_b128 v[192:195], v134 offset:23552
	s_waitcnt vmcnt(4)
	s_barrier
	s_waitcnt lgkmcnt(0)
	s_setprio 1
	s_waitcnt lgkmcnt(7)
	v_mfma_f32_16x16x32_bf16 v[62:65], v[66:69], v[130:133], v[62:65]
	s_waitcnt lgkmcnt(5)
	v_mfma_f32_16x16x32_bf16 v[54:57], v[78:81], v[130:133], v[54:57]
	v_mfma_f32_16x16x32_bf16 v[50:53], v[78:81], v[142:145], v[50:53]
	s_waitcnt lgkmcnt(1)
	v_mfma_f32_16x16x32_bf16 v[38:41], v[188:191], v[130:133], v[38:41]
	v_mfma_f32_16x16x32_bf16 v[34:37], v[188:191], v[142:145], v[34:37]
	v_mfma_f32_16x16x32_bf16 v[62:65], v[74:77], v[138:141], v[62:65]
	v_mfma_f32_16x16x32_bf16 v[58:61], v[66:69], v[142:145], v[58:61]
	v_mfma_f32_16x16x32_bf16 v[54:57], v[90:93], v[138:141], v[54:57]
	v_mfma_f32_16x16x32_bf16 v[50:53], v[90:93], v[156:159], v[50:53]
	v_mfma_f32_16x16x32_bf16 v[46:49], v[94:97], v[130:133], v[46:49]
	v_mfma_f32_16x16x32_bf16 v[42:45], v[94:97], v[142:145], v[42:45]
	s_waitcnt lgkmcnt(0)
	v_mfma_f32_16x16x32_bf16 v[38:41], v[192:195], v[138:141], v[38:41]
	v_mfma_f32_16x16x32_bf16 v[34:37], v[192:195], v[156:159], v[34:37]
	v_mfma_f32_16x16x32_bf16 v[196:199], v[74:77], v[156:159], v[58:61]
	v_mfma_f32_16x16x32_bf16 v[242:245], v[184:187], v[138:141], v[46:49]
	v_mfma_f32_16x16x32_bf16 v[246:249], v[184:187], v[156:159], v[42:45]
	s_setprio 0
	s_setprio 1
	v_mfma_f32_16x16x32_bf16 v[22:25], v[78:81], v[106:109], v[22:25]
	v_mfma_f32_16x16x32_bf16 v[18:21], v[78:81], v[122:125], v[18:21]
	v_mfma_f32_16x16x32_bf16 v[6:9], v[188:191], v[106:109], v[6:9]
	v_mfma_f32_16x16x32_bf16 v[30:33], v[66:69], v[106:109], v[30:33]
	v_mfma_f32_16x16x32_bf16 v[26:29], v[66:69], v[122:125], v[26:29]
	v_mfma_f32_16x16x32_bf16 v[22:25], v[90:93], v[110:113], v[22:25]
	v_mfma_f32_16x16x32_bf16 v[18:21], v[90:93], v[212:215], v[18:21]
	v_mfma_f32_16x16x32_bf16 v[14:17], v[94:97], v[106:109], v[14:17]
	v_mfma_f32_16x16x32_bf16 v[10:13], v[94:97], v[122:125], v[10:13]
	v_mfma_f32_16x16x32_bf16 v[6:9], v[192:195], v[110:113], v[6:9]
	v_mfma_f32_16x16x32_bf16 v[2:5], v[188:191], v[122:125], v[2:5]
	v_mfma_f32_16x16x32_bf16 v[130:133], v[74:77], v[110:113], v[30:33]
	v_mfma_f32_16x16x32_bf16 v[136:139], v[74:77], v[212:215], v[26:29]
	v_mfma_f32_16x16x32_bf16 v[140:143], v[184:187], v[110:113], v[14:17]
	v_mfma_f32_16x16x32_bf16 v[156:159], v[184:187], v[212:215], v[10:13]
	v_mfma_f32_16x16x32_bf16 v[184:187], v[192:195], v[212:215], v[2:5]
	s_setprio 0
	v_add_u32_e32 v26, 0x18000, v160
	s_barrier
	ds_read_b128 v[2:5], v26
	ds_read_b128 v[10:13], v26 offset:1024
	ds_read_b128 v[14:17], v26 offset:2048
	ds_read_b128 v[188:191], v26 offset:3072
	ds_read_b128 v[26:29], v134 offset:32768
	ds_read_b128 v[30:33], v134 offset:33792
	ds_read_b128 v[42:45], v134 offset:34816
	ds_read_b128 v[46:49], v134 offset:35840
	ds_read_b128 v[58:61], v134 offset:36864
	ds_read_b128 v[66:69], v134 offset:37888
	ds_read_b128 v[192:195], v134 offset:38912
	ds_read_b128 v[212:215], v134 offset:39936
	s_waitcnt vmcnt(2)
	s_barrier
; #define WAIT_V(n) asm volatile("s_waitcnt vmcnt(" #n ")" ::: "memory")
; #define WAIT_L(n) asm volatile("s_waitcnt lgkmcnt(" #n ")" ::: "memory")
; #define BAR __builtin_amdgcn_s_barrier()
; #define LDA8(b, h) _Pragma("unroll") for (int m = 0; m < 4; ++m) _Pragma("unroll") for (int k = 0; k < 2; ++k) \
;     At[m][k] = *(const bf16x8*)(SA_(shm, b, h) + abase + (m * 2 + k) * 1024)
; #define LDB8(dst, b, h) _Pragma("unroll") for (int n = 0; n < 2; ++n) _Pragma("unroll") for (int k = 0; k < 2; ++k) \
;     dst[n][k] = *(const bf16x8*)(SB_(shm, b, h) + bbase + (n * 2 + k) * 1024)
; #define MMA8(ai, bj, Bx) do { __builtin_amdgcn_s_setprio(1); \
;     _Pragma("unroll") for (int m = 0; m < 4; ++m) _Pragma("unroll") for (int n = 0; n < 2; ++n) _Pragma("unroll") for (int k = 0; k < 2; ++k) \
;       acc[ai][bj][m][n] = __builtin_amdgcn_mfma_f32_16x16x32_bf16(At[m][k], Bx[n][k], acc[ai][bj][m][n], 0, 0, 0); \
;     __builtin_amdgcn_s_setprio(0); } while (0)
; template <bool HS>
; __device__ __forceinline__ void gemm_tile8(const u16* __restrict__ Ap, const u16* __restrict__ Bp, int K,
;                                            f32x4 (&acc)[2][2][4][2], char* shm, const int tid, const float* hsr = nullptr) {
;     ...
;   { LDB8(B0, 1, 0); LDA8(1, 0); WAIT_V(2); BAR; WAIT_L(0); MMA8(0, 0, B0); BAR;
;     LDB8(B1, 1, 1); WAIT_V(0); BAR; WAIT_L(0); MMA8(0, 1, B1); BAR;
;     LDA8(1, 1); BAR; WAIT_L(0); MMA8(1, 0, B0); MMA8(1, 1, B1); BAR; }
;   if (wr == 0) BAR;
	s_waitcnt lgkmcnt(0)
	s_setprio 1
	s_waitcnt lgkmcnt(7)
	v_mfma_f32_16x16x32_bf16 v[74:77], v[26:29], v[2:5], v[126:129]
	s_waitcnt lgkmcnt(6)
	v_mfma_f32_16x16x32_bf16 v[122:125], v[30:33], v[10:13], v[74:77]
	v_mfma_f32_16x16x32_bf16 v[74:77], v[26:29], v[14:17], v[200:203]
	v_mfma_f32_16x16x32_bf16 v[126:129], v[30:33], v[188:191], v[74:77]
	s_waitcnt lgkmcnt(5)
	v_mfma_f32_16x16x32_bf16 v[74:77], v[42:45], v[2:5], v[118:121]
	s_waitcnt lgkmcnt(4)
	v_mfma_f32_16x16x32_bf16 v[106:109], v[46:49], v[10:13], v[74:77]
	v_mfma_f32_16x16x32_bf16 v[74:77], v[42:45], v[14:17], v[114:117]
	v_mfma_f32_16x16x32_bf16 v[110:113], v[46:49], v[188:191], v[74:77]
	s_waitcnt lgkmcnt(3)
	v_mfma_f32_16x16x32_bf16 v[74:77], v[58:61], v[2:5], v[204:207]
	s_waitcnt lgkmcnt(2)
	v_mfma_f32_16x16x32_bf16 v[90:93], v[66:69], v[10:13], v[74:77]
	v_mfma_f32_16x16x32_bf16 v[74:77], v[58:61], v[14:17], v[208:211]
	v_mfma_f32_16x16x32_bf16 v[94:97], v[66:69], v[188:191], v[74:77]
	s_waitcnt lgkmcnt(1)
	v_mfma_f32_16x16x32_bf16 v[74:77], v[192:195], v[2:5], v[102:105]
	v_mfma_f32_16x16x32_bf16 v[78:81], v[192:195], v[14:17], v[98:101]
	s_waitcnt lgkmcnt(0)
	v_mfma_f32_16x16x32_bf16 v[74:77], v[212:215], v[10:13], v[74:77]
	v_mfma_f32_16x16x32_bf16 v[78:81], v[212:215], v[188:191], v[78:81]
	s_setprio 0
	v_add_u32_e32 v98, 0x1c000, v160
	s_barrier
	ds_read_b128 v[200:203], v98
	ds_read_b128 v[204:207], v98 offset:1024
	ds_read_b128 v[208:211], v98 offset:2048
	ds_read_b128 v[224:227], v98 offset:3072
	s_waitcnt vmcnt(0)
	s_barrier
	s_waitcnt lgkmcnt(0)
	s_setprio 1
	s_waitcnt lgkmcnt(3)
	v_mfma_f32_16x16x32_bf16 v[98:101], v[26:29], v[200:203], v[220:223]
	s_waitcnt lgkmcnt(1)
	v_mfma_f32_16x16x32_bf16 v[26:29], v[26:29], v[208:211], v[164:167]
	s_waitcnt lgkmcnt(0)
	v_mfma_f32_16x16x32_bf16 v[118:121], v[30:33], v[224:227], v[26:29]
	v_mfma_f32_16x16x32_bf16 v[26:29], v[42:45], v[200:203], v[86:89]
	v_mfma_f32_16x16x32_bf16 v[114:117], v[30:33], v[204:207], v[98:101]
	v_mfma_f32_16x16x32_bf16 v[98:101], v[46:49], v[204:207], v[26:29]
	v_mfma_f32_16x16x32_bf16 v[26:29], v[42:45], v[208:211], v[82:85]
	v_mfma_f32_16x16x32_bf16 v[102:105], v[46:49], v[224:227], v[26:29]
	v_mfma_f32_16x16x32_bf16 v[26:29], v[58:61], v[200:203], v[168:171]
	v_mfma_f32_16x16x32_bf16 v[82:85], v[66:69], v[204:207], v[26:29]
	v_mfma_f32_16x16x32_bf16 v[26:29], v[58:61], v[208:211], v[172:175]
	v_mfma_f32_16x16x32_bf16 v[86:89], v[66:69], v[224:227], v[26:29]
	v_mfma_f32_16x16x32_bf16 v[26:29], v[192:195], v[200:203], v[70:73]
	v_mfma_f32_16x16x32_bf16 v[66:69], v[212:215], v[204:207], v[26:29]
	v_mfma_f32_16x16x32_bf16 v[26:29], v[192:195], v[208:211], v[180:183]
	v_mfma_f32_16x16x32_bf16 v[70:73], v[212:215], v[224:227], v[26:29]
	s_setprio 0
	s_barrier
	ds_read_b128 v[164:167], v134 offset:49152
	ds_read_b128 v[168:171], v134 offset:50176
	ds_read_b128 v[172:175], v134 offset:51200
	ds_read_b128 v[180:183], v134 offset:52224
	ds_read_b128 v[192:195], v134 offset:53248
	ds_read_b128 v[212:215], v134 offset:54272
	ds_read_b128 v[220:223], v134 offset:55296
	ds_read_b128 v[228:231], v134 offset:56320
	s_barrier
	s_waitcnt lgkmcnt(0)
	s_setprio 1
	s_waitcnt lgkmcnt(7)
	v_mfma_f32_16x16x32_bf16 v[26:29], v[164:167], v[2:5], v[62:65]
	s_waitcnt lgkmcnt(6)
	v_mfma_f32_16x16x32_bf16 v[58:61], v[168:171], v[10:13], v[26:29]
	v_mfma_f32_16x16x32_bf16 v[26:29], v[164:167], v[14:17], v[196:199]
	v_mfma_f32_16x16x32_bf16 v[62:65], v[168:171], v[188:191], v[26:29]
	s_waitcnt lgkmcnt(5)
	v_mfma_f32_16x16x32_bf16 v[26:29], v[172:175], v[2:5], v[54:57]
	s_waitcnt lgkmcnt(4)
	v_mfma_f32_16x16x32_bf16 v[42:45], v[180:183], v[10:13], v[26:29]
	v_mfma_f32_16x16x32_bf16 v[26:29], v[172:175], v[14:17], v[50:53]
	v_mfma_f32_16x16x32_bf16 v[46:49], v[180:183], v[188:191], v[26:29]
	s_waitcnt lgkmcnt(3)
	v_mfma_f32_16x16x32_bf16 v[26:29], v[192:195], v[2:5], v[242:245]
	s_waitcnt lgkmcnt(1)
	v_mfma_f32_16x16x32_bf16 v[2:5], v[220:223], v[2:5], v[38:41]
	v_mfma_f32_16x16x32_bf16 v[26:29], v[212:215], v[10:13], v[26:29]
	v_mfma_f32_16x16x32_bf16 v[30:33], v[192:195], v[14:17], v[246:249]
	s_waitcnt lgkmcnt(0)
	v_mfma_f32_16x16x32_bf16 v[10:13], v[228:231], v[10:13], v[2:5]
	v_mfma_f32_16x16x32_bf16 v[2:5], v[220:223], v[14:17], v[34:37]
	v_mfma_f32_16x16x32_bf16 v[30:33], v[212:215], v[188:191], v[30:33]
	v_mfma_f32_16x16x32_bf16 v[14:17], v[228:231], v[188:191], v[2:5]
	s_setprio 0
	s_setprio 1
	v_mfma_f32_16x16x32_bf16 v[2:5], v[164:167], v[200:203], v[130:133]
	v_mfma_f32_16x16x32_bf16 v[50:53], v[168:171], v[204:207], v[2:5]
	v_mfma_f32_16x16x32_bf16 v[2:5], v[164:167], v[208:211], v[136:139]
	v_mfma_f32_16x16x32_bf16 v[54:57], v[168:171], v[224:227], v[2:5]
	v_mfma_f32_16x16x32_bf16 v[2:5], v[172:175], v[200:203], v[22:25]
	v_mfma_f32_16x16x32_bf16 v[34:37], v[180:183], v[204:207], v[2:5]
	v_mfma_f32_16x16x32_bf16 v[2:5], v[172:175], v[208:211], v[18:21]
	v_mfma_f32_16x16x32_bf16 v[38:41], v[180:183], v[224:227], v[2:5]
	v_mfma_f32_16x16x32_bf16 v[2:5], v[192:195], v[200:203], v[140:143]
	v_mfma_f32_16x16x32_bf16 v[18:21], v[212:215], v[204:207], v[2:5]
	v_mfma_f32_16x16x32_bf16 v[2:5], v[192:195], v[208:211], v[156:159]
	v_mfma_f32_16x16x32_bf16 v[22:25], v[212:215], v[224:227], v[2:5]
	v_mfma_f32_16x16x32_bf16 v[2:5], v[220:223], v[200:203], v[6:9]
	v_mfma_f32_16x16x32_bf16 v[6:9], v[220:223], v[208:211], v[184:187]
	v_mfma_f32_16x16x32_bf16 v[2:5], v[228:231], v[204:207], v[2:5]
	v_mfma_f32_16x16x32_bf16 v[6:9], v[228:231], v[224:227], v[6:9]
	s_setprio 0
	s_movk_i32 s0, 0x100
	v_cmp_gt_u32_e32 vcc, s0, v0
	s_barrier
	s_and_saveexec_b64 s[0:1], vcc
	s_cbranch_execz .LBB0_654
	s_barrier

; #define SCHED __builtin_amdgcn_sched_barrier(0)
; __device__ __forceinline__ float silu_f(float g) {
;   return g * __builtin_amdgcn_rcpf(1.0f + __builtin_amdgcn_exp2f(-1.4426950408889634f * g));
; }
; template <int EPI, bool HS = false>
; __device__ __forceinline__ void gemm_phase(const Params& p, const GemmCfg& g, char* shm, const int wave_s) {
;     ...
;     } else if constexpr (EPI == EPI_SWIGLU) {
;       u16* ot = g.o16 + (size_t)orow0 * DFF + pn * 128;
;       const unsigned tb = (unsigned)((wr * 64 + fq * 4) * DFF + wc * 16 + fr);
; #pragma unroll
;       for (int ai = 0; ai < 2; ++ai)
; #pragma unroll
;         for (int m = 0; m < 4; ++m) {
;           const f32x4 r4 = *(const f32x4*)(rsw + ai * 128 + m * 16);
; #pragma unroll
;           for (int j = 0; j < 4; ++j)
; #pragma unroll
;             for (int bj = 0; bj < 2; ++bj) {
;               float gv = r4[j] * acc[ai][bj][m][0][j] + swv[bj][0], uv = r4[j] * acc[ai][bj][m][1][j] + swv[bj][1];
;               ot[tb + (ai * 128 + m * 16 + j) * DFF + bj * 64] = f2bf(silu_f(gv) * uv);
;             }
;           SCHED;
;         }
.LBB0_853:
	s_mov_b32 s5, -1
	v_mbcnt_lo_u32_b32 v0, s5, 0
	v_mbcnt_hi_u32_b32 v0, s5, v0
	s_mul_hi_i32 s3, s4, 0x1600
	s_mulk_i32 s4, 0x1600
	s_add_u32 s4, s90, s4
	s_addc_u32 s5, s91, s3
	s_lshl_b32 s2, s2, 7
	s_ashr_i32 s3, s2, 31
	s_lshl_b64 s[2:3], s[2:3], 1
	s_add_u32 s2, s4, s2
	s_addc_u32 s3, s5, s3
	v_and_b32_e32 v130, 15, v0
	v_lshrrev_b32_e32 v131, 4, v0
	v_lshrrev_b32_e32 v132, 2, v0
	v_and_b32_e32 v133, 3, v0
	s_andn2_b32 s4, s82, 3
	s_lshl_b32 s4, s4, 6
	v_lshl_add_u32 v142, v131, 4, s9
	v_add_u32_e32 v142, s4, v142
	ds_read_b128 v[146:149], v142
	ds_read_b128 v[150:153], v142 offset:64
	ds_read_b128 v[154:157], v142 offset:128
	ds_read_b128 v[158:161], v142 offset:192
	ds_read_b128 v[162:165], v142 offset:512
	ds_read_b128 v[166:169], v142 offset:576
	ds_read_b128 v[170:173], v142 offset:640
	ds_read_b128 v[174:177], v142 offset:704
	s_mul_i32 s4, s4, 0x580
	v_mul_u32_u24_e32 v145, 0x1600, v132
	v_add_u32_e32 v145, s4, v145
	s_and_b32 s5, s82, 3
	s_lshl_b32 s5, s5, 6
	v_lshl_add_u32 v145, v133, 4, v145
	v_add_u32_e32 v145, s5, v145
	s_lshl_b32 s5, s82, 10
	s_add_i32 s5, s5, 0x20800
	v_lshlrev_b32_e32 v143, 8, v131
	v_lshl_add_u32 v143, v130, 2, v143
	v_add_u32_e32 v143, s5, v143
	v_lshl_add_u32 v144, v0, 4, s5
	s_waitcnt lgkmcnt(0)
	v_fma_f32 v126, v126, v146, v140
	v_fma_f32 v94, v94, v146, v138
	v_mul_f32_e32 v188, 0xbfb8aa3b, v126
	v_mul_f32_e32 v189, 0xbfb8aa3b, v94
	v_exp_f32_e32 v188, v188
	v_exp_f32_e32 v189, v189
	v_fma_f32 v122, v122, v146, v141
	v_add_f32_e32 v188, 1.0, v188
	v_add_f32_e32 v189, 1.0, v189
	v_rcp_f32_e32 v188, v188
	v_rcp_f32_e32 v189, v189
	v_fma_f32 v90, v90, v146, v139
	v_mul_f32_e32 v126, v126, v188
	v_mul_f32_e32 v94, v94, v189
	v_mul_f32_e32 v126, v122, v126
	v_mul_f32_e32 v94, v90, v94
	v_cvt_pk_bf16_f32 v190, v126, v94
	v_fma_f32 v127, v127, v147, v140
	v_fma_f32 v95, v95, v147, v138
	v_mul_f32_e32 v188, 0xbfb8aa3b, v127
	v_mul_f32_e32 v189, 0xbfb8aa3b, v95
	v_exp_f32_e32 v188, v188
	v_exp_f32_e32 v189, v189
	v_fma_f32 v123, v123, v147, v141
	v_add_f32_e32 v188, 1.0, v188
	v_add_f32_e32 v189, 1.0, v189
	v_rcp_f32_e32 v188, v188
	v_rcp_f32_e32 v189, v189
	v_fma_f32 v91, v91, v147, v139
	v_mul_f32_e32 v127, v127, v188
	v_mul_f32_e32 v95, v95, v189
	v_mul_f32_e32 v127, v123, v127
	v_mul_f32_e32 v95, v91, v95
	v_cvt_pk_bf16_f32 v191, v127, v95
	v_fma_f32 v128, v128, v148, v140
	v_fma_f32 v96, v96, v148, v138
	v_mul_f32_e32 v188, 0xbfb8aa3b, v128
	v_mul_f32_e32 v189, 0xbfb8aa3b, v96
	v_exp_f32_e32 v188, v188
	v_exp_f32_e32 v189, v189
	v_fma_f32 v124, v124, v148, v141
	v_add_f32_e32 v188, 1.0, v188
	v_add_f32_e32 v189, 1.0, v189
	v_rcp_f32_e32 v188, v188
	v_rcp_f32_e32 v189, v189
	v_fma_f32 v92, v92, v148, v139
	v_mul_f32_e32 v128, v128, v188
	v_mul_f32_e32 v96, v96, v189
	v_mul_f32_e32 v128, v124, v128
	v_mul_f32_e32 v96, v92, v96
	v_cvt_pk_bf16_f32 v192, v128, v96
	v_fma_f32 v129, v129, v149, v140
	v_fma_f32 v97, v97, v149, v138
	v_mul_f32_e32 v188, 0xbfb8aa3b, v129
	v_mul_f32_e32 v189, 0xbfb8aa3b, v97
	v_exp_f32_e32 v188, v188
	v_exp_f32_e32 v189, v189
	v_fma_f32 v125, v125, v149, v141
	v_add_f32_e32 v188, 1.0, v188
	v_add_f32_e32 v189, 1.0, v189
	v_rcp_f32_e32 v188, v188
	v_rcp_f32_e32 v189, v189
	v_fma_f32 v93, v93, v149, v139
	v_mul_f32_e32 v129, v129, v188
	v_mul_f32_e32 v97, v97, v189
	v_mul_f32_e32 v129, v125, v129
	v_mul_f32_e32 v97, v93, v97
	v_cvt_pk_bf16_f32 v193, v129, v97
	s_waitcnt lgkmcnt(0)
	ds_write_b32 v143, v190
	ds_write_b32 v143, v191 offset:64
	ds_write_b32 v143, v192 offset:128
	ds_write_b32 v143, v193 offset:192
	ds_read_b128 v[180:183], v144
	v_fma_f32 v118, v118, v150, v140
	v_fma_f32 v86, v86, v150, v138
	v_mul_f32_e32 v188, 0xbfb8aa3b, v118
	v_mul_f32_e32 v189, 0xbfb8aa3b, v86
	v_exp_f32_e32 v188, v188
	v_exp_f32_e32 v189, v189
	v_fma_f32 v114, v114, v150, v141
	v_add_f32_e32 v188, 1.0, v188
	v_add_f32_e32 v189, 1.0, v189
	v_rcp_f32_e32 v188, v188
	v_rcp_f32_e32 v189, v189
	v_fma_f32 v82, v82, v150, v139
	v_mul_f32_e32 v118, v118, v188
	v_mul_f32_e32 v86, v86, v189
	v_mul_f32_e32 v118, v114, v118
	v_mul_f32_e32 v86, v82, v86
	v_cvt_pk_bf16_f32 v190, v118, v86
	v_fma_f32 v119, v119, v151, v140
	v_fma_f32 v87, v87, v151, v138
	v_mul_f32_e32 v188, 0xbfb8aa3b, v119
	v_mul_f32_e32 v189, 0xbfb8aa3b, v87
	v_exp_f32_e32 v188, v188
	v_exp_f32_e32 v189, v189
	v_fma_f32 v115, v115, v151, v141
	v_add_f32_e32 v188, 1.0, v188
	v_add_f32_e32 v189, 1.0, v189
	v_rcp_f32_e32 v188, v188
	v_rcp_f32_e32 v189, v189
	v_fma_f32 v83, v83, v151, v139
	v_mul_f32_e32 v119, v119, v188
	v_mul_f32_e32 v87, v87, v189
	v_mul_f32_e32 v119, v115, v119
	v_mul_f32_e32 v87, v83, v87
	v_cvt_pk_bf16_f32 v191, v119, v87
	v_fma_f32 v120, v120, v152, v140
	v_fma_f32 v88, v88, v152, v138
	v_mul_f32_e32 v188, 0xbfb8aa3b, v120
	v_mul_f32_e32 v189, 0xbfb8aa3b, v88
	v_exp_f32_e32 v188, v188
	v_exp_f32_e32 v189, v189
	v_fma_f32 v116, v116, v152, v141
	v_add_f32_e32 v188, 1.0, v188
	v_add_f32_e32 v189, 1.0, v189
	v_rcp_f32_e32 v188, v188
	v_rcp_f32_e32 v189, v189
	v_fma_f32 v84, v84, v152, v139
	v_mul_f32_e32 v120, v120, v188
	v_mul_f32_e32 v88, v88, v189
	v_mul_f32_e32 v120, v116, v120
	v_mul_f32_e32 v88, v84, v88
	v_cvt_pk_bf16_f32 v192, v120, v88
	v_fma_f32 v121, v121, v153, v140
	v_fma_f32 v89, v89, v153, v138
	v_mul_f32_e32 v188, 0xbfb8aa3b, v121
	v_mul_f32_e32 v189, 0xbfb8aa3b, v89
	v_exp_f32_e32 v188, v188
	v_exp_f32_e32 v189, v189
	v_fma_f32 v117, v117, v153, v141
	v_add_f32_e32 v188, 1.0, v188
	v_add_f32_e32 v189, 1.0, v189
	v_rcp_f32_e32 v188, v188
	v_rcp_f32_e32 v189, v189
	v_fma_f32 v85, v85, v153, v139
	v_mul_f32_e32 v121, v121, v188
	v_mul_f32_e32 v89, v89, v189
	v_mul_f32_e32 v121, v117, v121
	v_mul_f32_e32 v89, v85, v89
	v_cvt_pk_bf16_f32 v193, v121, v89
	s_waitcnt lgkmcnt(0)
; #define SCHED __builtin_amdgcn_sched_barrier(0)
; template <int EPI, bool HS = false>
; __device__ __forceinline__ void gemm_phase(const Params& p, const GemmCfg& g, char* shm, const int wave_s) {
;     ...
;     } else if constexpr (EPI == EPI_SWIGLU) {
;       u16* ot = g.o16 + (size_t)orow0 * DFF + pn * 128;
;       const unsigned tb = (unsigned)((wr * 64 + fq * 4) * DFF + wc * 16 + fr);
; #pragma unroll
;       for (int ai = 0; ai < 2; ++ai)
; #pragma unroll
;         for (int m = 0; m < 4; ++m) {
;           const f32x4 r4 = *(const f32x4*)(rsw + ai * 128 + m * 16);
; #pragma unroll
;           for (int j = 0; j < 4; ++j)
; #pragma unroll
;             for (int bj = 0; bj < 2; ++bj) {
;               float gv = r4[j] * acc[ai][bj][m][0][j] + swv[bj][0], uv = r4[j] * acc[ai][bj][m][1][j] + swv[bj][1];
;               ot[tb + (ai * 128 + m * 16 + j) * DFF + bj * 64] = f2bf(silu_f(gv) * uv);
;             }
;           SCHED;
;         }
	global_store_dwordx4 v145, v[180:183], s[2:3]
	s_add_u32 s2, s2, 0x16000
	s_addc_u32 s3, s3, 0
	ds_write_b32 v143, v190
	ds_write_b32 v143, v191 offset:64
	ds_write_b32 v143, v192 offset:128
	ds_write_b32 v143, v193 offset:192
	ds_read_b128 v[184:187], v144
	v_fma_f32 v110, v110, v154, v140
	v_fma_f32 v78, v78, v154, v138
	v_mul_f32_e32 v188, 0xbfb8aa3b, v110
	v_mul_f32_e32 v189, 0xbfb8aa3b, v78
	v_exp_f32_e32 v188, v188
	v_exp_f32_e32 v189, v189
	v_fma_f32 v106, v106, v154, v141
	v_add_f32_e32 v188, 1.0, v188
	v_add_f32_e32 v189, 1.0, v189
	v_rcp_f32_e32 v188, v188
	v_rcp_f32_e32 v189, v189
	v_fma_f32 v74, v74, v154, v139
	v_mul_f32_e32 v110, v110, v188
	v_mul_f32_e32 v78, v78, v189
	v_mul_f32_e32 v110, v106, v110
	v_mul_f32_e32 v78, v74, v78
	v_cvt_pk_bf16_f32 v190, v110, v78
	v_fma_f32 v111, v111, v155, v140
	v_fma_f32 v79, v79, v155, v138
	v_mul_f32_e32 v188, 0xbfb8aa3b, v111
	v_mul_f32_e32 v189, 0xbfb8aa3b, v79
	v_exp_f32_e32 v188, v188
	v_exp_f32_e32 v189, v189
	v_fma_f32 v107, v107, v155, v141
	v_add_f32_e32 v188, 1.0, v188
	v_add_f32_e32 v189, 1.0, v189
	v_rcp_f32_e32 v188, v188
	v_rcp_f32_e32 v189, v189
	v_fma_f32 v75, v75, v155, v139
	v_mul_f32_e32 v111, v111, v188
	v_mul_f32_e32 v79, v79, v189
	v_mul_f32_e32 v111, v107, v111
	v_mul_f32_e32 v79, v75, v79
	v_cvt_pk_bf16_f32 v191, v111, v79
	v_fma_f32 v112, v112, v156, v140
	v_fma_f32 v80, v80, v156, v138
	v_mul_f32_e32 v188, 0xbfb8aa3b, v112
	v_mul_f32_e32 v189, 0xbfb8aa3b, v80
	v_exp_f32_e32 v188, v188
	v_exp_f32_e32 v189, v189
	v_fma_f32 v108, v108, v156, v141
	v_add_f32_e32 v188, 1.0, v188
	v_add_f32_e32 v189, 1.0, v189
	v_rcp_f32_e32 v188, v188
	v_rcp_f32_e32 v189, v189
	v_fma_f32 v76, v76, v156, v139
	v_mul_f32_e32 v112, v112, v188
	v_mul_f32_e32 v80, v80, v189
	v_mul_f32_e32 v112, v108, v112
	v_mul_f32_e32 v80, v76, v80
	v_cvt_pk_bf16_f32 v192, v112, v80
	v_fma_f32 v113, v113, v157, v140
	v_fma_f32 v81, v81, v157, v138
	v_mul_f32_e32 v188, 0xbfb8aa3b, v113
	v_mul_f32_e32 v189, 0xbfb8aa3b, v81
	v_exp_f32_e32 v188, v188
	v_exp_f32_e32 v189, v189
	v_fma_f32 v109, v109, v157, v141
	v_add_f32_e32 v188, 1.0, v188
	v_add_f32_e32 v189, 1.0, v189
	v_rcp_f32_e32 v188, v188
	v_rcp_f32_e32 v189, v189
	v_fma_f32 v77, v77, v157, v139
	v_mul_f32_e32 v113, v113, v188
	v_mul_f32_e32 v81, v81, v189
	v_mul_f32_e32 v113, v109, v113
	v_mul_f32_e32 v81, v77, v81
	v_cvt_pk_bf16_f32 v193, v113, v81
	s_waitcnt lgkmcnt(0)
	global_store_dwordx4 v145, v[184:187], s[2:3]
	s_add_u32 s2, s2, 0x16000
	s_addc_u32 s3, s3, 0
	ds_write_b32 v143, v190
	ds_write_b32 v143, v191 offset:64
	ds_write_b32 v143, v192 offset:128
	ds_write_b32 v143, v193 offset:192
	ds_read_b128 v[180:183], v144
	v_fma_f32 v102, v102, v158, v140
	v_fma_f32 v70, v70, v158, v138
	v_mul_f32_e32 v188, 0xbfb8aa3b, v102
	v_mul_f32_e32 v189, 0xbfb8aa3b, v70
	v_exp_f32_e32 v188, v188
	v_exp_f32_e32 v189, v189
	v_fma_f32 v98, v98, v158, v141
	v_add_f32_e32 v188, 1.0, v188
	v_add_f32_e32 v189, 1.0, v189
	v_rcp_f32_e32 v188, v188
	v_rcp_f32_e32 v189, v189
	v_fma_f32 v66, v66, v158, v139
	v_mul_f32_e32 v102, v102, v188
	v_mul_f32_e32 v70, v70, v189
	v_mul_f32_e32 v102, v98, v102
	v_mul_f32_e32 v70, v66, v70
	v_cvt_pk_bf16_f32 v190, v102, v70
	v_fma_f32 v103, v103, v159, v140
	v_fma_f32 v71, v71, v159, v138
	v_mul_f32_e32 v188, 0xbfb8aa3b, v103
	v_mul_f32_e32 v189, 0xbfb8aa3b, v71
	v_exp_f32_e32 v188, v188
	v_exp_f32_e32 v189, v189
	v_fma_f32 v99, v99, v159, v141
	v_add_f32_e32 v188, 1.0, v188
	v_add_f32_e32 v189, 1.0, v189
	v_rcp_f32_e32 v188, v188
	v_rcp_f32_e32 v189, v189
	v_fma_f32 v67, v67, v159, v139
	v_mul_f32_e32 v103, v103, v188
	v_mul_f32_e32 v71, v71, v189
	v_mul_f32_e32 v103, v99, v103
	v_mul_f32_e32 v71, v67, v71
	v_cvt_pk_bf16_f32 v191, v103, v71
	v_fma_f32 v104, v104, v160, v140
	v_fma_f32 v72, v72, v160, v138
	v_mul_f32_e32 v188, 0xbfb8aa3b, v104
	v_mul_f32_e32 v189, 0xbfb8aa3b, v72
	v_exp_f32_e32 v188, v188
	v_exp_f32_e32 v189, v189
	v_fma_f32 v100, v100, v160, v141
	v_add_f32_e32 v188, 1.0, v188
	v_add_f32_e32 v189, 1.0, v189
	v_rcp_f32_e32 v188, v188
	v_rcp_f32_e32 v189, v189
	v_fma_f32 v68, v68, v160, v139
	v_mul_f32_e32 v104, v104, v188
	v_mul_f32_e32 v72, v72, v189
	v_mul_f32_e32 v104, v100, v104
	v_mul_f32_e32 v72, v68, v72
	v_cvt_pk_bf16_f32 v192, v104, v72
	v_fma_f32 v105, v105, v161, v140
	v_fma_f32 v73, v73, v161, v138
	v_mul_f32_e32 v188, 0xbfb8aa3b, v105
	v_mul_f32_e32 v189, 0xbfb8aa3b, v73
	v_exp_f32_e32 v188, v188
	v_exp_f32_e32 v189, v189
	v_fma_f32 v101, v101, v161, v141
	v_add_f32_e32 v188, 1.0, v188
	v_add_f32_e32 v189, 1.0, v189
	v_rcp_f32_e32 v188, v188
	v_rcp_f32_e32 v189, v189
	v_fma_f32 v69, v69, v161, v139
	v_mul_f32_e32 v105, v105, v188
	v_mul_f32_e32 v73, v73, v189
	v_mul_f32_e32 v105, v101, v105
	v_mul_f32_e32 v73, v69, v73
	v_cvt_pk_bf16_f32 v193, v105, v73
	s_waitcnt lgkmcnt(0)
; #define SCHED __builtin_amdgcn_sched_barrier(0)
; template <int EPI, bool HS = false>
; __device__ __forceinline__ void gemm_phase(const Params& p, const GemmCfg& g, char* shm, const int wave_s) {
;     ...
;     } else if constexpr (EPI == EPI_SWIGLU) {
;       u16* ot = g.o16 + (size_t)orow0 * DFF + pn * 128;
;       const unsigned tb = (unsigned)((wr * 64 + fq * 4) * DFF + wc * 16 + fr);
; #pragma unroll
;       for (int ai = 0; ai < 2; ++ai)
; #pragma unroll
;         for (int m = 0; m < 4; ++m) {
;           const f32x4 r4 = *(const f32x4*)(rsw + ai * 128 + m * 16);
; #pragma unroll
;           for (int j = 0; j < 4; ++j)
; #pragma unroll
;             for (int bj = 0; bj < 2; ++bj) {
;               float gv = r4[j] * acc[ai][bj][m][0][j] + swv[bj][0], uv = r4[j] * acc[ai][bj][m][1][j] + swv[bj][1];
;               ot[tb + (ai * 128 + m * 16 + j) * DFF + bj * 64] = f2bf(silu_f(gv) * uv);
;             }
;           SCHED;
;         }
	global_store_dwordx4 v145, v[180:183], s[2:3]
	s_add_u32 s2, s2, 0x16000
	s_addc_u32 s3, s3, 0
	ds_write_b32 v143, v190
	ds_write_b32 v143, v191 offset:64
	ds_write_b32 v143, v192 offset:128
	ds_write_b32 v143, v193 offset:192
	ds_read_b128 v[184:187], v144
	v_fma_f32 v62, v62, v162, v140
	v_fma_f32 v30, v30, v162, v138
	v_mul_f32_e32 v188, 0xbfb8aa3b, v62
	v_mul_f32_e32 v189, 0xbfb8aa3b, v30
	v_exp_f32_e32 v188, v188
	v_exp_f32_e32 v189, v189
	v_fma_f32 v58, v58, v162, v141
	v_add_f32_e32 v188, 1.0, v188
	v_add_f32_e32 v189, 1.0, v189
	v_rcp_f32_e32 v188, v188
	v_rcp_f32_e32 v189, v189
	v_fma_f32 v26, v26, v162, v139
	v_mul_f32_e32 v62, v62, v188
	v_mul_f32_e32 v30, v30, v189
	v_mul_f32_e32 v62, v58, v62
	v_mul_f32_e32 v30, v26, v30
	v_cvt_pk_bf16_f32 v190, v62, v30
	v_fma_f32 v63, v63, v163, v140
	v_fma_f32 v31, v31, v163, v138
	v_mul_f32_e32 v188, 0xbfb8aa3b, v63
	v_mul_f32_e32 v189, 0xbfb8aa3b, v31
	v_exp_f32_e32 v188, v188
	v_exp_f32_e32 v189, v189
	v_fma_f32 v59, v59, v163, v141
	v_add_f32_e32 v188, 1.0, v188
	v_add_f32_e32 v189, 1.0, v189
	v_rcp_f32_e32 v188, v188
	v_rcp_f32_e32 v189, v189
	v_fma_f32 v27, v27, v163, v139
	v_mul_f32_e32 v63, v63, v188
	v_mul_f32_e32 v31, v31, v189
	v_mul_f32_e32 v63, v59, v63
	v_mul_f32_e32 v31, v27, v31
	v_cvt_pk_bf16_f32 v191, v63, v31
	v_fma_f32 v64, v64, v164, v140
	v_fma_f32 v32, v32, v164, v138
	v_mul_f32_e32 v188, 0xbfb8aa3b, v64
	v_mul_f32_e32 v189, 0xbfb8aa3b, v32
	v_exp_f32_e32 v188, v188
	v_exp_f32_e32 v189, v189
	v_fma_f32 v60, v60, v164, v141
	v_add_f32_e32 v188, 1.0, v188
	v_add_f32_e32 v189, 1.0, v189
	v_rcp_f32_e32 v188, v188
	v_rcp_f32_e32 v189, v189
	v_fma_f32 v28, v28, v164, v139
	v_mul_f32_e32 v64, v64, v188
	v_mul_f32_e32 v32, v32, v189
	v_mul_f32_e32 v64, v60, v64
	v_mul_f32_e32 v32, v28, v32
	v_cvt_pk_bf16_f32 v192, v64, v32
	v_fma_f32 v65, v65, v165, v140
	v_fma_f32 v33, v33, v165, v138
	v_mul_f32_e32 v188, 0xbfb8aa3b, v65
	v_mul_f32_e32 v189, 0xbfb8aa3b, v33
	v_exp_f32_e32 v188, v188
	v_exp_f32_e32 v189, v189
	v_fma_f32 v61, v61, v165, v141
	v_add_f32_e32 v188, 1.0, v188
	v_add_f32_e32 v189, 1.0, v189
	v_rcp_f32_e32 v188, v188
	v_rcp_f32_e32 v189, v189
	v_fma_f32 v29, v29, v165, v139
	v_mul_f32_e32 v65, v65, v188
	v_mul_f32_e32 v33, v33, v189
	v_mul_f32_e32 v65, v61, v65
	v_mul_f32_e32 v33, v29, v33
	v_cvt_pk_bf16_f32 v193, v65, v33
	s_waitcnt lgkmcnt(0)
	global_store_dwordx4 v145, v[184:187], s[2:3]
	s_add_u32 s2, s2, 0x6e000
	s_addc_u32 s3, s3, 0
	ds_write_b32 v143, v190
	ds_write_b32 v143, v191 offset:64
	ds_write_b32 v143, v192 offset:128
	ds_write_b32 v143, v193 offset:192
	ds_read_b128 v[180:183], v144
	v_fma_f32 v54, v54, v166, v140
	v_fma_f32 v22, v22, v166, v138
	v_mul_f32_e32 v188, 0xbfb8aa3b, v54
	v_mul_f32_e32 v189, 0xbfb8aa3b, v22
	v_exp_f32_e32 v188, v188
	v_exp_f32_e32 v189, v189
	v_fma_f32 v50, v50, v166, v141
	v_add_f32_e32 v188, 1.0, v188
	v_add_f32_e32 v189, 1.0, v189
	v_rcp_f32_e32 v188, v188
	v_rcp_f32_e32 v189, v189
	v_fma_f32 v18, v18, v166, v139
	v_mul_f32_e32 v54, v54, v188
	v_mul_f32_e32 v22, v22, v189
	v_mul_f32_e32 v54, v50, v54
	v_mul_f32_e32 v22, v18, v22
	v_cvt_pk_bf16_f32 v190, v54, v22
	v_fma_f32 v55, v55, v167, v140
	v_fma_f32 v23, v23, v167, v138
	v_mul_f32_e32 v188, 0xbfb8aa3b, v55
	v_mul_f32_e32 v189, 0xbfb8aa3b, v23
	v_exp_f32_e32 v188, v188
	v_exp_f32_e32 v189, v189
	v_fma_f32 v51, v51, v167, v141
	v_add_f32_e32 v188, 1.0, v188
	v_add_f32_e32 v189, 1.0, v189
	v_rcp_f32_e32 v188, v188
	v_rcp_f32_e32 v189, v189
	v_fma_f32 v19, v19, v167, v139
	v_mul_f32_e32 v55, v55, v188
	v_mul_f32_e32 v23, v23, v189
	v_mul_f32_e32 v55, v51, v55
	v_mul_f32_e32 v23, v19, v23
	v_cvt_pk_bf16_f32 v191, v55, v23
	v_fma_f32 v56, v56, v168, v140
	v_fma_f32 v24, v24, v168, v138
	v_mul_f32_e32 v188, 0xbfb8aa3b, v56
	v_mul_f32_e32 v189, 0xbfb8aa3b, v24
	v_exp_f32_e32 v188, v188
	v_exp_f32_e32 v189, v189
	v_fma_f32 v52, v52, v168, v141
	v_add_f32_e32 v188, 1.0, v188
	v_add_f32_e32 v189, 1.0, v189
	v_rcp_f32_e32 v188, v188
	v_rcp_f32_e32 v189, v189
	v_fma_f32 v20, v20, v168, v139
	v_mul_f32_e32 v56, v56, v188
	v_mul_f32_e32 v24, v24, v189
	v_mul_f32_e32 v56, v52, v56
	v_mul_f32_e32 v24, v20, v24
	v_cvt_pk_bf16_f32 v192, v56, v24
	v_fma_f32 v57, v57, v169, v140
	v_fma_f32 v25, v25, v169, v138
	v_mul_f32_e32 v188, 0xbfb8aa3b, v57
	v_mul_f32_e32 v189, 0xbfb8aa3b, v25
	v_exp_f32_e32 v188, v188
	v_exp_f32_e32 v189, v189
	v_fma_f32 v53, v53, v169, v141
	v_add_f32_e32 v188, 1.0, v188
	v_add_f32_e32 v189, 1.0, v189
	v_rcp_f32_e32 v188, v188
	v_rcp_f32_e32 v189, v189
	v_fma_f32 v21, v21, v169, v139
	v_mul_f32_e32 v57, v57, v188
	v_mul_f32_e32 v25, v25, v189
	v_mul_f32_e32 v57, v53, v57
	v_mul_f32_e32 v25, v21, v25
	v_cvt_pk_bf16_f32 v193, v57, v25
	s_waitcnt lgkmcnt(0)
; #define SCHED __builtin_amdgcn_sched_barrier(0)
; template <int EPI, bool HS = false>
; __device__ __forceinline__ void gemm_phase(const Params& p, const GemmCfg& g, char* shm, const int wave_s) {
;     ...
;     } else if constexpr (EPI == EPI_SWIGLU) {
;       u16* ot = g.o16 + (size_t)orow0 * DFF + pn * 128;
;       const unsigned tb = (unsigned)((wr * 64 + fq * 4) * DFF + wc * 16 + fr);
; #pragma unroll
;       for (int ai = 0; ai < 2; ++ai)
; #pragma unroll
;         for (int m = 0; m < 4; ++m) {
;           const f32x4 r4 = *(const f32x4*)(rsw + ai * 128 + m * 16);
; #pragma unroll
;           for (int j = 0; j < 4; ++j)
; #pragma unroll
;             for (int bj = 0; bj < 2; ++bj) {
;               float gv = r4[j] * acc[ai][bj][m][0][j] + swv[bj][0], uv = r4[j] * acc[ai][bj][m][1][j] + swv[bj][1];
;               ot[tb + (ai * 128 + m * 16 + j) * DFF + bj * 64] = f2bf(silu_f(gv) * uv);
;             }
;           SCHED;
;         }
	global_store_dwordx4 v145, v[180:183], s[2:3]
	s_add_u32 s2, s2, 0x16000
	s_addc_u32 s3, s3, 0
	ds_write_b32 v143, v190
	ds_write_b32 v143, v191 offset:64
	ds_write_b32 v143, v192 offset:128
	ds_write_b32 v143, v193 offset:192
	ds_read_b128 v[184:187], v144
	v_fma_f32 v46, v46, v170, v140
	v_fma_f32 v14, v14, v170, v138
	v_mul_f32_e32 v188, 0xbfb8aa3b, v46
	v_mul_f32_e32 v189, 0xbfb8aa3b, v14
	v_exp_f32_e32 v188, v188
	v_exp_f32_e32 v189, v189
	v_fma_f32 v42, v42, v170, v141
	v_add_f32_e32 v188, 1.0, v188
	v_add_f32_e32 v189, 1.0, v189
	v_rcp_f32_e32 v188, v188
	v_rcp_f32_e32 v189, v189
	v_fma_f32 v10, v10, v170, v139
	v_mul_f32_e32 v46, v46, v188
	v_mul_f32_e32 v14, v14, v189
	v_mul_f32_e32 v46, v42, v46
	v_mul_f32_e32 v14, v10, v14
	v_cvt_pk_bf16_f32 v190, v46, v14
	v_fma_f32 v47, v47, v171, v140
	v_fma_f32 v15, v15, v171, v138
	v_mul_f32_e32 v188, 0xbfb8aa3b, v47
	v_mul_f32_e32 v189, 0xbfb8aa3b, v15
	v_exp_f32_e32 v188, v188
	v_exp_f32_e32 v189, v189
	v_fma_f32 v43, v43, v171, v141
	v_add_f32_e32 v188, 1.0, v188
	v_add_f32_e32 v189, 1.0, v189
	v_rcp_f32_e32 v188, v188
	v_rcp_f32_e32 v189, v189
	v_fma_f32 v11, v11, v171, v139
	v_mul_f32_e32 v47, v47, v188
	v_mul_f32_e32 v15, v15, v189
	v_mul_f32_e32 v47, v43, v47
	v_mul_f32_e32 v15, v11, v15
	v_cvt_pk_bf16_f32 v191, v47, v15
	v_fma_f32 v48, v48, v172, v140
	v_fma_f32 v16, v16, v172, v138
	v_mul_f32_e32 v188, 0xbfb8aa3b, v48
	v_mul_f32_e32 v189, 0xbfb8aa3b, v16
	v_exp_f32_e32 v188, v188
	v_exp_f32_e32 v189, v189
	v_fma_f32 v44, v44, v172, v141
	v_add_f32_e32 v188, 1.0, v188
	v_add_f32_e32 v189, 1.0, v189
	v_rcp_f32_e32 v188, v188
	v_rcp_f32_e32 v189, v189
	v_fma_f32 v12, v12, v172, v139
	v_mul_f32_e32 v48, v48, v188
	v_mul_f32_e32 v16, v16, v189
	v_mul_f32_e32 v48, v44, v48
	v_mul_f32_e32 v16, v12, v16
	v_cvt_pk_bf16_f32 v192, v48, v16
	v_fma_f32 v49, v49, v173, v140
	v_fma_f32 v17, v17, v173, v138
	v_mul_f32_e32 v188, 0xbfb8aa3b, v49
	v_mul_f32_e32 v189, 0xbfb8aa3b, v17
	v_exp_f32_e32 v188, v188
	v_exp_f32_e32 v189, v189
	v_fma_f32 v45, v45, v173, v141
	v_add_f32_e32 v188, 1.0, v188
	v_add_f32_e32 v189, 1.0, v189
	v_rcp_f32_e32 v188, v188
	v_rcp_f32_e32 v189, v189
	v_fma_f32 v13, v13, v173, v139
	v_mul_f32_e32 v49, v49, v188
	v_mul_f32_e32 v17, v17, v189
	v_mul_f32_e32 v49, v45, v49
	v_mul_f32_e32 v17, v13, v17
	v_cvt_pk_bf16_f32 v193, v49, v17
	s_waitcnt lgkmcnt(0)
	global_store_dwordx4 v145, v[184:187], s[2:3]
	s_add_u32 s2, s2, 0x16000
	s_addc_u32 s3, s3, 0
	ds_write_b32 v143, v190
	ds_write_b32 v143, v191 offset:64
	ds_write_b32 v143, v192 offset:128
	ds_write_b32 v143, v193 offset:192
	ds_read_b128 v[180:183], v144
	v_fma_f32 v38, v38, v174, v140
	v_fma_f32 v6, v6, v174, v138
	v_mul_f32_e32 v188, 0xbfb8aa3b, v38
	v_mul_f32_e32 v189, 0xbfb8aa3b, v6
	v_exp_f32_e32 v188, v188
	v_exp_f32_e32 v189, v189
	v_fma_f32 v34, v34, v174, v141
	v_add_f32_e32 v188, 1.0, v188
	v_add_f32_e32 v189, 1.0, v189
	v_rcp_f32_e32 v188, v188
	v_rcp_f32_e32 v189, v189
	v_fma_f32 v2, v2, v174, v139
	v_mul_f32_e32 v38, v38, v188
	v_mul_f32_e32 v6, v6, v189
	v_mul_f32_e32 v38, v34, v38
	v_mul_f32_e32 v6, v2, v6
	v_cvt_pk_bf16_f32 v190, v38, v6
	v_fma_f32 v39, v39, v175, v140
	v_fma_f32 v7, v7, v175, v138
	v_mul_f32_e32 v188, 0xbfb8aa3b, v39
	v_mul_f32_e32 v189, 0xbfb8aa3b, v7
	v_exp_f32_e32 v188, v188
	v_exp_f32_e32 v189, v189
	v_fma_f32 v35, v35, v175, v141
	v_add_f32_e32 v188, 1.0, v188
	v_add_f32_e32 v189, 1.0, v189
	v_rcp_f32_e32 v188, v188
	v_rcp_f32_e32 v189, v189
	v_fma_f32 v3, v3, v175, v139
	v_mul_f32_e32 v39, v39, v188
	v_mul_f32_e32 v7, v7, v189
	v_mul_f32_e32 v39, v35, v39
	v_mul_f32_e32 v7, v3, v7
	v_cvt_pk_bf16_f32 v191, v39, v7
	v_fma_f32 v40, v40, v176, v140
	v_fma_f32 v8, v8, v176, v138
	v_mul_f32_e32 v188, 0xbfb8aa3b, v40
	v_mul_f32_e32 v189, 0xbfb8aa3b, v8
	v_exp_f32_e32 v188, v188
	v_exp_f32_e32 v189, v189
	v_fma_f32 v36, v36, v176, v141
	v_add_f32_e32 v188, 1.0, v188
	v_add_f32_e32 v189, 1.0, v189
	v_rcp_f32_e32 v188, v188
	v_rcp_f32_e32 v189, v189
	v_fma_f32 v4, v4, v176, v139
	v_mul_f32_e32 v40, v40, v188
	v_mul_f32_e32 v8, v8, v189
	v_mul_f32_e32 v40, v36, v40
	v_mul_f32_e32 v8, v4, v8
	v_cvt_pk_bf16_f32 v192, v40, v8
	v_fma_f32 v41, v41, v177, v140
	v_fma_f32 v9, v9, v177, v138
	v_mul_f32_e32 v188, 0xbfb8aa3b, v41
	v_mul_f32_e32 v189, 0xbfb8aa3b, v9
	v_exp_f32_e32 v188, v188
	v_exp_f32_e32 v189, v189
	v_fma_f32 v37, v37, v177, v141
	v_add_f32_e32 v188, 1.0, v188
	v_add_f32_e32 v189, 1.0, v189
	v_rcp_f32_e32 v188, v188
	v_rcp_f32_e32 v189, v189
	v_fma_f32 v5, v5, v177, v139
	v_mul_f32_e32 v41, v41, v188
	v_mul_f32_e32 v9, v9, v189
	v_mul_f32_e32 v41, v37, v41
	v_mul_f32_e32 v9, v5, v9
	v_cvt_pk_bf16_f32 v193, v41, v9
	s_waitcnt lgkmcnt(0)
	global_store_dwordx4 v145, v[180:183], s[2:3]
	s_add_u32 s2, s2, 0x16000
	s_addc_u32 s3, s3, 0
	ds_write_b32 v143, v190
	ds_write_b32 v143, v191 offset:64
	ds_write_b32 v143, v192 offset:128
	ds_write_b32 v143, v193 offset:192
	ds_read_b128 v[184:187], v144
	s_waitcnt lgkmcnt(0)
	global_store_dwordx4 v145, v[184:187], s[2:3]
	s_and_b64 vcc, exec, s[0:1]
	s_cbranch_vccnz .LBB0_864

; #define WAIT_V(n) asm volatile("s_waitcnt vmcnt(" #n ")" ::: "memory")
; #define WAIT_L(n) asm volatile("s_waitcnt lgkmcnt(" #n ")" ::: "memory")
; #define BAR __builtin_amdgcn_s_barrier()
; #define SCHED __builtin_amdgcn_sched_barrier(0)
; #define STG_A(b, h, kt) stage_half_s(lds0 + ((b) * 2 + (h)) * HT_B, ((h) ? A1 : Ap) + (kt) * BK, off0, off1)
; #define STG_B(b, h, kt) stage_half_s(lds0 + (4 + (b) * 2 + (h)) * HT_B, ((h) ? B1p : Bp) + (kt) * BK, off0, off1)
; #define STG_A(b, h, kt) stage_half_s(lds0 + ((b) * 2 + (h)) * HT_B, ((h) ? A1 : Ap) + (kt) * BK, off0, off1)
; #define STG_B(b, h, kt) stage_half_s(lds0 + (4 + (b) * 2 + (h)) * HT_B, ((h) ? B1p : Bp) + (kt) * BK, off0, off1)
; #define LDA8(b, h) _Pragma("unroll") for (int m = 0; m < 4; ++m) _Pragma("unroll") for (int k = 0; k < 2; ++k) \
;     At[m][k] = *(const bf16x8*)(SA_(shm, b, h) + abase + (m * 2 + k) * 1024)
; template <bool HS>
; __device__ __forceinline__ void gemm_tile8(const u16* __restrict__ Ap, const u16* __restrict__ Bp, int K,
;                                            f32x4 (&acc)[2][2][4][2], char* shm, const int tid, const float* hsr = nullptr) {
;   const int wid = tid >> 6, lane = tid & 63, wr = wid >> 2, wc = wid & 3, fr = lane & 15, fq = lane >> 4;
;   int r0, c0, r1, c1;
;   stage_rc(tid * 16, r0, c0);
;   stage_rc(tid * 16 + 8192, r1, c1);
;   const unsigned off0 = (unsigned)(r0 * K + c0) * 2u, off1 = (unsigned)(r1 * K + c1) * 2u;
;   const int wvoff = __builtin_amdgcn_readfirstlane(tid >> 6) * 1024;
;   const u16* A1 = Ap + (size_t)128 * K;
;   const u16* B1p = Bp + (size_t)128 * K;
; #pragma unroll
;   for (int a = 0; a < 2; ++a)
; #pragma unroll
;     for (int b = 0; b < 2; ++b)
; #pragma unroll
;       for (int m = 0; m < 4; ++m)
; #pragma unroll
;         for (int n = 0; n < 2; ++n) acc[a][b][m][n] = f32x4{0.f, 0.f, 0.f, 0.f};
;   const int abase = lds_byte(wr * 64 + fr, fq * 8), bbase = lds_byte(wc * 32 + fr, fq * 8);
;   bf16x8 At[4][2], B0[2][2], B1[2][2];
;   const unsigned lds0 = (unsigned)(size_t)(__attribute__((address_space(3))) char*)shm + (unsigned)wvoff;
;     ...
;   const int nt = K / BK;
;   WAIT_V(0);
;   if (wr == 1) BAR;
;   BAR;
;   BAR;
;     ...
;     LDB8(B0, 0, 0); SCHED; LDA8(0, 0); STG_A(1, 1, t + 1);
;     WAIT_L(8); BAR; WAIT_L(0); MMA8(0, 0, B0); BAR; SCHED;
;     LDB8(B1, 0, 1); STG_B(0, 0, t + 2);
;     BAR; WAIT_L(0); MMA8(0, 1, B1); BAR;
.LBB0_858:
	s_or_b64 exec, exec, s[0:1]
	v_bfe_i32 v6, v0, 27, 1
	v_lshlrev_b32_e32 v4, 4, v0
	v_lshrrev_b32_e32 v6, 22, v6
	v_add_u32_e32 v6, v4, v6
	v_and_b32_e32 v6, 0xfffffc00, v6
	v_ashrrev_i32_e32 v5, 31, v0
	v_sub_u32_e32 v6, v4, v6
	v_lshrrev_b32_e32 v5, 26, v5
	v_lshrrev_b32_e32 v7, 4, v6
	v_add_u32_e32 v5, v0, v5
	v_bitop3_b32 v7, v7, v6, 32 bitop3:0x6c
	v_ashrrev_i32_e32 v6, 31, v6
	v_ashrrev_i32_e32 v5, 6, v5
	v_lshrrev_b32_e32 v6, 26, v6
	v_lshlrev_b32_e32 v8, 3, v5
	v_add_u32_e32 v6, v7, v6
	v_and_b32_e32 v8, 0x1ffff0, v8
	v_ashrrev_i32_e32 v6, 6, v6
	v_add_u32_e32 v8, v6, v8
	v_mul_i32_i24_e32 v6, 64, v6
	v_add_u32_e32 v4, 0x2000, v4
	v_sub_u32_e32 v6, v7, v6
	v_ashrrev_i32_e32 v7, 31, v4
	v_lshrrev_b32_e32 v7, 22, v7
	v_add_u32_e32 v7, v4, v7
	v_ashrrev_i32_e32 v7, 10, v7
	v_mul_i32_i24_e32 v9, 0x400, v7
	v_sub_u32_e32 v4, v4, v9
	v_lshrrev_b32_e32 v9, 4, v4
	v_bitop3_b32 v4, v9, v4, 32 bitop3:0x6c
	v_ashrrev_i32_e32 v10, 31, v4
	v_lshrrev_b32_e32 v10, 26, v10
	v_add_u32_e32 v10, v4, v10
	v_lshlrev_b32_e32 v9, 3, v7
	v_lshrrev_b32_e32 v11, 6, v10
	v_and_b32_e32 v10, 0xc0, v10
	v_and_b32_e32 v9, 0x1ffff0, v9
	v_lshlrev_b32_e32 v7, 5, v7
	v_sub_u32_e32 v4, v4, v10
	s_ashr_i32 s5, s4, 31
	v_lshlrev_b32_e32 v5, 5, v5
	v_add_u32_e32 v9, v11, v9
	v_and_b32_e32 v7, 32, v7
	v_ashrrev_i16_sdwa v4, v178, sext(v4) dst_sel:DWORD dst_unused:UNUSED_PAD src0_sel:DWORD src1_sel:BYTE_0
	s_lshl_b64 s[0:1], s[4:5], 11
	v_and_b32_e32 v5, 32, v5
	v_ashrrev_i16_sdwa v6, v178, sext(v6) dst_sel:DWORD dst_unused:UNUSED_PAD src0_sel:DWORD src1_sel:BYTE_0
	v_bfe_i32 v4, v4, 0, 16
	v_lshl_or_b32 v7, v9, 10, v7
	s_add_u32 s5, s88, s0
	v_bfe_i32 v6, v6, 0, 16
	v_lshl_or_b32 v5, v8, 10, v5
	v_and_b32_e32 v8, 15, v0
	v_add_lshl_u32 v143, v7, v4, 1
	v_lshlrev_b32_e32 v7, 2, v0
	s_addc_u32 s6, s89, s1
	s_ashr_i32 s3, s2, 31
	v_add_lshl_u32 v144, v5, v6, 1
	v_and_b32_e32 v4, 48, v0
	v_lshlrev_b32_e32 v5, 6, v8
	v_and_b32_e32 v7, 32, v7
	s_lshl_b64 s[10:11], s[2:3], 19
	s_lshl_b32 s3, s7, 10
	v_or_b32_e32 v6, v5, v4
	v_bitop3_b32 v4, v5, v7, v4 bitop3:0x36
	v_lshlrev_b32_e32 v2, 12, v2
	s_movk_i32 s7, 0x3000
	v_lshl_add_u64 v[130:131], v[134:135], 0, s[10:11]
	s_mov_b64 s[10:11], 0x40000
	v_and_or_b32 v145, v2, s7, v4
	s_add_i32 s7, s3, 0
	v_lshl_add_u64 v[132:133], v[130:131], 0, s[10:11]
	s_add_u32 s10, s5, 0x40100
	v_lshlrev_b32_e32 v3, 13, v3
	s_addc_u32 s11, s6, 0
	v_readlane_b32 s12, v254, 34
	v_bitop3_b32 v3, v6, v3, v7 bitop3:0xde
	s_add_u32 s12, s12, s0
	v_readlane_b32 s0, v254, 35
	v_mov_b32_e32 v2, 0
	s_addc_u32 s13, s0, s1
	s_mov_b32 s14, -2
	s_mov_b64 s[0:1], 0
	v_add_u32_e32 v142, 0, v3
	s_waitcnt lgkmcnt(0)
	v_readfirstlane_b32 s20, v130
	v_readfirstlane_b32 s21, v131
	v_readfirstlane_b32 s22, v132
	v_readfirstlane_b32 s23, v133
	s_mov_b32 s16, s5
	s_mov_b32 s17, s6
	s_mov_b32 s18, s12
	s_mov_b32 s19, s13
	s_barrier
	s_barrier
	v_add_u32_e32 v158, 0x10000, v145
	ds_read_b128 v[146:149], v158
	ds_read_b128 v[150:153], v158 offset:1024
	ds_read_b128 v[154:157], v158 offset:2048
	ds_read_b128 v[158:161], v158 offset:3072
	ds_read_b128 v[162:165], v142
	ds_read_b128 v[166:169], v142 offset:1024
	ds_read_b128 v[170:173], v142 offset:2048
	ds_read_b128 v[174:177], v142 offset:3072
	ds_read_b128 v[180:183], v142 offset:4096
	ds_read_b128 v[184:187], v142 offset:5120
	ds_read_b128 v[188:191], v142 offset:6144
	ds_read_b128 v[192:195], v142 offset:7168
	v_add_u32_e32 v208, 0x14000, v145
	ds_read_b128 v[196:199], v208
	ds_read_b128 v[200:203], v208 offset:1024
	ds_read_b128 v[204:207], v208 offset:2048
	ds_read_b128 v[208:211], v208 offset:3072
	s_add_u32 s0, s18, 0x80
	s_addc_u32 s1, s19, 0
	s_add_i32 s3, s7, 0xc000
	s_mov_b32 m0, s3
	s_nop 0
	global_load_lds_dwordx4 v144, s[0:1]
	s_add_i32 s3, s7, 0xe000
	s_mov_b32 m0, s3
	s_nop 0
	global_load_lds_dwordx4 v143, s[0:1]
	s_waitcnt vmcnt(8) lgkmcnt(0)
	s_barrier
	s_setprio 1
	v_mfma_f32_16x16x32_bf16 v[126:129], v[162:165], v[146:149], 0
	v_mfma_f32_16x16x32_bf16 v[122:125], v[162:165], v[154:157], 0
	v_mfma_f32_16x16x32_bf16 v[118:121], v[170:173], v[146:149], 0
	v_mfma_f32_16x16x32_bf16 v[114:117], v[170:173], v[154:157], 0
	v_mfma_f32_16x16x32_bf16 v[110:113], v[180:183], v[146:149], 0
	v_mfma_f32_16x16x32_bf16 v[106:109], v[180:183], v[154:157], 0
	v_mfma_f32_16x16x32_bf16 v[102:105], v[188:191], v[146:149], 0
	v_mfma_f32_16x16x32_bf16 v[98:101], v[188:191], v[154:157], 0
	v_mfma_f32_16x16x32_bf16 v[126:129], v[166:169], v[150:153], v[126:129]
	v_mfma_f32_16x16x32_bf16 v[122:125], v[166:169], v[158:161], v[122:125]
	v_mfma_f32_16x16x32_bf16 v[118:121], v[174:177], v[150:153], v[118:121]
	v_mfma_f32_16x16x32_bf16 v[114:117], v[174:177], v[158:161], v[114:117]
	v_mfma_f32_16x16x32_bf16 v[110:113], v[184:187], v[150:153], v[110:113]
	v_mfma_f32_16x16x32_bf16 v[106:109], v[184:187], v[158:161], v[106:109]
	v_mfma_f32_16x16x32_bf16 v[102:105], v[192:195], v[150:153], v[102:105]
	v_mfma_f32_16x16x32_bf16 v[98:101], v[192:195], v[158:161], v[98:101]
	v_mfma_f32_16x16x32_bf16 v[94:97], v[162:165], v[196:199], 0
	v_mfma_f32_16x16x32_bf16 v[90:93], v[162:165], v[204:207], 0
	v_mfma_f32_16x16x32_bf16 v[86:89], v[170:173], v[196:199], 0
	v_mfma_f32_16x16x32_bf16 v[82:85], v[170:173], v[204:207], 0
	v_mfma_f32_16x16x32_bf16 v[78:81], v[180:183], v[196:199], 0
	v_mfma_f32_16x16x32_bf16 v[74:77], v[180:183], v[204:207], 0
	v_mfma_f32_16x16x32_bf16 v[70:73], v[188:191], v[196:199], 0
	v_mfma_f32_16x16x32_bf16 v[66:69], v[188:191], v[204:207], 0
	v_mfma_f32_16x16x32_bf16 v[94:97], v[166:169], v[200:203], v[94:97]
	v_mfma_f32_16x16x32_bf16 v[90:93], v[166:169], v[208:211], v[90:93]
	v_mfma_f32_16x16x32_bf16 v[86:89], v[174:177], v[200:203], v[86:89]
	v_mfma_f32_16x16x32_bf16 v[82:85], v[174:177], v[208:211], v[82:85]
	v_mfma_f32_16x16x32_bf16 v[78:81], v[184:187], v[200:203], v[78:81]
	v_mfma_f32_16x16x32_bf16 v[74:77], v[184:187], v[208:211], v[74:77]
	v_mfma_f32_16x16x32_bf16 v[70:73], v[192:195], v[200:203], v[70:73]
	v_mfma_f32_16x16x32_bf16 v[66:69], v[192:195], v[208:211], v[66:69]
	s_setprio 0
	s_barrier
; #define WAIT_V(n) asm volatile("s_waitcnt vmcnt(" #n ")" ::: "memory")
; #define WAIT_L(n) asm volatile("s_waitcnt lgkmcnt(" #n ")" ::: "memory")
; #define BAR __builtin_amdgcn_s_barrier()
; #define SCHED __builtin_amdgcn_sched_barrier(0)
; #define STG_A(b, h, kt) stage_half_s(lds0 + ((b) * 2 + (h)) * HT_B, ((h) ? A1 : Ap) + (kt) * BK, off0, off1)
; #define STG_B(b, h, kt) stage_half_s(lds0 + (4 + (b) * 2 + (h)) * HT_B, ((h) ? B1p : Bp) + (kt) * BK, off0, off1)
; #define STG_A(b, h, kt) stage_half_s(lds0 + ((b) * 2 + (h)) * HT_B, ((h) ? A1 : Ap) + (kt) * BK, off0, off1)
; #define STG_B(b, h, kt) stage_half_s(lds0 + (4 + (b) * 2 + (h)) * HT_B, ((h) ? B1p : Bp) + (kt) * BK, off0, off1)
; #define LDA8(b, h) _Pragma("unroll") for (int m = 0; m < 4; ++m) _Pragma("unroll") for (int k = 0; k < 2; ++k) \
;     At[m][k] = *(const bf16x8*)(SA_(shm, b, h) + abase + (m * 2 + k) * 1024)
; #define LDB8(dst, b, h) _Pragma("unroll") for (int n = 0; n < 2; ++n) _Pragma("unroll") for (int k = 0; k < 2; ++k) \
;     dst[n][k] = *(const bf16x8*)(SB_(shm, b, h) + bbase + (n * 2 + k) * 1024)
; #define MMA8(ai, bj, Bx) do { __builtin_amdgcn_s_setprio(1); \
;     _Pragma("unroll") for (int m = 0; m < 4; ++m) _Pragma("unroll") for (int n = 0; n < 2; ++n) _Pragma("unroll") for (int k = 0; k < 2; ++k) \
;       acc[ai][bj][m][n] = __builtin_amdgcn_mfma_f32_16x16x32_bf16(At[m][k], Bx[n][k], acc[ai][bj][m][n], 0, 0, 0); \
;     __builtin_amdgcn_s_setprio(0); } while (0)
; template <bool HS>
; __device__ __forceinline__ void gemm_tile8(const u16* __restrict__ Ap, const u16* __restrict__ Bp, int K,
;                                            f32x4 (&acc)[2][2][4][2], char* shm, const int tid, const float* hsr = nullptr) {
;     ...
;     BAR; WAIT_L(0); MMA8(0, 1, B1); BAR;
;     LDA8(0, 1); STG_A(0, 0, t + 2);
;     BAR; WAIT_L(0); MMA8(1, 0, B0); BAR; SCHED;
;     STG_B(0, 1, t + 2);
;     WAIT_V(6); BAR; MMA8(1, 1, B1); BAR;
;     LDB8(B0, 1, 0); SCHED; LDA8(1, 0); STG_A(0, 1, t + 2);
;     WAIT_L(8); BAR; WAIT_L(0); MMA8(0, 0, B0); BAR; SCHED;
	ds_read_b128 v[162:165], v142 offset:16384
	ds_read_b128 v[166:169], v142 offset:17408
	ds_read_b128 v[170:173], v142 offset:18432
	ds_read_b128 v[174:177], v142 offset:19456
	ds_read_b128 v[180:183], v142 offset:20480
	ds_read_b128 v[184:187], v142 offset:21504
	ds_read_b128 v[188:191], v142 offset:22528
	ds_read_b128 v[192:195], v142 offset:23552
	s_add_u32 s0, s20, 0x100
	s_addc_u32 s1, s21, 0
	s_add_i32 s3, s7, 0x10000
	s_mov_b32 m0, s3
	s_nop 0
	global_load_lds_dwordx4 v144, s[0:1]
	s_add_i32 s3, s7, 0x12000
	s_mov_b32 m0, s3
	s_nop 0
	global_load_lds_dwordx4 v143, s[0:1]
	s_add_u32 s0, s16, 0x100
	s_addc_u32 s1, s17, 0
	s_mov_b32 m0, s7
	s_nop 0
	global_load_lds_dwordx4 v144, s[0:1]
	s_add_i32 s3, s7, 0x2000
	s_mov_b32 m0, s3
	s_nop 0
	global_load_lds_dwordx4 v143, s[0:1]
	s_add_u32 s0, s22, 0x100
	s_addc_u32 s1, s23, 0
	s_add_i32 s3, s7, 0x14000
	s_mov_b32 m0, s3
	s_nop 0
	global_load_lds_dwordx4 v144, s[0:1]
	s_add_i32 s3, s7, 0x16000
	s_mov_b32 m0, s3
	s_nop 0
	global_load_lds_dwordx4 v143, s[0:1]
	s_waitcnt vmcnt(8) lgkmcnt(0)
	s_barrier
	s_setprio 1
	v_mfma_f32_16x16x32_bf16 v[62:65], v[162:165], v[146:149], 0
	v_mfma_f32_16x16x32_bf16 v[58:61], v[162:165], v[154:157], 0
	v_mfma_f32_16x16x32_bf16 v[54:57], v[170:173], v[146:149], 0
	v_mfma_f32_16x16x32_bf16 v[50:53], v[170:173], v[154:157], 0
	v_mfma_f32_16x16x32_bf16 v[46:49], v[180:183], v[146:149], 0
	v_mfma_f32_16x16x32_bf16 v[42:45], v[180:183], v[154:157], 0
	v_mfma_f32_16x16x32_bf16 v[38:41], v[188:191], v[146:149], 0
	v_mfma_f32_16x16x32_bf16 v[34:37], v[188:191], v[154:157], 0
	v_mfma_f32_16x16x32_bf16 v[62:65], v[166:169], v[150:153], v[62:65]
	v_mfma_f32_16x16x32_bf16 v[58:61], v[166:169], v[158:161], v[58:61]
	v_mfma_f32_16x16x32_bf16 v[54:57], v[174:177], v[150:153], v[54:57]
	v_mfma_f32_16x16x32_bf16 v[50:53], v[174:177], v[158:161], v[50:53]
	v_mfma_f32_16x16x32_bf16 v[46:49], v[184:187], v[150:153], v[46:49]
	v_mfma_f32_16x16x32_bf16 v[42:45], v[184:187], v[158:161], v[42:45]
	v_mfma_f32_16x16x32_bf16 v[38:41], v[192:195], v[150:153], v[38:41]
	v_mfma_f32_16x16x32_bf16 v[34:37], v[192:195], v[158:161], v[34:37]
	v_mfma_f32_16x16x32_bf16 v[30:33], v[162:165], v[196:199], 0
	v_mfma_f32_16x16x32_bf16 v[26:29], v[162:165], v[204:207], 0
	v_mfma_f32_16x16x32_bf16 v[22:25], v[170:173], v[196:199], 0
	v_mfma_f32_16x16x32_bf16 v[18:21], v[170:173], v[204:207], 0
	v_mfma_f32_16x16x32_bf16 v[14:17], v[180:183], v[196:199], 0
	v_mfma_f32_16x16x32_bf16 v[10:13], v[180:183], v[204:207], 0
	v_mfma_f32_16x16x32_bf16 v[6:9], v[188:191], v[196:199], 0
	v_mfma_f32_16x16x32_bf16 v[2:5], v[188:191], v[204:207], 0
	v_mfma_f32_16x16x32_bf16 v[30:33], v[166:169], v[200:203], v[30:33]
	v_mfma_f32_16x16x32_bf16 v[26:29], v[166:169], v[208:211], v[26:29]
	v_mfma_f32_16x16x32_bf16 v[22:25], v[174:177], v[200:203], v[22:25]
	v_mfma_f32_16x16x32_bf16 v[18:21], v[174:177], v[208:211], v[18:21]
	v_mfma_f32_16x16x32_bf16 v[14:17], v[184:187], v[200:203], v[14:17]
	v_mfma_f32_16x16x32_bf16 v[10:13], v[184:187], v[208:211], v[10:13]
	v_mfma_f32_16x16x32_bf16 v[6:9], v[192:195], v[200:203], v[6:9]
	v_mfma_f32_16x16x32_bf16 v[2:5], v[192:195], v[208:211], v[2:5]
	s_setprio 0
	s_barrier
	v_add_u32_e32 v158, 0x18000, v145
	ds_read_b128 v[146:149], v158
	ds_read_b128 v[150:153], v158 offset:1024
	ds_read_b128 v[154:157], v158 offset:2048
	ds_read_b128 v[158:161], v158 offset:3072
	ds_read_b128 v[162:165], v142 offset:32768
	ds_read_b128 v[166:169], v142 offset:33792
	ds_read_b128 v[170:173], v142 offset:34816
	ds_read_b128 v[174:177], v142 offset:35840
	ds_read_b128 v[180:183], v142 offset:36864
	ds_read_b128 v[184:187], v142 offset:37888
	ds_read_b128 v[188:191], v142 offset:38912
	ds_read_b128 v[192:195], v142 offset:39936
	v_add_u32_e32 v208, 0x1c000, v145
	ds_read_b128 v[196:199], v208
	ds_read_b128 v[200:203], v208 offset:1024
	ds_read_b128 v[204:207], v208 offset:2048
	ds_read_b128 v[208:211], v208 offset:3072
	s_add_u32 s0, s18, 0x100
	s_addc_u32 s1, s19, 0
	s_add_i32 s3, s7, 0x4000
	s_mov_b32 m0, s3
	s_nop 0
	global_load_lds_dwordx4 v144, s[0:1]
	s_add_i32 s3, s7, 0x6000
	s_mov_b32 m0, s3
	s_nop 0
	global_load_lds_dwordx4 v143, s[0:1]
	s_waitcnt vmcnt(8) lgkmcnt(0)
	s_barrier
	s_setprio 1
	v_mfma_f32_16x16x32_bf16 v[126:129], v[162:165], v[146:149], v[126:129]
	v_mfma_f32_16x16x32_bf16 v[122:125], v[162:165], v[154:157], v[122:125]
	v_mfma_f32_16x16x32_bf16 v[118:121], v[170:173], v[146:149], v[118:121]
	v_mfma_f32_16x16x32_bf16 v[114:117], v[170:173], v[154:157], v[114:117]
	v_mfma_f32_16x16x32_bf16 v[110:113], v[180:183], v[146:149], v[110:113]
	v_mfma_f32_16x16x32_bf16 v[106:109], v[180:183], v[154:157], v[106:109]
	v_mfma_f32_16x16x32_bf16 v[102:105], v[188:191], v[146:149], v[102:105]
	v_mfma_f32_16x16x32_bf16 v[98:101], v[188:191], v[154:157], v[98:101]
	v_mfma_f32_16x16x32_bf16 v[126:129], v[166:169], v[150:153], v[126:129]
	v_mfma_f32_16x16x32_bf16 v[122:125], v[166:169], v[158:161], v[122:125]
	v_mfma_f32_16x16x32_bf16 v[118:121], v[174:177], v[150:153], v[118:121]
	v_mfma_f32_16x16x32_bf16 v[114:117], v[174:177], v[158:161], v[114:117]
	v_mfma_f32_16x16x32_bf16 v[110:113], v[184:187], v[150:153], v[110:113]
	v_mfma_f32_16x16x32_bf16 v[106:109], v[184:187], v[158:161], v[106:109]
	v_mfma_f32_16x16x32_bf16 v[102:105], v[192:195], v[150:153], v[102:105]
	v_mfma_f32_16x16x32_bf16 v[98:101], v[192:195], v[158:161], v[98:101]
	v_mfma_f32_16x16x32_bf16 v[94:97], v[162:165], v[196:199], v[94:97]
	v_mfma_f32_16x16x32_bf16 v[90:93], v[162:165], v[204:207], v[90:93]
	v_mfma_f32_16x16x32_bf16 v[86:89], v[170:173], v[196:199], v[86:89]
	v_mfma_f32_16x16x32_bf16 v[82:85], v[170:173], v[204:207], v[82:85]
	v_mfma_f32_16x16x32_bf16 v[78:81], v[180:183], v[196:199], v[78:81]
	v_mfma_f32_16x16x32_bf16 v[74:77], v[180:183], v[204:207], v[74:77]
	v_mfma_f32_16x16x32_bf16 v[70:73], v[188:191], v[196:199], v[70:73]
	v_mfma_f32_16x16x32_bf16 v[66:69], v[188:191], v[204:207], v[66:69]
	v_mfma_f32_16x16x32_bf16 v[94:97], v[166:169], v[200:203], v[94:97]
	v_mfma_f32_16x16x32_bf16 v[90:93], v[166:169], v[208:211], v[90:93]
	v_mfma_f32_16x16x32_bf16 v[86:89], v[174:177], v[200:203], v[86:89]
	v_mfma_f32_16x16x32_bf16 v[82:85], v[174:177], v[208:211], v[82:85]
	v_mfma_f32_16x16x32_bf16 v[78:81], v[184:187], v[200:203], v[78:81]
	v_mfma_f32_16x16x32_bf16 v[74:77], v[184:187], v[208:211], v[74:77]
	v_mfma_f32_16x16x32_bf16 v[70:73], v[192:195], v[200:203], v[70:73]
	v_mfma_f32_16x16x32_bf16 v[66:69], v[192:195], v[208:211], v[66:69]
	s_setprio 0
	s_barrier
; #define WAIT_V(n) asm volatile("s_waitcnt vmcnt(" #n ")" ::: "memory")
; #define WAIT_L(n) asm volatile("s_waitcnt lgkmcnt(" #n ")" ::: "memory")
; #define BAR __builtin_amdgcn_s_barrier()
; #define SCHED __builtin_amdgcn_sched_barrier(0)
; #define STG_A(b, h, kt) stage_half_s(lds0 + ((b) * 2 + (h)) * HT_B, ((h) ? A1 : Ap) + (kt) * BK, off0, off1)
; #define STG_B(b, h, kt) stage_half_s(lds0 + (4 + (b) * 2 + (h)) * HT_B, ((h) ? B1p : Bp) + (kt) * BK, off0, off1)
; #define STG_A(b, h, kt) stage_half_s(lds0 + ((b) * 2 + (h)) * HT_B, ((h) ? A1 : Ap) + (kt) * BK, off0, off1)
; #define STG_B(b, h, kt) stage_half_s(lds0 + (4 + (b) * 2 + (h)) * HT_B, ((h) ? B1p : Bp) + (kt) * BK, off0, off1)
; #define LDA8(b, h) _Pragma("unroll") for (int m = 0; m < 4; ++m) _Pragma("unroll") for (int k = 0; k < 2; ++k) \
;     At[m][k] = *(const bf16x8*)(SA_(shm, b, h) + abase + (m * 2 + k) * 1024)
; #define LDB8(dst, b, h) _Pragma("unroll") for (int n = 0; n < 2; ++n) _Pragma("unroll") for (int k = 0; k < 2; ++k) \
;     dst[n][k] = *(const bf16x8*)(SB_(shm, b, h) + bbase + (n * 2 + k) * 1024)
; #define MMA8(ai, bj, Bx) do { __builtin_amdgcn_s_setprio(1); \
;     _Pragma("unroll") for (int m = 0; m < 4; ++m) _Pragma("unroll") for (int n = 0; n < 2; ++n) _Pragma("unroll") for (int k = 0; k < 2; ++k) \
;       acc[ai][bj][m][n] = __builtin_amdgcn_mfma_f32_16x16x32_bf16(At[m][k], Bx[n][k], acc[ai][bj][m][n], 0, 0, 0); \
;     __builtin_amdgcn_s_setprio(0); } while (0)
; template <bool HS>
; __device__ __forceinline__ void gemm_tile8(const u16* __restrict__ Ap, const u16* __restrict__ Bp, int K,
;                                            f32x4 (&acc)[2][2][4][2], char* shm, const int tid, const float* hsr = nullptr) {
;     ...
;     LDB8(B1, 1, 1); STG_B(1, 0, t + 3);
;     BAR; WAIT_L(0); MMA8(0, 1, B1); BAR;
;     LDA8(1, 1); STG_A(1, 0, t + 3);
;     BAR; WAIT_L(0); MMA8(1, 0, B0); BAR; SCHED;
;     STG_B(1, 1, t + 3);
;     WAIT_V(6); BAR; MMA8(1, 1, B1); BAR;
;   }
	ds_read_b128 v[162:165], v142 offset:49152
	ds_read_b128 v[166:169], v142 offset:50176
	ds_read_b128 v[170:173], v142 offset:51200
	ds_read_b128 v[174:177], v142 offset:52224
	ds_read_b128 v[180:183], v142 offset:53248
	ds_read_b128 v[184:187], v142 offset:54272
	ds_read_b128 v[188:191], v142 offset:55296
	ds_read_b128 v[192:195], v142 offset:56320
	s_add_u32 s0, s20, 0x180
	s_addc_u32 s1, s21, 0
	s_add_i32 s3, s7, 0x18000
	s_mov_b32 m0, s3
	s_nop 0
	global_load_lds_dwordx4 v144, s[0:1]
	s_add_i32 s3, s7, 0x1a000
	s_mov_b32 m0, s3
	s_nop 0
	global_load_lds_dwordx4 v143, s[0:1]
	s_add_u32 s0, s16, 0x180
	s_addc_u32 s1, s17, 0
	s_add_i32 s3, s7, 0x8000
	s_mov_b32 m0, s3
	s_nop 0
	global_load_lds_dwordx4 v144, s[0:1]
	s_add_i32 s3, s7, 0xa000
	s_mov_b32 m0, s3
	s_nop 0
	global_load_lds_dwordx4 v143, s[0:1]
	s_add_u32 s0, s22, 0x180
	s_addc_u32 s1, s23, 0
	s_add_i32 s3, s7, 0x1c000
	s_mov_b32 m0, s3
	s_nop 0
	global_load_lds_dwordx4 v144, s[0:1]
	s_add_i32 s3, s7, 0x1e000
	s_mov_b32 m0, s3
	s_nop 0
	global_load_lds_dwordx4 v143, s[0:1]
	s_waitcnt vmcnt(8) lgkmcnt(0)
	s_barrier
	s_setprio 1
	v_mfma_f32_16x16x32_bf16 v[62:65], v[162:165], v[146:149], v[62:65]
	v_mfma_f32_16x16x32_bf16 v[58:61], v[162:165], v[154:157], v[58:61]
	v_mfma_f32_16x16x32_bf16 v[54:57], v[170:173], v[146:149], v[54:57]
	v_mfma_f32_16x16x32_bf16 v[50:53], v[170:173], v[154:157], v[50:53]
	v_mfma_f32_16x16x32_bf16 v[46:49], v[180:183], v[146:149], v[46:49]
	v_mfma_f32_16x16x32_bf16 v[42:45], v[180:183], v[154:157], v[42:45]
	v_mfma_f32_16x16x32_bf16 v[38:41], v[188:191], v[146:149], v[38:41]
	v_mfma_f32_16x16x32_bf16 v[34:37], v[188:191], v[154:157], v[34:37]
	v_mfma_f32_16x16x32_bf16 v[62:65], v[166:169], v[150:153], v[62:65]
	v_mfma_f32_16x16x32_bf16 v[58:61], v[166:169], v[158:161], v[58:61]
	v_mfma_f32_16x16x32_bf16 v[54:57], v[174:177], v[150:153], v[54:57]
	v_mfma_f32_16x16x32_bf16 v[50:53], v[174:177], v[158:161], v[50:53]
	v_mfma_f32_16x16x32_bf16 v[46:49], v[184:187], v[150:153], v[46:49]
	v_mfma_f32_16x16x32_bf16 v[42:45], v[184:187], v[158:161], v[42:45]
	v_mfma_f32_16x16x32_bf16 v[38:41], v[192:195], v[150:153], v[38:41]
	v_mfma_f32_16x16x32_bf16 v[34:37], v[192:195], v[158:161], v[34:37]
	v_mfma_f32_16x16x32_bf16 v[30:33], v[162:165], v[196:199], v[30:33]
	v_mfma_f32_16x16x32_bf16 v[26:29], v[162:165], v[204:207], v[26:29]
	v_mfma_f32_16x16x32_bf16 v[22:25], v[170:173], v[196:199], v[22:25]
	v_mfma_f32_16x16x32_bf16 v[18:21], v[170:173], v[204:207], v[18:21]
	v_mfma_f32_16x16x32_bf16 v[14:17], v[180:183], v[196:199], v[14:17]
	v_mfma_f32_16x16x32_bf16 v[10:13], v[180:183], v[204:207], v[10:13]
	v_mfma_f32_16x16x32_bf16 v[6:9], v[188:191], v[196:199], v[6:9]
	v_mfma_f32_16x16x32_bf16 v[2:5], v[188:191], v[204:207], v[2:5]
	v_mfma_f32_16x16x32_bf16 v[30:33], v[166:169], v[200:203], v[30:33]
	v_mfma_f32_16x16x32_bf16 v[26:29], v[166:169], v[208:211], v[26:29]
	v_mfma_f32_16x16x32_bf16 v[22:25], v[174:177], v[200:203], v[22:25]
	v_mfma_f32_16x16x32_bf16 v[18:21], v[174:177], v[208:211], v[18:21]
	v_mfma_f32_16x16x32_bf16 v[14:17], v[184:187], v[200:203], v[14:17]
	v_mfma_f32_16x16x32_bf16 v[10:13], v[184:187], v[208:211], v[10:13]
	v_mfma_f32_16x16x32_bf16 v[6:9], v[192:195], v[200:203], v[6:9]
	v_mfma_f32_16x16x32_bf16 v[2:5], v[192:195], v[208:211], v[2:5]
	s_setprio 0
	s_add_u32 s16, s16, 0x100
	s_addc_u32 s17, s17, 0
	s_add_u32 s18, s18, 0x100
	s_addc_u32 s19, s19, 0
	s_add_u32 s20, s20, 0x100
	s_addc_u32 s21, s21, 0
	s_add_u32 s22, s22, 0x100
	s_addc_u32 s23, s23, 0
	s_mov_b32 s14, 6
	s_barrier
.Lk_ffn_in:
	v_add_u32_e32 v158, 0x10000, v145
	ds_read_b128 v[146:149], v158
	ds_read_b128 v[150:153], v158 offset:1024
	ds_read_b128 v[154:157], v158 offset:2048
	ds_read_b128 v[158:161], v158 offset:3072
	ds_read_b128 v[162:165], v142
	ds_read_b128 v[166:169], v142 offset:1024
	ds_read_b128 v[170:173], v142 offset:2048
	ds_read_b128 v[174:177], v142 offset:3072
	ds_read_b128 v[180:183], v142 offset:4096
	ds_read_b128 v[184:187], v142 offset:5120
	ds_read_b128 v[188:191], v142 offset:6144
	ds_read_b128 v[192:195], v142 offset:7168
	v_add_u32_e32 v208, 0x14000, v145
	ds_read_b128 v[196:199], v208
	ds_read_b128 v[200:203], v208 offset:1024
	ds_read_b128 v[204:207], v208 offset:2048
	ds_read_b128 v[208:211], v208 offset:3072
	s_add_u32 s0, s18, 0x80
	s_addc_u32 s1, s19, 0
	s_add_i32 s3, s7, 0xc000
	s_mov_b32 m0, s3
	s_nop 0
	global_load_lds_dwordx4 v144, s[0:1]
	s_add_i32 s3, s7, 0xe000
	s_mov_b32 m0, s3
	s_nop 0
	global_load_lds_dwordx4 v143, s[0:1]
	s_waitcnt vmcnt(8) lgkmcnt(0)
	s_barrier
; #define WAIT_V(n) asm volatile("s_waitcnt vmcnt(" #n ")" ::: "memory")
; #define WAIT_L(n) asm volatile("s_waitcnt lgkmcnt(" #n ")" ::: "memory")
; #define BAR __builtin_amdgcn_s_barrier()
; #define SCHED __builtin_amdgcn_sched_barrier(0)
; #define STG_A(b, h, kt) stage_half_s(lds0 + ((b) * 2 + (h)) * HT_B, ((h) ? A1 : Ap) + (kt) * BK, off0, off1)
; #define STG_B(b, h, kt) stage_half_s(lds0 + (4 + (b) * 2 + (h)) * HT_B, ((h) ? B1p : Bp) + (kt) * BK, off0, off1)
; #define STG_A(b, h, kt) stage_half_s(lds0 + ((b) * 2 + (h)) * HT_B, ((h) ? A1 : Ap) + (kt) * BK, off0, off1)
; #define STG_B(b, h, kt) stage_half_s(lds0 + (4 + (b) * 2 + (h)) * HT_B, ((h) ? B1p : Bp) + (kt) * BK, off0, off1)
; #define LDA8(b, h) _Pragma("unroll") for (int m = 0; m < 4; ++m) _Pragma("unroll") for (int k = 0; k < 2; ++k) \
;     At[m][k] = *(const bf16x8*)(SA_(shm, b, h) + abase + (m * 2 + k) * 1024)
; #define LDB8(dst, b, h) _Pragma("unroll") for (int n = 0; n < 2; ++n) _Pragma("unroll") for (int k = 0; k < 2; ++k) \
;     dst[n][k] = *(const bf16x8*)(SB_(shm, b, h) + bbase + (n * 2 + k) * 1024)
; #define MMA8(ai, bj, Bx) do { __builtin_amdgcn_s_setprio(1); \
;     _Pragma("unroll") for (int m = 0; m < 4; ++m) _Pragma("unroll") for (int n = 0; n < 2; ++n) _Pragma("unroll") for (int k = 0; k < 2; ++k) \
;       acc[ai][bj][m][n] = __builtin_amdgcn_mfma_f32_16x16x32_bf16(At[m][k], Bx[n][k], acc[ai][bj][m][n], 0, 0, 0); \
;     __builtin_amdgcn_s_setprio(0); } while (0)
; template <bool HS>
; __device__ __forceinline__ void gemm_tile8(const u16* __restrict__ Ap, const u16* __restrict__ Bp, int K,
;                                            f32x4 (&acc)[2][2][4][2], char* shm, const int tid, const float* hsr = nullptr) {
;     ...
;     LDB8(B0, 0, 0); SCHED; LDA8(0, 0); STG_A(1, 1, t + 1);
;     WAIT_L(8); BAR; WAIT_L(0); MMA8(0, 0, B0); BAR; SCHED;
;     LDB8(B1, 0, 1); STG_B(0, 0, t + 2);
;     BAR; WAIT_L(0); MMA8(0, 1, B1); BAR;
;     LDA8(0, 1); STG_A(0, 0, t + 2);
;     BAR; WAIT_L(0); MMA8(1, 0, B0); BAR; SCHED;
;     STG_B(0, 1, t + 2);
;     WAIT_V(6); BAR; MMA8(1, 1, B1); BAR;
;     LDB8(B0, 1, 0); SCHED; LDA8(1, 0); STG_A(0, 1, t + 2);
;     WAIT_L(8); BAR; WAIT_L(0); MMA8(0, 0, B0); BAR; SCHED;
	s_setprio 1
	v_mfma_f32_16x16x32_bf16 v[126:129], v[162:165], v[146:149], v[126:129]
	v_mfma_f32_16x16x32_bf16 v[122:125], v[162:165], v[154:157], v[122:125]
	v_mfma_f32_16x16x32_bf16 v[118:121], v[170:173], v[146:149], v[118:121]
	v_mfma_f32_16x16x32_bf16 v[114:117], v[170:173], v[154:157], v[114:117]
	v_mfma_f32_16x16x32_bf16 v[110:113], v[180:183], v[146:149], v[110:113]
	v_mfma_f32_16x16x32_bf16 v[106:109], v[180:183], v[154:157], v[106:109]
	v_mfma_f32_16x16x32_bf16 v[102:105], v[188:191], v[146:149], v[102:105]
	v_mfma_f32_16x16x32_bf16 v[98:101], v[188:191], v[154:157], v[98:101]
	v_mfma_f32_16x16x32_bf16 v[126:129], v[166:169], v[150:153], v[126:129]
	v_mfma_f32_16x16x32_bf16 v[122:125], v[166:169], v[158:161], v[122:125]
	v_mfma_f32_16x16x32_bf16 v[118:121], v[174:177], v[150:153], v[118:121]
	v_mfma_f32_16x16x32_bf16 v[114:117], v[174:177], v[158:161], v[114:117]
	v_mfma_f32_16x16x32_bf16 v[110:113], v[184:187], v[150:153], v[110:113]
	v_mfma_f32_16x16x32_bf16 v[106:109], v[184:187], v[158:161], v[106:109]
	v_mfma_f32_16x16x32_bf16 v[102:105], v[192:195], v[150:153], v[102:105]
	v_mfma_f32_16x16x32_bf16 v[98:101], v[192:195], v[158:161], v[98:101]
	v_mfma_f32_16x16x32_bf16 v[94:97], v[162:165], v[196:199], v[94:97]
	v_mfma_f32_16x16x32_bf16 v[90:93], v[162:165], v[204:207], v[90:93]
	v_mfma_f32_16x16x32_bf16 v[86:89], v[170:173], v[196:199], v[86:89]
	v_mfma_f32_16x16x32_bf16 v[82:85], v[170:173], v[204:207], v[82:85]
	v_mfma_f32_16x16x32_bf16 v[78:81], v[180:183], v[196:199], v[78:81]
	v_mfma_f32_16x16x32_bf16 v[74:77], v[180:183], v[204:207], v[74:77]
	v_mfma_f32_16x16x32_bf16 v[70:73], v[188:191], v[196:199], v[70:73]
	v_mfma_f32_16x16x32_bf16 v[66:69], v[188:191], v[204:207], v[66:69]
	v_mfma_f32_16x16x32_bf16 v[94:97], v[166:169], v[200:203], v[94:97]
	v_mfma_f32_16x16x32_bf16 v[90:93], v[166:169], v[208:211], v[90:93]
	v_mfma_f32_16x16x32_bf16 v[86:89], v[174:177], v[200:203], v[86:89]
	v_mfma_f32_16x16x32_bf16 v[82:85], v[174:177], v[208:211], v[82:85]
	v_mfma_f32_16x16x32_bf16 v[78:81], v[184:187], v[200:203], v[78:81]
	v_mfma_f32_16x16x32_bf16 v[74:77], v[184:187], v[208:211], v[74:77]
	v_mfma_f32_16x16x32_bf16 v[70:73], v[192:195], v[200:203], v[70:73]
	v_mfma_f32_16x16x32_bf16 v[66:69], v[192:195], v[208:211], v[66:69]
	s_setprio 0
	s_barrier
	ds_read_b128 v[162:165], v142 offset:16384
	ds_read_b128 v[166:169], v142 offset:17408
	ds_read_b128 v[170:173], v142 offset:18432
	ds_read_b128 v[174:177], v142 offset:19456
	ds_read_b128 v[180:183], v142 offset:20480
	ds_read_b128 v[184:187], v142 offset:21504
	ds_read_b128 v[188:191], v142 offset:22528
	ds_read_b128 v[192:195], v142 offset:23552
	s_add_u32 s0, s20, 0x100
	s_addc_u32 s1, s21, 0
	s_add_i32 s3, s7, 0x10000
	s_mov_b32 m0, s3
	s_nop 0
	global_load_lds_dwordx4 v144, s[0:1]
	s_add_i32 s3, s7, 0x12000
	s_mov_b32 m0, s3
	s_nop 0
	global_load_lds_dwordx4 v143, s[0:1]
	s_add_u32 s0, s16, 0x100
	s_addc_u32 s1, s17, 0
	s_mov_b32 m0, s7
	s_nop 0
	global_load_lds_dwordx4 v144, s[0:1]
	s_add_i32 s3, s7, 0x2000
	s_mov_b32 m0, s3
	s_nop 0
	global_load_lds_dwordx4 v143, s[0:1]
	s_add_u32 s0, s22, 0x100
	s_addc_u32 s1, s23, 0
	s_add_i32 s3, s7, 0x14000
	s_mov_b32 m0, s3
	s_nop 0
	global_load_lds_dwordx4 v144, s[0:1]
	s_add_i32 s3, s7, 0x16000
	s_mov_b32 m0, s3
	s_nop 0
	global_load_lds_dwordx4 v143, s[0:1]
	s_waitcnt vmcnt(8) lgkmcnt(0)
	s_barrier
	s_setprio 1
	v_mfma_f32_16x16x32_bf16 v[62:65], v[162:165], v[146:149], v[62:65]
	v_mfma_f32_16x16x32_bf16 v[58:61], v[162:165], v[154:157], v[58:61]
	v_mfma_f32_16x16x32_bf16 v[54:57], v[170:173], v[146:149], v[54:57]
	v_mfma_f32_16x16x32_bf16 v[50:53], v[170:173], v[154:157], v[50:53]
	v_mfma_f32_16x16x32_bf16 v[46:49], v[180:183], v[146:149], v[46:49]
	v_mfma_f32_16x16x32_bf16 v[42:45], v[180:183], v[154:157], v[42:45]
	v_mfma_f32_16x16x32_bf16 v[38:41], v[188:191], v[146:149], v[38:41]
	v_mfma_f32_16x16x32_bf16 v[34:37], v[188:191], v[154:157], v[34:37]
	v_mfma_f32_16x16x32_bf16 v[62:65], v[166:169], v[150:153], v[62:65]
	v_mfma_f32_16x16x32_bf16 v[58:61], v[166:169], v[158:161], v[58:61]
	v_mfma_f32_16x16x32_bf16 v[54:57], v[174:177], v[150:153], v[54:57]
	v_mfma_f32_16x16x32_bf16 v[50:53], v[174:177], v[158:161], v[50:53]
	v_mfma_f32_16x16x32_bf16 v[46:49], v[184:187], v[150:153], v[46:49]
	v_mfma_f32_16x16x32_bf16 v[42:45], v[184:187], v[158:161], v[42:45]
	v_mfma_f32_16x16x32_bf16 v[38:41], v[192:195], v[150:153], v[38:41]
	v_mfma_f32_16x16x32_bf16 v[34:37], v[192:195], v[158:161], v[34:37]
	v_mfma_f32_16x16x32_bf16 v[30:33], v[162:165], v[196:199], v[30:33]
	v_mfma_f32_16x16x32_bf16 v[26:29], v[162:165], v[204:207], v[26:29]
	v_mfma_f32_16x16x32_bf16 v[22:25], v[170:173], v[196:199], v[22:25]
	v_mfma_f32_16x16x32_bf16 v[18:21], v[170:173], v[204:207], v[18:21]
	v_mfma_f32_16x16x32_bf16 v[14:17], v[180:183], v[196:199], v[14:17]
	v_mfma_f32_16x16x32_bf16 v[10:13], v[180:183], v[204:207], v[10:13]
	v_mfma_f32_16x16x32_bf16 v[6:9], v[188:191], v[196:199], v[6:9]
	v_mfma_f32_16x16x32_bf16 v[2:5], v[188:191], v[204:207], v[2:5]
	v_mfma_f32_16x16x32_bf16 v[30:33], v[166:169], v[200:203], v[30:33]
	v_mfma_f32_16x16x32_bf16 v[26:29], v[166:169], v[208:211], v[26:29]
	v_mfma_f32_16x16x32_bf16 v[22:25], v[174:177], v[200:203], v[22:25]
	v_mfma_f32_16x16x32_bf16 v[18:21], v[174:177], v[208:211], v[18:21]
	v_mfma_f32_16x16x32_bf16 v[14:17], v[184:187], v[200:203], v[14:17]
	v_mfma_f32_16x16x32_bf16 v[10:13], v[184:187], v[208:211], v[10:13]
	v_mfma_f32_16x16x32_bf16 v[6:9], v[192:195], v[200:203], v[6:9]
	v_mfma_f32_16x16x32_bf16 v[2:5], v[192:195], v[208:211], v[2:5]
	s_setprio 0
	s_barrier
; #define WAIT_L(n) asm volatile("s_waitcnt lgkmcnt(" #n ")" ::: "memory")
; #define BAR __builtin_amdgcn_s_barrier()
; #define SCHED __builtin_amdgcn_sched_barrier(0)
; #define STG_A(b, h, kt) stage_half_s(lds0 + ((b) * 2 + (h)) * HT_B, ((h) ? A1 : Ap) + (kt) * BK, off0, off1)
; #define STG_B(b, h, kt) stage_half_s(lds0 + (4 + (b) * 2 + (h)) * HT_B, ((h) ? B1p : Bp) + (kt) * BK, off0, off1)
; #define STG_A(b, h, kt) stage_half_s(lds0 + ((b) * 2 + (h)) * HT_B, ((h) ? A1 : Ap) + (kt) * BK, off0, off1)
; #define STG_B(b, h, kt) stage_half_s(lds0 + (4 + (b) * 2 + (h)) * HT_B, ((h) ? B1p : Bp) + (kt) * BK, off0, off1)
; #define LDA8(b, h) _Pragma("unroll") for (int m = 0; m < 4; ++m) _Pragma("unroll") for (int k = 0; k < 2; ++k) \
;     At[m][k] = *(const bf16x8*)(SA_(shm, b, h) + abase + (m * 2 + k) * 1024)
; #define LDB8(dst, b, h) _Pragma("unroll") for (int n = 0; n < 2; ++n) _Pragma("unroll") for (int k = 0; k < 2; ++k) \
;     dst[n][k] = *(const bf16x8*)(SB_(shm, b, h) + bbase + (n * 2 + k) * 1024)
; #define MMA8(ai, bj, Bx) do { __builtin_amdgcn_s_setprio(1); \
;     _Pragma("unroll") for (int m = 0; m < 4; ++m) _Pragma("unroll") for (int n = 0; n < 2; ++n) _Pragma("unroll") for (int k = 0; k < 2; ++k) \
;       acc[ai][bj][m][n] = __builtin_amdgcn_mfma_f32_16x16x32_bf16(At[m][k], Bx[n][k], acc[ai][bj][m][n], 0, 0, 0); \
;     __builtin_amdgcn_s_setprio(0); } while (0)
; template <bool HS>
; __device__ __forceinline__ void gemm_tile8(const u16* __restrict__ Ap, const u16* __restrict__ Bp, int K,
;                                            f32x4 (&acc)[2][2][4][2], char* shm, const int tid, const float* hsr = nullptr) {
;     ...
;     LDB8(B0, 1, 0); SCHED; LDA8(1, 0); STG_A(0, 1, t + 2);
;     WAIT_L(8); BAR; WAIT_L(0); MMA8(0, 0, B0); BAR; SCHED;
;     LDB8(B1, 1, 1); STG_B(1, 0, t + 3);
;     BAR; WAIT_L(0); MMA8(0, 1, B1); BAR;
;     LDA8(1, 1); STG_A(1, 0, t + 3);
;     BAR; WAIT_L(0); MMA8(1, 0, B0); BAR; SCHED;
;     STG_B(1, 1, t + 3);
	v_add_u32_e32 v158, 0x18000, v145
	ds_read_b128 v[146:149], v158
	ds_read_b128 v[150:153], v158 offset:1024
	ds_read_b128 v[154:157], v158 offset:2048
	ds_read_b128 v[158:161], v158 offset:3072
	ds_read_b128 v[162:165], v142 offset:32768
	ds_read_b128 v[166:169], v142 offset:33792
	ds_read_b128 v[170:173], v142 offset:34816
	ds_read_b128 v[174:177], v142 offset:35840
	ds_read_b128 v[180:183], v142 offset:36864
	ds_read_b128 v[184:187], v142 offset:37888
	ds_read_b128 v[188:191], v142 offset:38912
	ds_read_b128 v[192:195], v142 offset:39936
	v_add_u32_e32 v208, 0x1c000, v145
	ds_read_b128 v[196:199], v208
	ds_read_b128 v[200:203], v208 offset:1024
	ds_read_b128 v[204:207], v208 offset:2048
	ds_read_b128 v[208:211], v208 offset:3072
	s_add_u32 s0, s18, 0x100
	s_addc_u32 s1, s19, 0
	s_add_i32 s3, s7, 0x4000
	s_mov_b32 m0, s3
	s_nop 0
	global_load_lds_dwordx4 v144, s[0:1]
	s_add_i32 s3, s7, 0x6000
	s_mov_b32 m0, s3
	s_nop 0
	global_load_lds_dwordx4 v143, s[0:1]
	s_waitcnt vmcnt(8) lgkmcnt(0)
	s_barrier
	s_setprio 1
	v_mfma_f32_16x16x32_bf16 v[126:129], v[162:165], v[146:149], v[126:129]
	v_mfma_f32_16x16x32_bf16 v[122:125], v[162:165], v[154:157], v[122:125]
	v_mfma_f32_16x16x32_bf16 v[118:121], v[170:173], v[146:149], v[118:121]
	v_mfma_f32_16x16x32_bf16 v[114:117], v[170:173], v[154:157], v[114:117]
	v_mfma_f32_16x16x32_bf16 v[110:113], v[180:183], v[146:149], v[110:113]
	v_mfma_f32_16x16x32_bf16 v[106:109], v[180:183], v[154:157], v[106:109]
	v_mfma_f32_16x16x32_bf16 v[102:105], v[188:191], v[146:149], v[102:105]
	v_mfma_f32_16x16x32_bf16 v[98:101], v[188:191], v[154:157], v[98:101]
	v_mfma_f32_16x16x32_bf16 v[126:129], v[166:169], v[150:153], v[126:129]
	v_mfma_f32_16x16x32_bf16 v[122:125], v[166:169], v[158:161], v[122:125]
	v_mfma_f32_16x16x32_bf16 v[118:121], v[174:177], v[150:153], v[118:121]
	v_mfma_f32_16x16x32_bf16 v[114:117], v[174:177], v[158:161], v[114:117]
	v_mfma_f32_16x16x32_bf16 v[110:113], v[184:187], v[150:153], v[110:113]
	v_mfma_f32_16x16x32_bf16 v[106:109], v[184:187], v[158:161], v[106:109]
	v_mfma_f32_16x16x32_bf16 v[102:105], v[192:195], v[150:153], v[102:105]
	v_mfma_f32_16x16x32_bf16 v[98:101], v[192:195], v[158:161], v[98:101]
	v_mfma_f32_16x16x32_bf16 v[94:97], v[162:165], v[196:199], v[94:97]
	v_mfma_f32_16x16x32_bf16 v[90:93], v[162:165], v[204:207], v[90:93]
	v_mfma_f32_16x16x32_bf16 v[86:89], v[170:173], v[196:199], v[86:89]
	v_mfma_f32_16x16x32_bf16 v[82:85], v[170:173], v[204:207], v[82:85]
	v_mfma_f32_16x16x32_bf16 v[78:81], v[180:183], v[196:199], v[78:81]
	v_mfma_f32_16x16x32_bf16 v[74:77], v[180:183], v[204:207], v[74:77]
	v_mfma_f32_16x16x32_bf16 v[70:73], v[188:191], v[196:199], v[70:73]
	v_mfma_f32_16x16x32_bf16 v[66:69], v[188:191], v[204:207], v[66:69]
	v_mfma_f32_16x16x32_bf16 v[94:97], v[166:169], v[200:203], v[94:97]
	v_mfma_f32_16x16x32_bf16 v[90:93], v[166:169], v[208:211], v[90:93]
	v_mfma_f32_16x16x32_bf16 v[86:89], v[174:177], v[200:203], v[86:89]
	v_mfma_f32_16x16x32_bf16 v[82:85], v[174:177], v[208:211], v[82:85]
	v_mfma_f32_16x16x32_bf16 v[78:81], v[184:187], v[200:203], v[78:81]
	v_mfma_f32_16x16x32_bf16 v[74:77], v[184:187], v[208:211], v[74:77]
	v_mfma_f32_16x16x32_bf16 v[70:73], v[192:195], v[200:203], v[70:73]
	v_mfma_f32_16x16x32_bf16 v[66:69], v[192:195], v[208:211], v[66:69]
	s_setprio 0
	s_barrier
	ds_read_b128 v[162:165], v142 offset:49152
	ds_read_b128 v[166:169], v142 offset:50176
	ds_read_b128 v[170:173], v142 offset:51200
	ds_read_b128 v[174:177], v142 offset:52224
	ds_read_b128 v[180:183], v142 offset:53248
	ds_read_b128 v[184:187], v142 offset:54272
	ds_read_b128 v[188:191], v142 offset:55296
	ds_read_b128 v[192:195], v142 offset:56320
	s_add_u32 s0, s20, 0x180
	s_addc_u32 s1, s21, 0
	s_add_i32 s3, s7, 0x18000
	s_mov_b32 m0, s3
	s_nop 0
	global_load_lds_dwordx4 v144, s[0:1]
	s_add_i32 s3, s7, 0x1a000
	s_mov_b32 m0, s3
	s_nop 0
	global_load_lds_dwordx4 v143, s[0:1]
	s_add_u32 s0, s16, 0x180
	s_addc_u32 s1, s17, 0
	s_add_i32 s3, s7, 0x8000
	s_mov_b32 m0, s3
	s_nop 0
	global_load_lds_dwordx4 v144, s[0:1]
	s_add_i32 s3, s7, 0xa000
	s_mov_b32 m0, s3
	s_nop 0
	global_load_lds_dwordx4 v143, s[0:1]
	s_add_u32 s0, s22, 0x180
	s_addc_u32 s1, s23, 0
	s_add_i32 s3, s7, 0x1c000
	s_mov_b32 m0, s3
	s_nop 0
	global_load_lds_dwordx4 v144, s[0:1]
	s_add_i32 s3, s7, 0x1e000
	s_mov_b32 m0, s3
	s_nop 0
	global_load_lds_dwordx4 v143, s[0:1]
	s_waitcnt vmcnt(8) lgkmcnt(0)
	s_barrier
; #define WAIT_V(n) asm volatile("s_waitcnt vmcnt(" #n ")" ::: "memory")
; #define WAIT_L(n) asm volatile("s_waitcnt lgkmcnt(" #n ")" ::: "memory")
; #define BAR __builtin_amdgcn_s_barrier()
; #define STG_A(b, h, kt) stage_half_s(lds0 + ((b) * 2 + (h)) * HT_B, ((h) ? A1 : Ap) + (kt) * BK, off0, off1)
; #define STG_B(b, h, kt) stage_half_s(lds0 + (4 + (b) * 2 + (h)) * HT_B, ((h) ? B1p : Bp) + (kt) * BK, off0, off1)
; #define STG_A(b, h, kt) stage_half_s(lds0 + ((b) * 2 + (h)) * HT_B, ((h) ? A1 : Ap) + (kt) * BK, off0, off1)
; #define STG_B(b, h, kt) stage_half_s(lds0 + (4 + (b) * 2 + (h)) * HT_B, ((h) ? B1p : Bp) + (kt) * BK, off0, off1)
; #define LDA8(b, h) _Pragma("unroll") for (int m = 0; m < 4; ++m) _Pragma("unroll") for (int k = 0; k < 2; ++k) \
;     At[m][k] = *(const bf16x8*)(SA_(shm, b, h) + abase + (m * 2 + k) * 1024)
; #define LDB8(dst, b, h) _Pragma("unroll") for (int n = 0; n < 2; ++n) _Pragma("unroll") for (int k = 0; k < 2; ++k) \
;     dst[n][k] = *(const bf16x8*)(SB_(shm, b, h) + bbase + (n * 2 + k) * 1024)
; #define MMA8(ai, bj, Bx) do { __builtin_amdgcn_s_setprio(1); \
;     _Pragma("unroll") for (int m = 0; m < 4; ++m) _Pragma("unroll") for (int n = 0; n < 2; ++n) _Pragma("unroll") for (int k = 0; k < 2; ++k) \
;       acc[ai][bj][m][n] = __builtin_amdgcn_mfma_f32_16x16x32_bf16(At[m][k], Bx[n][k], acc[ai][bj][m][n], 0, 0, 0); \
;     __builtin_amdgcn_s_setprio(0); } while (0)
; template <bool HS>
; __device__ __forceinline__ void gemm_tile8(const u16* __restrict__ Ap, const u16* __restrict__ Bp, int K,
;                                            f32x4 (&acc)[2][2][4][2], char* shm, const int tid, const float* hsr = nullptr) {
;     ...
;     STG_B(1, 1, t + 3);
;     WAIT_V(6); BAR; MMA8(1, 1, B1); BAR;
;   }
;   { LDB8(B0, 0, 0); LDA8(0, 0); STG_A(1, 1, nt - 1);
;     BAR; WAIT_L(0); MMA8(0, 0, B0); BAR;
;     LDB8(B1, 0, 1); BAR; WAIT_L(0); MMA8(0, 1, B1); BAR;
;     LDA8(0, 1); WAIT_V(4); BAR; WAIT_L(0); MMA8(1, 0, B0); MMA8(1, 1, B1); BAR; }
;   { LDB8(B0, 1, 0); LDA8(1, 0); WAIT_V(2); BAR; WAIT_L(0); MMA8(0, 0, B0); BAR;
	s_setprio 1
	v_mfma_f32_16x16x32_bf16 v[62:65], v[162:165], v[146:149], v[62:65]
	v_mfma_f32_16x16x32_bf16 v[58:61], v[162:165], v[154:157], v[58:61]
	v_mfma_f32_16x16x32_bf16 v[54:57], v[170:173], v[146:149], v[54:57]
	v_mfma_f32_16x16x32_bf16 v[50:53], v[170:173], v[154:157], v[50:53]
	v_mfma_f32_16x16x32_bf16 v[46:49], v[180:183], v[146:149], v[46:49]
	v_mfma_f32_16x16x32_bf16 v[42:45], v[180:183], v[154:157], v[42:45]
	v_mfma_f32_16x16x32_bf16 v[38:41], v[188:191], v[146:149], v[38:41]
	v_mfma_f32_16x16x32_bf16 v[34:37], v[188:191], v[154:157], v[34:37]
	v_mfma_f32_16x16x32_bf16 v[62:65], v[166:169], v[150:153], v[62:65]
	v_mfma_f32_16x16x32_bf16 v[58:61], v[166:169], v[158:161], v[58:61]
	v_mfma_f32_16x16x32_bf16 v[54:57], v[174:177], v[150:153], v[54:57]
	v_mfma_f32_16x16x32_bf16 v[50:53], v[174:177], v[158:161], v[50:53]
	v_mfma_f32_16x16x32_bf16 v[46:49], v[184:187], v[150:153], v[46:49]
	v_mfma_f32_16x16x32_bf16 v[42:45], v[184:187], v[158:161], v[42:45]
	v_mfma_f32_16x16x32_bf16 v[38:41], v[192:195], v[150:153], v[38:41]
	v_mfma_f32_16x16x32_bf16 v[34:37], v[192:195], v[158:161], v[34:37]
	v_mfma_f32_16x16x32_bf16 v[30:33], v[162:165], v[196:199], v[30:33]
	v_mfma_f32_16x16x32_bf16 v[26:29], v[162:165], v[204:207], v[26:29]
	v_mfma_f32_16x16x32_bf16 v[22:25], v[170:173], v[196:199], v[22:25]
	v_mfma_f32_16x16x32_bf16 v[18:21], v[170:173], v[204:207], v[18:21]
	v_mfma_f32_16x16x32_bf16 v[14:17], v[180:183], v[196:199], v[14:17]
	v_mfma_f32_16x16x32_bf16 v[10:13], v[180:183], v[204:207], v[10:13]
	v_mfma_f32_16x16x32_bf16 v[6:9], v[188:191], v[196:199], v[6:9]
	v_mfma_f32_16x16x32_bf16 v[2:5], v[188:191], v[204:207], v[2:5]
	v_mfma_f32_16x16x32_bf16 v[30:33], v[166:169], v[200:203], v[30:33]
	v_mfma_f32_16x16x32_bf16 v[26:29], v[166:169], v[208:211], v[26:29]
	v_mfma_f32_16x16x32_bf16 v[22:25], v[174:177], v[200:203], v[22:25]
	v_mfma_f32_16x16x32_bf16 v[18:21], v[174:177], v[208:211], v[18:21]
	v_mfma_f32_16x16x32_bf16 v[14:17], v[184:187], v[200:203], v[14:17]
	v_mfma_f32_16x16x32_bf16 v[10:13], v[184:187], v[208:211], v[10:13]
	v_mfma_f32_16x16x32_bf16 v[6:9], v[192:195], v[200:203], v[6:9]
	v_mfma_f32_16x16x32_bf16 v[2:5], v[192:195], v[208:211], v[2:5]
	s_setprio 0
	s_add_u32 s16, s16, 0x100
	s_addc_u32 s17, s17, 0
	s_add_u32 s18, s18, 0x100
	s_addc_u32 s19, s19, 0
	s_add_u32 s20, s20, 0x100
	s_addc_u32 s21, s21, 0
	s_add_u32 s22, s22, 0x100
	s_addc_u32 s23, s23, 0
	s_sub_i32 s14, s14, 1
	s_cmp_lg_u32 s14, 0
	s_barrier
	s_cbranch_scc1 .Lk_ffn_in
	v_add_u32_e32 v158, 0x10000, v145
	ds_read_b128 v[146:149], v158
	ds_read_b128 v[150:153], v158 offset:1024
	ds_read_b128 v[154:157], v158 offset:2048
	ds_read_b128 v[158:161], v158 offset:3072
	ds_read_b128 v[162:165], v142
	ds_read_b128 v[166:169], v142 offset:1024
	ds_read_b128 v[170:173], v142 offset:2048
	ds_read_b128 v[174:177], v142 offset:3072
	ds_read_b128 v[180:183], v142 offset:4096
	ds_read_b128 v[184:187], v142 offset:5120
	ds_read_b128 v[188:191], v142 offset:6144
	ds_read_b128 v[192:195], v142 offset:7168
	v_add_u32_e32 v208, 0x14000, v145
	ds_read_b128 v[196:199], v208
	ds_read_b128 v[200:203], v208 offset:1024
	ds_read_b128 v[204:207], v208 offset:2048
	ds_read_b128 v[208:211], v208 offset:3072
	s_add_u32 s0, s18, 0x80
	s_addc_u32 s1, s19, 0
	s_add_i32 s3, s7, 0xc000
	s_mov_b32 m0, s3
	s_nop 0
	global_load_lds_dwordx4 v144, s[0:1]
	s_add_i32 s3, s7, 0xe000
	s_mov_b32 m0, s3
	s_nop 0
	global_load_lds_dwordx4 v143, s[0:1]
	s_waitcnt vmcnt(8) lgkmcnt(0)
	s_barrier
	s_setprio 1
	v_mfma_f32_16x16x32_bf16 v[126:129], v[162:165], v[146:149], v[126:129]
	v_mfma_f32_16x16x32_bf16 v[122:125], v[162:165], v[154:157], v[122:125]
	v_mfma_f32_16x16x32_bf16 v[118:121], v[170:173], v[146:149], v[118:121]
	v_mfma_f32_16x16x32_bf16 v[114:117], v[170:173], v[154:157], v[114:117]
	v_mfma_f32_16x16x32_bf16 v[110:113], v[180:183], v[146:149], v[110:113]
	v_mfma_f32_16x16x32_bf16 v[106:109], v[180:183], v[154:157], v[106:109]
	v_mfma_f32_16x16x32_bf16 v[102:105], v[188:191], v[146:149], v[102:105]
	v_mfma_f32_16x16x32_bf16 v[98:101], v[188:191], v[154:157], v[98:101]
	v_mfma_f32_16x16x32_bf16 v[126:129], v[166:169], v[150:153], v[126:129]
	v_mfma_f32_16x16x32_bf16 v[122:125], v[166:169], v[158:161], v[122:125]
	v_mfma_f32_16x16x32_bf16 v[118:121], v[174:177], v[150:153], v[118:121]
	v_mfma_f32_16x16x32_bf16 v[114:117], v[174:177], v[158:161], v[114:117]
	v_mfma_f32_16x16x32_bf16 v[110:113], v[184:187], v[150:153], v[110:113]
	v_mfma_f32_16x16x32_bf16 v[106:109], v[184:187], v[158:161], v[106:109]
	v_mfma_f32_16x16x32_bf16 v[102:105], v[192:195], v[150:153], v[102:105]
	v_mfma_f32_16x16x32_bf16 v[98:101], v[192:195], v[158:161], v[98:101]
	v_mfma_f32_16x16x32_bf16 v[94:97], v[162:165], v[196:199], v[94:97]
	v_mfma_f32_16x16x32_bf16 v[90:93], v[162:165], v[204:207], v[90:93]
	v_mfma_f32_16x16x32_bf16 v[86:89], v[170:173], v[196:199], v[86:89]
	v_mfma_f32_16x16x32_bf16 v[82:85], v[170:173], v[204:207], v[82:85]
	v_mfma_f32_16x16x32_bf16 v[78:81], v[180:183], v[196:199], v[78:81]
	v_mfma_f32_16x16x32_bf16 v[74:77], v[180:183], v[204:207], v[74:77]
	v_mfma_f32_16x16x32_bf16 v[70:73], v[188:191], v[196:199], v[70:73]
	v_mfma_f32_16x16x32_bf16 v[66:69], v[188:191], v[204:207], v[66:69]
	v_mfma_f32_16x16x32_bf16 v[94:97], v[166:169], v[200:203], v[94:97]
	v_mfma_f32_16x16x32_bf16 v[90:93], v[166:169], v[208:211], v[90:93]
	v_mfma_f32_16x16x32_bf16 v[86:89], v[174:177], v[200:203], v[86:89]
	v_mfma_f32_16x16x32_bf16 v[82:85], v[174:177], v[208:211], v[82:85]
	v_mfma_f32_16x16x32_bf16 v[78:81], v[184:187], v[200:203], v[78:81]
	v_mfma_f32_16x16x32_bf16 v[74:77], v[184:187], v[208:211], v[74:77]
	v_mfma_f32_16x16x32_bf16 v[70:73], v[192:195], v[200:203], v[70:73]
	v_mfma_f32_16x16x32_bf16 v[66:69], v[192:195], v[208:211], v[66:69]
	s_setprio 0
	s_barrier
; #define WAIT_V(n) asm volatile("s_waitcnt vmcnt(" #n ")" ::: "memory")
; #define WAIT_L(n) asm volatile("s_waitcnt lgkmcnt(" #n ")" ::: "memory")
; #define BAR __builtin_amdgcn_s_barrier()
; #define LDA8(b, h) _Pragma("unroll") for (int m = 0; m < 4; ++m) _Pragma("unroll") for (int k = 0; k < 2; ++k) \
;     At[m][k] = *(const bf16x8*)(SA_(shm, b, h) + abase + (m * 2 + k) * 1024)
; #define LDB8(dst, b, h) _Pragma("unroll") for (int n = 0; n < 2; ++n) _Pragma("unroll") for (int k = 0; k < 2; ++k) \
;     dst[n][k] = *(const bf16x8*)(SB_(shm, b, h) + bbase + (n * 2 + k) * 1024)
; #define MMA8(ai, bj, Bx) do { __builtin_amdgcn_s_setprio(1); \
;     _Pragma("unroll") for (int m = 0; m < 4; ++m) _Pragma("unroll") for (int n = 0; n < 2; ++n) _Pragma("unroll") for (int k = 0; k < 2; ++k) \
;       acc[ai][bj][m][n] = __builtin_amdgcn_mfma_f32_16x16x32_bf16(At[m][k], Bx[n][k], acc[ai][bj][m][n], 0, 0, 0); \
;     __builtin_amdgcn_s_setprio(0); } while (0)
; template <bool HS>
; __device__ __forceinline__ void gemm_tile8(const u16* __restrict__ Ap, const u16* __restrict__ Bp, int K,
;                                            f32x4 (&acc)[2][2][4][2], char* shm, const int tid, const float* hsr = nullptr) {
;     ...
;     LDA8(0, 1); WAIT_V(4); BAR; WAIT_L(0); MMA8(1, 0, B0); MMA8(1, 1, B1); BAR; }
;   { LDB8(B0, 1, 0); LDA8(1, 0); WAIT_V(2); BAR; WAIT_L(0); MMA8(0, 0, B0); BAR;
;     LDB8(B1, 1, 1); WAIT_V(0); BAR; WAIT_L(0); MMA8(0, 1, B1); BAR;
	ds_read_b128 v[162:165], v142 offset:16384
	ds_read_b128 v[166:169], v142 offset:17408
	ds_read_b128 v[170:173], v142 offset:18432
	ds_read_b128 v[174:177], v142 offset:19456
	ds_read_b128 v[180:183], v142 offset:20480
	ds_read_b128 v[184:187], v142 offset:21504
	ds_read_b128 v[188:191], v142 offset:22528
	ds_read_b128 v[192:195], v142 offset:23552
	s_waitcnt vmcnt(2) lgkmcnt(0)
	s_barrier
	s_setprio 1
	v_mfma_f32_16x16x32_bf16 v[62:65], v[162:165], v[146:149], v[62:65]
	v_mfma_f32_16x16x32_bf16 v[58:61], v[162:165], v[154:157], v[58:61]
	v_mfma_f32_16x16x32_bf16 v[54:57], v[170:173], v[146:149], v[54:57]
	v_mfma_f32_16x16x32_bf16 v[50:53], v[170:173], v[154:157], v[50:53]
	v_mfma_f32_16x16x32_bf16 v[46:49], v[180:183], v[146:149], v[46:49]
	v_mfma_f32_16x16x32_bf16 v[42:45], v[180:183], v[154:157], v[42:45]
	v_mfma_f32_16x16x32_bf16 v[38:41], v[188:191], v[146:149], v[38:41]
	v_mfma_f32_16x16x32_bf16 v[34:37], v[188:191], v[154:157], v[34:37]
	v_mfma_f32_16x16x32_bf16 v[62:65], v[166:169], v[150:153], v[62:65]
	v_mfma_f32_16x16x32_bf16 v[58:61], v[166:169], v[158:161], v[58:61]
	v_mfma_f32_16x16x32_bf16 v[54:57], v[174:177], v[150:153], v[54:57]
	v_mfma_f32_16x16x32_bf16 v[50:53], v[174:177], v[158:161], v[50:53]
	v_mfma_f32_16x16x32_bf16 v[46:49], v[184:187], v[150:153], v[46:49]
	v_mfma_f32_16x16x32_bf16 v[42:45], v[184:187], v[158:161], v[42:45]
	v_mfma_f32_16x16x32_bf16 v[38:41], v[192:195], v[150:153], v[38:41]
	v_mfma_f32_16x16x32_bf16 v[34:37], v[192:195], v[158:161], v[34:37]
	v_mfma_f32_16x16x32_bf16 v[30:33], v[162:165], v[196:199], v[30:33]
	v_mfma_f32_16x16x32_bf16 v[26:29], v[162:165], v[204:207], v[26:29]
	v_mfma_f32_16x16x32_bf16 v[22:25], v[170:173], v[196:199], v[22:25]
	v_mfma_f32_16x16x32_bf16 v[18:21], v[170:173], v[204:207], v[18:21]
	v_mfma_f32_16x16x32_bf16 v[14:17], v[180:183], v[196:199], v[14:17]
	v_mfma_f32_16x16x32_bf16 v[10:13], v[180:183], v[204:207], v[10:13]
	v_mfma_f32_16x16x32_bf16 v[6:9], v[188:191], v[196:199], v[6:9]
	v_mfma_f32_16x16x32_bf16 v[2:5], v[188:191], v[204:207], v[2:5]
	v_mfma_f32_16x16x32_bf16 v[30:33], v[166:169], v[200:203], v[30:33]
	v_mfma_f32_16x16x32_bf16 v[26:29], v[166:169], v[208:211], v[26:29]
	v_mfma_f32_16x16x32_bf16 v[22:25], v[174:177], v[200:203], v[22:25]
	v_mfma_f32_16x16x32_bf16 v[18:21], v[174:177], v[208:211], v[18:21]
	v_mfma_f32_16x16x32_bf16 v[14:17], v[184:187], v[200:203], v[14:17]
	v_mfma_f32_16x16x32_bf16 v[10:13], v[184:187], v[208:211], v[10:13]
	v_mfma_f32_16x16x32_bf16 v[6:9], v[192:195], v[200:203], v[6:9]
	v_mfma_f32_16x16x32_bf16 v[2:5], v[192:195], v[208:211], v[2:5]
	s_setprio 0
	s_barrier
	v_add_u32_e32 v158, 0x18000, v145
	ds_read_b128 v[146:149], v158
	ds_read_b128 v[150:153], v158 offset:1024
	ds_read_b128 v[154:157], v158 offset:2048
	ds_read_b128 v[158:161], v158 offset:3072
	ds_read_b128 v[162:165], v142 offset:32768
	ds_read_b128 v[166:169], v142 offset:33792
	ds_read_b128 v[170:173], v142 offset:34816
	ds_read_b128 v[174:177], v142 offset:35840
	ds_read_b128 v[180:183], v142 offset:36864
	ds_read_b128 v[184:187], v142 offset:37888
	ds_read_b128 v[188:191], v142 offset:38912
	ds_read_b128 v[192:195], v142 offset:39936
	v_add_u32_e32 v208, 0x1c000, v145
	ds_read_b128 v[196:199], v208
	ds_read_b128 v[200:203], v208 offset:1024
	ds_read_b128 v[204:207], v208 offset:2048
	ds_read_b128 v[208:211], v208 offset:3072
	s_waitcnt vmcnt(0) lgkmcnt(0)
	s_barrier
; #define WAIT_V(n) asm volatile("s_waitcnt vmcnt(" #n ")" ::: "memory")
; #define WAIT_L(n) asm volatile("s_waitcnt lgkmcnt(" #n ")" ::: "memory")
; #define BAR __builtin_amdgcn_s_barrier()
; #define LDA8(b, h) _Pragma("unroll") for (int m = 0; m < 4; ++m) _Pragma("unroll") for (int k = 0; k < 2; ++k) \
;     At[m][k] = *(const bf16x8*)(SA_(shm, b, h) + abase + (m * 2 + k) * 1024)
; #define LDB8(dst, b, h) _Pragma("unroll") for (int n = 0; n < 2; ++n) _Pragma("unroll") for (int k = 0; k < 2; ++k) \
;     dst[n][k] = *(const bf16x8*)(SB_(shm, b, h) + bbase + (n * 2 + k) * 1024)
; #define MMA8(ai, bj, Bx) do { __builtin_amdgcn_s_setprio(1); \
;     _Pragma("unroll") for (int m = 0; m < 4; ++m) _Pragma("unroll") for (int n = 0; n < 2; ++n) _Pragma("unroll") for (int k = 0; k < 2; ++k) \
;       acc[ai][bj][m][n] = __builtin_amdgcn_mfma_f32_16x16x32_bf16(At[m][k], Bx[n][k], acc[ai][bj][m][n], 0, 0, 0); \
;     __builtin_amdgcn_s_setprio(0); } while (0)
; template <bool HS>
; __device__ __forceinline__ void gemm_tile8(const u16* __restrict__ Ap, const u16* __restrict__ Bp, int K,
;                                            f32x4 (&acc)[2][2][4][2], char* shm, const int tid, const float* hsr = nullptr) {
;     ...
;     LDB8(B1, 1, 1); WAIT_V(0); BAR; WAIT_L(0); MMA8(0, 1, B1); BAR;
;     LDA8(1, 1); BAR; WAIT_L(0); MMA8(1, 0, B0); MMA8(1, 1, B1); BAR; }
;   if (wr == 0) BAR;
	s_setprio 1
	v_mfma_f32_16x16x32_bf16 v[126:129], v[162:165], v[146:149], v[126:129]
	v_mfma_f32_16x16x32_bf16 v[122:125], v[162:165], v[154:157], v[122:125]
	v_mfma_f32_16x16x32_bf16 v[118:121], v[170:173], v[146:149], v[118:121]
	v_mfma_f32_16x16x32_bf16 v[114:117], v[170:173], v[154:157], v[114:117]
	v_mfma_f32_16x16x32_bf16 v[110:113], v[180:183], v[146:149], v[110:113]
	v_mfma_f32_16x16x32_bf16 v[106:109], v[180:183], v[154:157], v[106:109]
	v_mfma_f32_16x16x32_bf16 v[102:105], v[188:191], v[146:149], v[102:105]
	v_mfma_f32_16x16x32_bf16 v[98:101], v[188:191], v[154:157], v[98:101]
	v_mfma_f32_16x16x32_bf16 v[126:129], v[166:169], v[150:153], v[126:129]
	v_mfma_f32_16x16x32_bf16 v[122:125], v[166:169], v[158:161], v[122:125]
	v_mfma_f32_16x16x32_bf16 v[118:121], v[174:177], v[150:153], v[118:121]
	v_mfma_f32_16x16x32_bf16 v[114:117], v[174:177], v[158:161], v[114:117]
	v_mfma_f32_16x16x32_bf16 v[110:113], v[184:187], v[150:153], v[110:113]
	v_mfma_f32_16x16x32_bf16 v[106:109], v[184:187], v[158:161], v[106:109]
	v_mfma_f32_16x16x32_bf16 v[102:105], v[192:195], v[150:153], v[102:105]
	v_mfma_f32_16x16x32_bf16 v[98:101], v[192:195], v[158:161], v[98:101]
	v_mfma_f32_16x16x32_bf16 v[94:97], v[162:165], v[196:199], v[94:97]
	v_mfma_f32_16x16x32_bf16 v[90:93], v[162:165], v[204:207], v[90:93]
	v_mfma_f32_16x16x32_bf16 v[86:89], v[170:173], v[196:199], v[86:89]
	v_mfma_f32_16x16x32_bf16 v[82:85], v[170:173], v[204:207], v[82:85]
	v_mfma_f32_16x16x32_bf16 v[78:81], v[180:183], v[196:199], v[78:81]
	v_mfma_f32_16x16x32_bf16 v[74:77], v[180:183], v[204:207], v[74:77]
	v_mfma_f32_16x16x32_bf16 v[70:73], v[188:191], v[196:199], v[70:73]
	v_mfma_f32_16x16x32_bf16 v[66:69], v[188:191], v[204:207], v[66:69]
	v_mfma_f32_16x16x32_bf16 v[94:97], v[166:169], v[200:203], v[94:97]
	v_mfma_f32_16x16x32_bf16 v[90:93], v[166:169], v[208:211], v[90:93]
	v_mfma_f32_16x16x32_bf16 v[86:89], v[174:177], v[200:203], v[86:89]
	v_mfma_f32_16x16x32_bf16 v[82:85], v[174:177], v[208:211], v[82:85]
	v_mfma_f32_16x16x32_bf16 v[78:81], v[184:187], v[200:203], v[78:81]
	v_mfma_f32_16x16x32_bf16 v[74:77], v[184:187], v[208:211], v[74:77]
	v_mfma_f32_16x16x32_bf16 v[70:73], v[192:195], v[200:203], v[70:73]
	v_mfma_f32_16x16x32_bf16 v[66:69], v[192:195], v[208:211], v[66:69]
	s_setprio 0
	s_barrier
	ds_read_b128 v[162:165], v142 offset:49152
	ds_read_b128 v[166:169], v142 offset:50176
	ds_read_b128 v[170:173], v142 offset:51200
	ds_read_b128 v[174:177], v142 offset:52224
	ds_read_b128 v[180:183], v142 offset:53248
	ds_read_b128 v[184:187], v142 offset:54272
	ds_read_b128 v[188:191], v142 offset:55296
	ds_read_b128 v[192:195], v142 offset:56320
	s_waitcnt lgkmcnt(0)
	s_barrier
	s_setprio 1
	v_mfma_f32_16x16x32_bf16 v[62:65], v[162:165], v[146:149], v[62:65]
	v_mfma_f32_16x16x32_bf16 v[58:61], v[162:165], v[154:157], v[58:61]
	v_mfma_f32_16x16x32_bf16 v[54:57], v[170:173], v[146:149], v[54:57]
	v_mfma_f32_16x16x32_bf16 v[50:53], v[170:173], v[154:157], v[50:53]
	v_mfma_f32_16x16x32_bf16 v[46:49], v[180:183], v[146:149], v[46:49]
	v_mfma_f32_16x16x32_bf16 v[42:45], v[180:183], v[154:157], v[42:45]
	v_mfma_f32_16x16x32_bf16 v[38:41], v[188:191], v[146:149], v[38:41]
	v_mfma_f32_16x16x32_bf16 v[34:37], v[188:191], v[154:157], v[34:37]
	v_mfma_f32_16x16x32_bf16 v[62:65], v[166:169], v[150:153], v[62:65]
	v_mfma_f32_16x16x32_bf16 v[58:61], v[166:169], v[158:161], v[58:61]
	v_mfma_f32_16x16x32_bf16 v[54:57], v[174:177], v[150:153], v[54:57]
	v_mfma_f32_16x16x32_bf16 v[50:53], v[174:177], v[158:161], v[50:53]
	v_mfma_f32_16x16x32_bf16 v[46:49], v[184:187], v[150:153], v[46:49]
	v_mfma_f32_16x16x32_bf16 v[42:45], v[184:187], v[158:161], v[42:45]
	v_mfma_f32_16x16x32_bf16 v[38:41], v[192:195], v[150:153], v[38:41]
	v_mfma_f32_16x16x32_bf16 v[34:37], v[192:195], v[158:161], v[34:37]
	v_mfma_f32_16x16x32_bf16 v[30:33], v[162:165], v[196:199], v[30:33]
	v_mfma_f32_16x16x32_bf16 v[26:29], v[162:165], v[204:207], v[26:29]
	v_mfma_f32_16x16x32_bf16 v[22:25], v[170:173], v[196:199], v[22:25]
	v_mfma_f32_16x16x32_bf16 v[18:21], v[170:173], v[204:207], v[18:21]
	v_mfma_f32_16x16x32_bf16 v[14:17], v[180:183], v[196:199], v[14:17]
	v_mfma_f32_16x16x32_bf16 v[10:13], v[180:183], v[204:207], v[10:13]
	v_mfma_f32_16x16x32_bf16 v[6:9], v[188:191], v[196:199], v[6:9]
	v_mfma_f32_16x16x32_bf16 v[2:5], v[188:191], v[204:207], v[2:5]
	v_mfma_f32_16x16x32_bf16 v[30:33], v[166:169], v[200:203], v[30:33]
	v_mfma_f32_16x16x32_bf16 v[26:29], v[166:169], v[208:211], v[26:29]
	v_mfma_f32_16x16x32_bf16 v[22:25], v[174:177], v[200:203], v[22:25]
	v_mfma_f32_16x16x32_bf16 v[18:21], v[174:177], v[208:211], v[18:21]
	v_mfma_f32_16x16x32_bf16 v[14:17], v[184:187], v[200:203], v[14:17]
	v_mfma_f32_16x16x32_bf16 v[10:13], v[184:187], v[208:211], v[10:13]
	v_mfma_f32_16x16x32_bf16 v[6:9], v[192:195], v[200:203], v[6:9]
	v_mfma_f32_16x16x32_bf16 v[2:5], v[192:195], v[208:211], v[2:5]
	s_setprio 0
	s_movk_i32 s0, 0x100
	v_cmp_gt_u32_e32 vcc, s0, v0
	s_barrier
	s_and_saveexec_b64 s[0:1], vcc
	s_cbranch_execz .LBB0_862
	s_barrier
